# K-loops: deleted the s_setprio 0 / s_setprio 1 pair that sat between the 16th and 17th MFMA of every 32-MFMA segment (two inserted issue slots per segment); priority 1 now held across the whole segmen
# speedup vs baseline: 1.0120x; 1.0120x over previous
; #define PG8_STAGE(bufoff, gbase, voff) do { _Pragma("unroll") for (int _i = 0; _i < 2; ++_i) \
;         __builtin_amdgcn_global_load_lds((const unsigned*)((const char*)(gbase) + (voff)[_i]), (LAS unsigned*)(lds + (bufoff) + ldsw + _i * 8192), 16, 0, 0); } while (0)
; #define PG8_LDA(dst, b, h) do { _Pragma("unroll") for (int m = 0; m < 4; ++m) _Pragma("unroll") for (int k = 0; k < 2; ++k) dst[m][k] = *(const LAS bf16x8*)(lds + PG8_SA(b, h) + aoff + m * 2048 + k * 1024); } while (0)
; #define PG8_LDB(dst, b, h) do { _Pragma("unroll") for (int n = 0; n < 2; ++n) _Pragma("unroll") for (int k = 0; k < 2; ++k) dst[n][k] = *(const LAS bf16x8*)(lds + PG8_SB(b, h) + boff + n * 2048 + k * 1024); } while (0)
; #define PG8_MMA(ai, bj, At, Bt) do { __builtin_amdgcn_s_setprio(1); _Pragma("unroll") for (int m = 0; m < 4; ++m) _Pragma("unroll") for (int n = 0; n < 2; ++n) _Pragma("unroll") for (int k = 0; k < 2; ++k) \
;         acc[ai][bj][m][n] = __builtin_amdgcn_mfma_f32_16x16x32_bf16(Bt[n][k], At[m][k], acc[ai][bj][m][n], 0, 0, 0); __builtin_amdgcn_s_setprio(0); } while (0)
; #define PG8_WAIT_V(n) asm volatile("s_waitcnt vmcnt(" #n ")" ::: "memory")
; #define PG8_WAIT_L(n) asm volatile("s_waitcnt lgkmcnt(" #n ")" ::: "memory")
; #define PG8_BAR __builtin_amdgcn_s_barrier()
; #define PG8_SCHED __builtin_amdgcn_sched_barrier(0)
; template <class Epi>
; __device__ __forceinline__ void gemm_phase(LAS unsigned char* lds, const int tid, const Gemm g, const StaticOrder& S, const Epi& E) {
;     ...
;             const bool last = (t == nt - 2);
;             const char* a1 = cA + (size_t)(t + 1) * kstep;
;             const char* a2 = last ? nA : cA + (size_t)(t + 2) * kstep; const char* b2 = last ? nB : cB + (size_t)(t + 2) * kstep;
;             const char* a3 = a2 + kstep; const char* b3 = b2 + kstep;
;             PG8_LDB(B0, 0, 0); PG8_LDB(B1, 0, 1); PG8_SCHED; PG8_LDA(At, 0, 0); PG8_STAGE(PG8_SA(1, 1), a1 + hstepA, voffA);
;             PG8_WAIT_V(8); PG8_WAIT_L(0); PG8_BAR; PG8_MMA(0, 0, At, B0); PG8_MMA(0, 1, At, B1); PG8_BAR; PG8_SCHED;
;             PG8_LDA(At, 0, 1); PG8_STAGE(PG8_SB(0, 0), b2, voffB); PG8_STAGE(PG8_SB(0, 1), b2 + hstepB, voffB); PG8_STAGE(PG8_SA(0, 0), a2, voffA);
;             PG8_WAIT_V(8); PG8_WAIT_L(0); PG8_BAR; PG8_MMA(1, 0, At, B0); PG8_MMA(1, 1, At, B1); PG8_BAR; PG8_SCHED;
.LBB0_414:
	s_add_u32 s10, s68, 0xfffc0080
	s_addc_u32 s11, s69, -1
	s_add_i32 s17, 0, 0x10000
	s_cmp_eq_u32 s16, 12
	s_cselect_b32 s73, s7, s11
	s_cselect_b32 s72, s67, s10
	s_cselect_b32 s71, s5, s76
	s_cselect_b32 s70, vcc_lo, vcc_hi
	s_add_i32 s0, 0, 0x14000
	v_add_u32_e32 v70, s17, v202
	v_add_u32_e32 v160, s0, v202
	ds_read_b128 v[50:53], v70
	ds_read_b128 v[54:57], v70 offset:1024
	ds_read_b128 v[66:69], v70 offset:2048
	ds_read_b128 v[70:73], v70 offset:3072
	ds_read_b128 v[156:159], v160
	ds_read_b128 v[170:173], v160 offset:1024
	ds_read_b128 v[174:177], v160 offset:2048
	ds_read_b128 v[178:181], v160 offset:3072
	v_lshl_add_u64 v[160:161], s[68:69], 0, v[152:153]
	s_add_i32 m0, s83, 0xc000
	ds_read_b128 v[216:219], v215
	ds_read_b128 v[220:223], v215 offset:1024
	ds_read_b128 v[224:227], v215 offset:2048
	ds_read_b128 v[228:231], v215 offset:3072
	ds_read_b128 v[232:235], v215 offset:4096
	ds_read_b128 v[236:239], v215 offset:5120
	ds_read_b128 v[240:243], v215 offset:6144
	ds_read_b128 v[244:247], v215 offset:7168
	global_load_lds_dwordx4 v[160:161], off
	v_lshl_add_u64 v[160:161], s[68:69], 0, v[154:155]
	s_add_i32 m0, s83, 0xe000
	s_nop 0
	global_load_lds_dwordx4 v[160:161], off
	s_waitcnt vmcnt(8)
	s_waitcnt lgkmcnt(0)
	s_barrier
	s_setprio 1
	s_waitcnt lgkmcnt(0)
	v_mfma_f32_16x16x32_bf16 v[142:145], v[50:53], v[216:219], v[142:145]
	v_mfma_f32_16x16x32_bf16 v[138:141], v[66:69], v[216:219], v[138:141]
	v_mfma_f32_16x16x32_bf16 v[126:129], v[50:53], v[224:227], v[126:129]
	v_mfma_f32_16x16x32_bf16 v[122:125], v[66:69], v[224:227], v[122:125]
	v_mfma_f32_16x16x32_bf16 v[110:113], v[50:53], v[232:235], v[110:113]
	v_mfma_f32_16x16x32_bf16 v[106:109], v[66:69], v[232:235], v[106:109]
	v_mfma_f32_16x16x32_bf16 v[94:97], v[50:53], v[240:243], v[94:97]
	v_mfma_f32_16x16x32_bf16 v[90:93], v[66:69], v[240:243], v[90:93]
	v_mfma_f32_16x16x32_bf16 v[142:145], v[54:57], v[220:223], v[142:145]
	v_mfma_f32_16x16x32_bf16 v[138:141], v[70:73], v[220:223], v[138:141]
	v_mfma_f32_16x16x32_bf16 v[126:129], v[54:57], v[228:231], v[126:129]
	v_mfma_f32_16x16x32_bf16 v[122:125], v[70:73], v[228:231], v[122:125]
	v_mfma_f32_16x16x32_bf16 v[110:113], v[54:57], v[236:239], v[110:113]
	v_mfma_f32_16x16x32_bf16 v[106:109], v[70:73], v[236:239], v[106:109]
	v_mfma_f32_16x16x32_bf16 v[94:97], v[54:57], v[244:247], v[94:97]
	v_mfma_f32_16x16x32_bf16 v[90:93], v[70:73], v[244:247], v[90:93]
	v_mfma_f32_16x16x32_bf16 v[134:137], v[156:159], v[216:219], v[134:137]
	v_mfma_f32_16x16x32_bf16 v[130:133], v[174:177], v[216:219], v[130:133]
	v_mfma_f32_16x16x32_bf16 v[118:121], v[156:159], v[224:227], v[118:121]
	v_mfma_f32_16x16x32_bf16 v[114:117], v[174:177], v[224:227], v[114:117]
	v_mfma_f32_16x16x32_bf16 v[102:105], v[156:159], v[232:235], v[102:105]
	v_mfma_f32_16x16x32_bf16 v[98:101], v[174:177], v[232:235], v[98:101]
	v_mfma_f32_16x16x32_bf16 v[86:89], v[156:159], v[240:243], v[86:89]
	v_mfma_f32_16x16x32_bf16 v[82:85], v[174:177], v[240:243], v[82:85]
	v_mfma_f32_16x16x32_bf16 v[134:137], v[170:173], v[220:223], v[134:137]
	v_mfma_f32_16x16x32_bf16 v[130:133], v[178:181], v[220:223], v[130:133]
	v_mfma_f32_16x16x32_bf16 v[118:121], v[170:173], v[228:231], v[118:121]
	v_mfma_f32_16x16x32_bf16 v[114:117], v[178:181], v[228:231], v[114:117]
	v_mfma_f32_16x16x32_bf16 v[102:105], v[170:173], v[236:239], v[102:105]
	v_mfma_f32_16x16x32_bf16 v[98:101], v[178:181], v[236:239], v[98:101]
	v_mfma_f32_16x16x32_bf16 v[86:89], v[170:173], v[244:247], v[86:89]
	v_mfma_f32_16x16x32_bf16 v[82:85], v[178:181], v[244:247], v[82:85]
	s_setprio 0
	s_barrier
	s_add_i32 s1, s17, s82
	v_lshl_add_u64 v[160:161], s[70:71], 0, v[0:1]
	s_mov_b32 m0, s1
	ds_read_b128 v[216:219], v215 offset:16384
	ds_read_b128 v[220:223], v215 offset:17408
	ds_read_b128 v[224:227], v215 offset:18432
	ds_read_b128 v[228:231], v215 offset:19456
	ds_read_b128 v[232:235], v215 offset:20480
	ds_read_b128 v[236:239], v215 offset:21504
	ds_read_b128 v[240:243], v215 offset:22528
	ds_read_b128 v[244:247], v215 offset:23552
	global_load_lds_dwordx4 v[160:161], off
	s_add_i32 m0, s1, 0x2000
	s_add_u32 s10, s70, 0x40000
	v_lshl_add_u64 v[182:183], s[70:71], 0, v[146:147]
	s_addc_u32 s11, s71, 0
	s_add_i32 s0, s0, s82
	global_load_lds_dwordx4 v[182:183], off
	v_lshl_add_u64 v[162:163], s[10:11], 0, v[0:1]
	s_mov_b32 m0, s0
	v_lshl_add_u64 v[164:165], s[72:73], 0, v[150:151]
	global_load_lds_dwordx4 v[162:163], off
	v_lshl_add_u64 v[162:163], s[10:11], 0, v[146:147]
	s_add_i32 m0, s0, 0x2000
	s_nop 0
	global_load_lds_dwordx4 v[162:163], off
	v_lshl_add_u64 v[162:163], s[72:73], 0, v[148:149]
	s_mov_b32 m0, s83
	s_nop 0
	global_load_lds_dwordx4 v[162:163], off
	s_mov_b32 m0, s88
	s_nop 0
	global_load_lds_dwordx4 v[164:165], off
	s_waitcnt vmcnt(8)
	s_waitcnt lgkmcnt(0)
	s_barrier
; #define PG8_STAGE(bufoff, gbase, voff) do { _Pragma("unroll") for (int _i = 0; _i < 2; ++_i) \
;         __builtin_amdgcn_global_load_lds((const unsigned*)((const char*)(gbase) + (voff)[_i]), (LAS unsigned*)(lds + (bufoff) + ldsw + _i * 8192), 16, 0, 0); } while (0)
; #define PG8_LDA(dst, b, h) do { _Pragma("unroll") for (int m = 0; m < 4; ++m) _Pragma("unroll") for (int k = 0; k < 2; ++k) dst[m][k] = *(const LAS bf16x8*)(lds + PG8_SA(b, h) + aoff + m * 2048 + k * 1024); } while (0)
; #define PG8_LDB(dst, b, h) do { _Pragma("unroll") for (int n = 0; n < 2; ++n) _Pragma("unroll") for (int k = 0; k < 2; ++k) dst[n][k] = *(const LAS bf16x8*)(lds + PG8_SB(b, h) + boff + n * 2048 + k * 1024); } while (0)
; #define PG8_MMA(ai, bj, At, Bt) do { __builtin_amdgcn_s_setprio(1); _Pragma("unroll") for (int m = 0; m < 4; ++m) _Pragma("unroll") for (int n = 0; n < 2; ++n) _Pragma("unroll") for (int k = 0; k < 2; ++k) \
;         acc[ai][bj][m][n] = __builtin_amdgcn_mfma_f32_16x16x32_bf16(Bt[n][k], At[m][k], acc[ai][bj][m][n], 0, 0, 0); __builtin_amdgcn_s_setprio(0); } while (0)
; #define PG8_WAIT_V(n) asm volatile("s_waitcnt vmcnt(" #n ")" ::: "memory")
; #define PG8_WAIT_L(n) asm volatile("s_waitcnt lgkmcnt(" #n ")" ::: "memory")
; #define PG8_BAR __builtin_amdgcn_s_barrier()
; #define PG8_SCHED __builtin_amdgcn_sched_barrier(0)
; template <class Epi>
; __device__ __forceinline__ void gemm_phase(LAS unsigned char* lds, const int tid, const Gemm g, const StaticOrder& S, const Epi& E) {
;     ...
;             PG8_WAIT_V(8); PG8_WAIT_L(0); PG8_BAR; PG8_MMA(1, 0, At, B0); PG8_MMA(1, 1, At, B1); PG8_BAR; PG8_SCHED;
;             PG8_LDB(B0, 1, 0); PG8_LDB(B1, 1, 1); PG8_SCHED; PG8_LDA(At, 1, 0); PG8_STAGE(PG8_SA(0, 1), a2 + hstepA, voffA);
;             PG8_WAIT_V(8); PG8_WAIT_L(0); PG8_BAR; PG8_MMA(0, 0, At, B0); PG8_MMA(0, 1, At, B1); PG8_BAR; PG8_SCHED;
	s_setprio 1
	s_waitcnt lgkmcnt(0)
	v_mfma_f32_16x16x32_bf16 v[78:81], v[50:53], v[216:219], v[78:81]
	v_mfma_f32_16x16x32_bf16 v[74:77], v[66:69], v[216:219], v[74:77]
	v_mfma_f32_16x16x32_bf16 v[46:49], v[50:53], v[224:227], v[46:49]
	v_mfma_f32_16x16x32_bf16 v[42:45], v[66:69], v[224:227], v[42:45]
	v_mfma_f32_16x16x32_bf16 v[30:33], v[50:53], v[232:235], v[30:33]
	v_mfma_f32_16x16x32_bf16 v[26:29], v[66:69], v[232:235], v[26:29]
	v_mfma_f32_16x16x32_bf16 v[14:17], v[50:53], v[240:243], v[14:17]
	v_mfma_f32_16x16x32_bf16 v[10:13], v[66:69], v[240:243], v[10:13]
	v_mfma_f32_16x16x32_bf16 v[78:81], v[54:57], v[220:223], v[78:81]
	v_mfma_f32_16x16x32_bf16 v[74:77], v[70:73], v[220:223], v[74:77]
	v_mfma_f32_16x16x32_bf16 v[46:49], v[54:57], v[228:231], v[46:49]
	v_mfma_f32_16x16x32_bf16 v[42:45], v[70:73], v[228:231], v[42:45]
	v_mfma_f32_16x16x32_bf16 v[30:33], v[54:57], v[236:239], v[30:33]
	v_mfma_f32_16x16x32_bf16 v[26:29], v[70:73], v[236:239], v[26:29]
	v_mfma_f32_16x16x32_bf16 v[14:17], v[54:57], v[244:247], v[14:17]
	v_mfma_f32_16x16x32_bf16 v[10:13], v[70:73], v[244:247], v[10:13]
	v_mfma_f32_16x16x32_bf16 v[38:41], v[156:159], v[224:227], v[38:41]
	v_mfma_f32_16x16x32_bf16 v[34:37], v[174:177], v[224:227], v[34:37]
	v_mfma_f32_16x16x32_bf16 v[22:25], v[156:159], v[232:235], v[22:25]
	v_mfma_f32_16x16x32_bf16 v[18:21], v[174:177], v[232:235], v[18:21]
	v_mfma_f32_16x16x32_bf16 v[6:9], v[156:159], v[240:243], v[6:9]
	v_mfma_f32_16x16x32_bf16 v[2:5], v[174:177], v[240:243], v[2:5]
	v_mfma_f32_16x16x32_bf16 v[50:53], v[156:159], v[216:219], v[62:65]
	v_mfma_f32_16x16x32_bf16 v[54:57], v[174:177], v[216:219], v[58:61]
	v_mfma_f32_16x16x32_bf16 v[38:41], v[170:173], v[228:231], v[38:41]
	v_mfma_f32_16x16x32_bf16 v[34:37], v[178:181], v[228:231], v[34:37]
	v_mfma_f32_16x16x32_bf16 v[22:25], v[170:173], v[236:239], v[22:25]
	v_mfma_f32_16x16x32_bf16 v[18:21], v[178:181], v[236:239], v[18:21]
	v_mfma_f32_16x16x32_bf16 v[6:9], v[170:173], v[244:247], v[6:9]
	v_mfma_f32_16x16x32_bf16 v[2:5], v[178:181], v[244:247], v[2:5]
	v_mfma_f32_16x16x32_bf16 v[50:53], v[170:173], v[220:223], v[50:53]
	v_mfma_f32_16x16x32_bf16 v[54:57], v[178:181], v[220:223], v[54:57]
	s_setprio 0
	s_barrier
	s_add_i32 s0, 0, 0x18000
	s_add_i32 s1, 0, 0x1c000
	v_add_u32_e32 v70, s0, v202
	v_add_u32_e32 v178, s1, v202
	ds_read_b128 v[58:61], v70
	ds_read_b128 v[62:65], v70 offset:1024
	ds_read_b128 v[66:69], v70 offset:2048
	ds_read_b128 v[70:73], v70 offset:3072
	ds_read_b128 v[156:159], v178
	ds_read_b128 v[170:173], v178 offset:1024
	ds_read_b128 v[174:177], v178 offset:2048
	ds_read_b128 v[178:181], v178 offset:3072
	s_add_u32 s10, s72, 0x40000
	s_addc_u32 s11, s73, 0
	s_mov_b32 m0, s89
	v_lshl_add_u64 v[206:207], s[10:11], 0, v[148:149]
	ds_read_b128 v[216:219], v215 offset:32768
	ds_read_b128 v[220:223], v215 offset:33792
	ds_read_b128 v[224:227], v215 offset:34816
	ds_read_b128 v[228:231], v215 offset:35840
	ds_read_b128 v[232:235], v215 offset:36864
	ds_read_b128 v[236:239], v215 offset:37888
	ds_read_b128 v[240:243], v215 offset:38912
	ds_read_b128 v[244:247], v215 offset:39936
	global_load_lds_dwordx4 v[206:207], off
	v_lshl_add_u64 v[206:207], s[10:11], 0, v[150:151]
	s_mov_b32 m0, s92
	s_nop 0
	global_load_lds_dwordx4 v[206:207], off
	s_waitcnt vmcnt(8)
	s_waitcnt lgkmcnt(0)
	s_barrier
	s_setprio 1
	s_waitcnt lgkmcnt(0)
	v_mfma_f32_16x16x32_bf16 v[142:145], v[58:61], v[216:219], v[142:145]
	v_mfma_f32_16x16x32_bf16 v[138:141], v[66:69], v[216:219], v[138:141]
	v_mfma_f32_16x16x32_bf16 v[126:129], v[58:61], v[224:227], v[126:129]
	v_mfma_f32_16x16x32_bf16 v[122:125], v[66:69], v[224:227], v[122:125]
	v_mfma_f32_16x16x32_bf16 v[110:113], v[58:61], v[232:235], v[110:113]
	v_mfma_f32_16x16x32_bf16 v[106:109], v[66:69], v[232:235], v[106:109]
	v_mfma_f32_16x16x32_bf16 v[94:97], v[58:61], v[240:243], v[94:97]
	v_mfma_f32_16x16x32_bf16 v[90:93], v[66:69], v[240:243], v[90:93]
	v_mfma_f32_16x16x32_bf16 v[142:145], v[62:65], v[220:223], v[142:145]
	v_mfma_f32_16x16x32_bf16 v[138:141], v[70:73], v[220:223], v[138:141]
	v_mfma_f32_16x16x32_bf16 v[126:129], v[62:65], v[228:231], v[126:129]
	v_mfma_f32_16x16x32_bf16 v[122:125], v[70:73], v[228:231], v[122:125]
	v_mfma_f32_16x16x32_bf16 v[110:113], v[62:65], v[236:239], v[110:113]
	v_mfma_f32_16x16x32_bf16 v[106:109], v[70:73], v[236:239], v[106:109]
	v_mfma_f32_16x16x32_bf16 v[94:97], v[62:65], v[244:247], v[94:97]
	v_mfma_f32_16x16x32_bf16 v[90:93], v[70:73], v[244:247], v[90:93]
	v_mfma_f32_16x16x32_bf16 v[134:137], v[156:159], v[216:219], v[134:137]
	v_mfma_f32_16x16x32_bf16 v[130:133], v[174:177], v[216:219], v[130:133]
	v_mfma_f32_16x16x32_bf16 v[118:121], v[156:159], v[224:227], v[118:121]
	v_mfma_f32_16x16x32_bf16 v[114:117], v[174:177], v[224:227], v[114:117]
	v_mfma_f32_16x16x32_bf16 v[102:105], v[156:159], v[232:235], v[102:105]
	v_mfma_f32_16x16x32_bf16 v[98:101], v[174:177], v[232:235], v[98:101]
	v_mfma_f32_16x16x32_bf16 v[86:89], v[156:159], v[240:243], v[86:89]
	v_mfma_f32_16x16x32_bf16 v[82:85], v[174:177], v[240:243], v[82:85]
	v_mfma_f32_16x16x32_bf16 v[134:137], v[170:173], v[220:223], v[134:137]
	v_mfma_f32_16x16x32_bf16 v[130:133], v[178:181], v[220:223], v[130:133]
	v_mfma_f32_16x16x32_bf16 v[118:121], v[170:173], v[228:231], v[118:121]
	v_mfma_f32_16x16x32_bf16 v[114:117], v[178:181], v[228:231], v[114:117]
	v_mfma_f32_16x16x32_bf16 v[102:105], v[170:173], v[236:239], v[102:105]
	v_mfma_f32_16x16x32_bf16 v[98:101], v[178:181], v[236:239], v[98:101]
	v_mfma_f32_16x16x32_bf16 v[86:89], v[170:173], v[244:247], v[86:89]
	v_mfma_f32_16x16x32_bf16 v[82:85], v[178:181], v[244:247], v[82:85]
	s_setprio 0
	s_barrier
; #define PG8_STAGE(bufoff, gbase, voff) do { _Pragma("unroll") for (int _i = 0; _i < 2; ++_i) \
;         __builtin_amdgcn_global_load_lds((const unsigned*)((const char*)(gbase) + (voff)[_i]), (LAS unsigned*)(lds + (bufoff) + ldsw + _i * 8192), 16, 0, 0); } while (0)
; #define PG8_LDA(dst, b, h) do { _Pragma("unroll") for (int m = 0; m < 4; ++m) _Pragma("unroll") for (int k = 0; k < 2; ++k) dst[m][k] = *(const LAS bf16x8*)(lds + PG8_SA(b, h) + aoff + m * 2048 + k * 1024); } while (0)
; #define PG8_MMA(ai, bj, At, Bt) do { __builtin_amdgcn_s_setprio(1); _Pragma("unroll") for (int m = 0; m < 4; ++m) _Pragma("unroll") for (int n = 0; n < 2; ++n) _Pragma("unroll") for (int k = 0; k < 2; ++k) \
;         acc[ai][bj][m][n] = __builtin_amdgcn_mfma_f32_16x16x32_bf16(Bt[n][k], At[m][k], acc[ai][bj][m][n], 0, 0, 0); __builtin_amdgcn_s_setprio(0); } while (0)
; #define PG8_WAIT_V(n) asm volatile("s_waitcnt vmcnt(" #n ")" ::: "memory")
; #define PG8_WAIT_L(n) asm volatile("s_waitcnt lgkmcnt(" #n ")" ::: "memory")
; #define PG8_BAR __builtin_amdgcn_s_barrier()
; #define PG8_SCHED __builtin_amdgcn_sched_barrier(0)
; template <class Epi>
; __device__ __forceinline__ void gemm_phase(LAS unsigned char* lds, const int tid, const Gemm g, const StaticOrder& S, const Epi& E) {
;     ...
;             PG8_LDA(At, 1, 1); PG8_STAGE(PG8_SB(1, 0), b3, voffB); PG8_STAGE(PG8_SB(1, 1), b3 + hstepB, voffB); PG8_STAGE(PG8_SA(1, 0), a3, voffA);
;             PG8_WAIT_V(8); PG8_WAIT_L(0); PG8_BAR; PG8_MMA(1, 0, At, B0); PG8_MMA(1, 1, At, B1); PG8_BAR; PG8_SCHED;
;         }
;         if (wr == 0) PG8_BAR;
	s_add_i32 s0, s0, s82
	v_lshl_add_u64 v[160:161], v[160:161], 0, s[36:37]
	s_mov_b32 m0, s0
	ds_read_b128 v[216:219], v215 offset:49152
	ds_read_b128 v[220:223], v215 offset:50176
	ds_read_b128 v[224:227], v215 offset:51200
	ds_read_b128 v[228:231], v215 offset:52224
	ds_read_b128 v[232:235], v215 offset:53248
	ds_read_b128 v[236:239], v215 offset:54272
	ds_read_b128 v[240:243], v215 offset:55296
	ds_read_b128 v[244:247], v215 offset:56320
	global_load_lds_dwordx4 v[160:161], off
	s_add_i32 m0, s0, 0x2000
	s_add_u32 s10, s70, 0x40080
	v_lshl_add_u64 v[160:161], v[182:183], 0, s[36:37]
	s_addc_u32 s11, s71, 0
	s_add_i32 s0, s1, s82
	global_load_lds_dwordx4 v[160:161], off
	v_lshl_add_u64 v[160:161], s[10:11], 0, v[0:1]
	s_mov_b32 m0, s0
	s_nop 0
	global_load_lds_dwordx4 v[160:161], off
	v_lshl_add_u64 v[160:161], s[10:11], 0, v[146:147]
	s_add_i32 m0, s0, 0x2000
	s_nop 0
	global_load_lds_dwordx4 v[160:161], off
	v_lshl_add_u64 v[160:161], v[162:163], 0, s[36:37]
	s_mov_b32 m0, s93
	s_nop 0
	global_load_lds_dwordx4 v[160:161], off
	v_lshl_add_u64 v[160:161], v[164:165], 0, s[36:37]
	s_mov_b32 m0, s74
	s_nop 0
	global_load_lds_dwordx4 v[160:161], off
	s_waitcnt vmcnt(8)
	s_waitcnt lgkmcnt(0)
	s_barrier
	s_setprio 1
	s_waitcnt lgkmcnt(0)
	v_mfma_f32_16x16x32_bf16 v[78:81], v[58:61], v[216:219], v[78:81]
	v_mfma_f32_16x16x32_bf16 v[74:77], v[66:69], v[216:219], v[74:77]
	v_mfma_f32_16x16x32_bf16 v[46:49], v[58:61], v[224:227], v[46:49]
	v_mfma_f32_16x16x32_bf16 v[42:45], v[66:69], v[224:227], v[42:45]
	v_mfma_f32_16x16x32_bf16 v[30:33], v[58:61], v[232:235], v[30:33]
	v_mfma_f32_16x16x32_bf16 v[26:29], v[66:69], v[232:235], v[26:29]
	v_mfma_f32_16x16x32_bf16 v[14:17], v[58:61], v[240:243], v[14:17]
	v_mfma_f32_16x16x32_bf16 v[10:13], v[66:69], v[240:243], v[10:13]
	v_mfma_f32_16x16x32_bf16 v[78:81], v[62:65], v[220:223], v[78:81]
	v_mfma_f32_16x16x32_bf16 v[74:77], v[70:73], v[220:223], v[74:77]
	v_mfma_f32_16x16x32_bf16 v[46:49], v[62:65], v[228:231], v[46:49]
	v_mfma_f32_16x16x32_bf16 v[42:45], v[70:73], v[228:231], v[42:45]
	v_mfma_f32_16x16x32_bf16 v[30:33], v[62:65], v[236:239], v[30:33]
	v_mfma_f32_16x16x32_bf16 v[26:29], v[70:73], v[236:239], v[26:29]
	v_mfma_f32_16x16x32_bf16 v[14:17], v[62:65], v[244:247], v[14:17]
	v_mfma_f32_16x16x32_bf16 v[10:13], v[70:73], v[244:247], v[10:13]
	v_mfma_f32_16x16x32_bf16 v[50:53], v[156:159], v[216:219], v[50:53]
	v_mfma_f32_16x16x32_bf16 v[62:65], v[170:173], v[220:223], v[50:53]
	v_mfma_f32_16x16x32_bf16 v[50:53], v[174:177], v[216:219], v[54:57]
	v_mfma_f32_16x16x32_bf16 v[38:41], v[156:159], v[224:227], v[38:41]
	v_mfma_f32_16x16x32_bf16 v[34:37], v[174:177], v[224:227], v[34:37]
	v_mfma_f32_16x16x32_bf16 v[22:25], v[156:159], v[232:235], v[22:25]
	v_mfma_f32_16x16x32_bf16 v[18:21], v[174:177], v[232:235], v[18:21]
	v_mfma_f32_16x16x32_bf16 v[6:9], v[156:159], v[240:243], v[6:9]
	v_mfma_f32_16x16x32_bf16 v[2:5], v[174:177], v[240:243], v[2:5]
	v_mfma_f32_16x16x32_bf16 v[58:61], v[178:181], v[220:223], v[50:53]
	v_mfma_f32_16x16x32_bf16 v[38:41], v[170:173], v[228:231], v[38:41]
	v_mfma_f32_16x16x32_bf16 v[34:37], v[178:181], v[228:231], v[34:37]
	v_mfma_f32_16x16x32_bf16 v[22:25], v[170:173], v[236:239], v[22:25]
	v_mfma_f32_16x16x32_bf16 v[18:21], v[178:181], v[236:239], v[18:21]
	v_mfma_f32_16x16x32_bf16 v[6:9], v[170:173], v[244:247], v[6:9]
	v_mfma_f32_16x16x32_bf16 v[2:5], v[178:181], v[244:247], v[2:5]
	s_setprio 0
	s_barrier
	s_add_i32 s16, s16, 2
	s_add_u32 s68, s68, 0x100
	s_addc_u32 s69, s69, 0
	s_add_u32 vcc_hi, vcc_hi, 0x100
	s_addc_u32 s76, s76, 0
	s_cmp_gt_u32 s16, 13
	s_cbranch_scc0 .LBB0_414
	s_and_b64 vcc, exec, s[2:3]
	s_cbranch_vccz .LBB0_417
	s_barrier

; #define PG8_STAGE(bufoff, gbase, voff) do { _Pragma("unroll") for (int _i = 0; _i < 2; ++_i) \
;         __builtin_amdgcn_global_load_lds((const unsigned*)((const char*)(gbase) + (voff)[_i]), (LAS unsigned*)(lds + (bufoff) + ldsw + _i * 8192), 16, 0, 0); } while (0)
; #define PG8_LDA(dst, b, h) do { _Pragma("unroll") for (int m = 0; m < 4; ++m) _Pragma("unroll") for (int k = 0; k < 2; ++k) dst[m][k] = *(const LAS bf16x8*)(lds + PG8_SA(b, h) + aoff + m * 2048 + k * 1024); } while (0)
; #define PG8_LDB(dst, b, h) do { _Pragma("unroll") for (int n = 0; n < 2; ++n) _Pragma("unroll") for (int k = 0; k < 2; ++k) dst[n][k] = *(const LAS bf16x8*)(lds + PG8_SB(b, h) + boff + n * 2048 + k * 1024); } while (0)
; #define PG8_MMA(ai, bj, At, Bt) do { __builtin_amdgcn_s_setprio(1); _Pragma("unroll") for (int m = 0; m < 4; ++m) _Pragma("unroll") for (int n = 0; n < 2; ++n) _Pragma("unroll") for (int k = 0; k < 2; ++k) \
;         acc[ai][bj][m][n] = __builtin_amdgcn_mfma_f32_16x16x32_bf16(Bt[n][k], At[m][k], acc[ai][bj][m][n], 0, 0, 0); __builtin_amdgcn_s_setprio(0); } while (0)
; #define PG8_WAIT_V(n) asm volatile("s_waitcnt vmcnt(" #n ")" ::: "memory")
; #define PG8_WAIT_L(n) asm volatile("s_waitcnt lgkmcnt(" #n ")" ::: "memory")
; #define PG8_BAR __builtin_amdgcn_s_barrier()
; #define PG8_SCHED __builtin_amdgcn_sched_barrier(0)
; template <class Epi>
; __device__ __forceinline__ void gemm_phase(LAS unsigned char* lds, const int tid, const Gemm g, const StaticOrder& S, const Epi& E) {
;     ...
;             const bool last = (t == nt - 2);
;             const char* a1 = cA + (size_t)(t + 1) * kstep;
;             const char* a2 = last ? nA : cA + (size_t)(t + 2) * kstep; const char* b2 = last ? nB : cB + (size_t)(t + 2) * kstep;
;             const char* a3 = a2 + kstep; const char* b3 = b2 + kstep;
;             PG8_LDB(B0, 0, 0); PG8_LDB(B1, 0, 1); PG8_SCHED; PG8_LDA(At, 0, 0); PG8_STAGE(PG8_SA(1, 1), a1 + hstepA, voffA);
;             PG8_WAIT_V(8); PG8_WAIT_L(0); PG8_BAR; PG8_MMA(0, 0, At, B0); PG8_MMA(0, 1, At, B1); PG8_BAR; PG8_SCHED;
;             PG8_LDA(At, 0, 1); PG8_STAGE(PG8_SB(0, 0), b2, voffB); PG8_STAGE(PG8_SB(0, 1), b2 + hstepB, voffB); PG8_STAGE(PG8_SA(0, 0), a2, voffA);
;             PG8_WAIT_V(8); PG8_WAIT_L(0); PG8_BAR; PG8_MMA(1, 0, At, B0); PG8_MMA(1, 1, At, B1); PG8_BAR; PG8_SCHED;
.LBB0_945:
	s_add_u32 s30, s72, 0xfffc0080
	s_addc_u32 s31, s73, -1
	s_add_i32 s76, 0, 0x10000
	s_cmp_eq_u32 vcc_hi, 12
	s_cselect_b32 s75, s9, s31
	s_cselect_b32 s74, s27, s30
	v_add_u32_e32 v0, s76, v178
	s_cselect_b32 s31, s7, vcc_lo
	s_cselect_b32 s30, s28, s65
	s_add_i32 s0, 0, 0x14000
	ds_read_b128 v[18:21], v0
	ds_read_b128 v[22:25], v0 offset:1024
	ds_read_b128 v[26:29], v0 offset:2048
	ds_read_b128 v[30:33], v0 offset:3072
	v_add_u32_e32 v0, s0, v178
	ds_read_b128 v[170:173], v0
	ds_read_b128 v[174:177], v0 offset:1024
	ds_read_b128 v[190:193], v0 offset:2048
	ds_read_b128 v[194:197], v0 offset:3072
	v_lshl_add_u64 v[162:163], s[72:73], 0, v[158:159]
	s_add_i32 m0, s71, 0xc000
	ds_read_b128 v[198:201], v189
	ds_read_b128 v[210:213], v189 offset:1024
	ds_read_b128 v[214:217], v189 offset:2048
	ds_read_b128 v[218:221], v189 offset:3072
	ds_read_b128 v[222:225], v189 offset:4096
	ds_read_b128 v[226:229], v189 offset:5120
	ds_read_b128 v[230:233], v189 offset:6144
	ds_read_b128 v[234:237], v189 offset:7168
	global_load_lds_dwordx4 v[162:163], off
	v_lshl_add_u64 v[162:163], s[72:73], 0, v[160:161]
	s_add_i32 m0, s71, 0xe000
	s_nop 0
	global_load_lds_dwordx4 v[162:163], off
	s_waitcnt vmcnt(8)
	s_waitcnt lgkmcnt(0)
	s_barrier
	s_setprio 1
	s_waitcnt lgkmcnt(0)
	v_mfma_f32_16x16x32_bf16 v[142:145], v[18:21], v[198:201], v[142:145]
	v_mfma_f32_16x16x32_bf16 v[138:141], v[26:29], v[198:201], v[138:141]
	v_mfma_f32_16x16x32_bf16 v[126:129], v[18:21], v[214:217], v[126:129]
	v_mfma_f32_16x16x32_bf16 v[122:125], v[26:29], v[214:217], v[122:125]
	v_mfma_f32_16x16x32_bf16 v[110:113], v[18:21], v[222:225], v[110:113]
	v_mfma_f32_16x16x32_bf16 v[106:109], v[26:29], v[222:225], v[106:109]
	v_mfma_f32_16x16x32_bf16 v[94:97], v[18:21], v[230:233], v[94:97]
	v_mfma_f32_16x16x32_bf16 v[90:93], v[26:29], v[230:233], v[90:93]
	v_mfma_f32_16x16x32_bf16 v[142:145], v[22:25], v[210:213], v[142:145]
	v_mfma_f32_16x16x32_bf16 v[138:141], v[30:33], v[210:213], v[138:141]
	v_mfma_f32_16x16x32_bf16 v[126:129], v[22:25], v[218:221], v[126:129]
	v_mfma_f32_16x16x32_bf16 v[122:125], v[30:33], v[218:221], v[122:125]
	v_mfma_f32_16x16x32_bf16 v[110:113], v[22:25], v[226:229], v[110:113]
	v_mfma_f32_16x16x32_bf16 v[106:109], v[30:33], v[226:229], v[106:109]
	v_mfma_f32_16x16x32_bf16 v[94:97], v[22:25], v[234:237], v[94:97]
	v_mfma_f32_16x16x32_bf16 v[90:93], v[30:33], v[234:237], v[90:93]
	v_mfma_f32_16x16x32_bf16 v[134:137], v[170:173], v[198:201], v[134:137]
	v_mfma_f32_16x16x32_bf16 v[130:133], v[190:193], v[198:201], v[130:133]
	v_mfma_f32_16x16x32_bf16 v[118:121], v[170:173], v[214:217], v[118:121]
	v_mfma_f32_16x16x32_bf16 v[114:117], v[190:193], v[214:217], v[114:117]
	v_mfma_f32_16x16x32_bf16 v[102:105], v[170:173], v[222:225], v[102:105]
	v_mfma_f32_16x16x32_bf16 v[98:101], v[190:193], v[222:225], v[98:101]
	v_mfma_f32_16x16x32_bf16 v[86:89], v[170:173], v[230:233], v[86:89]
	v_mfma_f32_16x16x32_bf16 v[82:85], v[190:193], v[230:233], v[82:85]
	v_mfma_f32_16x16x32_bf16 v[134:137], v[174:177], v[210:213], v[134:137]
	v_mfma_f32_16x16x32_bf16 v[130:133], v[194:197], v[210:213], v[130:133]
	v_mfma_f32_16x16x32_bf16 v[118:121], v[174:177], v[218:221], v[118:121]
	v_mfma_f32_16x16x32_bf16 v[114:117], v[194:197], v[218:221], v[114:117]
	v_mfma_f32_16x16x32_bf16 v[102:105], v[174:177], v[226:229], v[102:105]
	v_mfma_f32_16x16x32_bf16 v[98:101], v[194:197], v[226:229], v[98:101]
	v_mfma_f32_16x16x32_bf16 v[86:89], v[174:177], v[234:237], v[86:89]
	v_mfma_f32_16x16x32_bf16 v[82:85], v[194:197], v[234:237], v[82:85]
	s_setprio 0
	s_barrier
	s_add_i32 s1, s76, s93
	v_lshl_add_u64 v[162:163], s[30:31], 0, v[150:151]
	s_mov_b32 m0, s1
	ds_read_b128 v[198:201], v189 offset:16384
	ds_read_b128 v[210:213], v189 offset:17408
	ds_read_b128 v[214:217], v189 offset:18432
	ds_read_b128 v[218:221], v189 offset:19456
	ds_read_b128 v[222:225], v189 offset:20480
	ds_read_b128 v[226:229], v189 offset:21504
	ds_read_b128 v[230:233], v189 offset:22528
	ds_read_b128 v[234:237], v189 offset:23552
	global_load_lds_dwordx4 v[162:163], off
	s_add_i32 m0, s1, 0x2000
	s_add_u32 s76, s30, 0x40000
	v_lshl_add_u64 v[164:165], s[30:31], 0, v[154:155]
	s_addc_u32 s77, s31, 0
	s_add_i32 s0, s0, s93
	global_load_lds_dwordx4 v[164:165], off
	v_lshl_add_u64 v[202:203], s[76:77], 0, v[150:151]
	s_mov_b32 m0, s0
	v_lshl_add_u64 v[206:207], s[74:75], 0, v[152:153]
	global_load_lds_dwordx4 v[202:203], off
	v_lshl_add_u64 v[202:203], s[76:77], 0, v[154:155]
	s_add_i32 m0, s0, 0x2000
	s_nop 0
	global_load_lds_dwordx4 v[202:203], off
	v_lshl_add_u64 v[202:203], s[74:75], 0, v[148:149]
	s_mov_b32 m0, s71
	s_nop 0
	global_load_lds_dwordx4 v[202:203], off
	s_mov_b32 m0, s88
	s_nop 0
	global_load_lds_dwordx4 v[206:207], off
	s_waitcnt vmcnt(8)
	s_waitcnt lgkmcnt(0)
	s_barrier
; #define PG8_STAGE(bufoff, gbase, voff) do { _Pragma("unroll") for (int _i = 0; _i < 2; ++_i) \
;         __builtin_amdgcn_global_load_lds((const unsigned*)((const char*)(gbase) + (voff)[_i]), (LAS unsigned*)(lds + (bufoff) + ldsw + _i * 8192), 16, 0, 0); } while (0)
; #define PG8_LDA(dst, b, h) do { _Pragma("unroll") for (int m = 0; m < 4; ++m) _Pragma("unroll") for (int k = 0; k < 2; ++k) dst[m][k] = *(const LAS bf16x8*)(lds + PG8_SA(b, h) + aoff + m * 2048 + k * 1024); } while (0)
; #define PG8_LDB(dst, b, h) do { _Pragma("unroll") for (int n = 0; n < 2; ++n) _Pragma("unroll") for (int k = 0; k < 2; ++k) dst[n][k] = *(const LAS bf16x8*)(lds + PG8_SB(b, h) + boff + n * 2048 + k * 1024); } while (0)
; #define PG8_MMA(ai, bj, At, Bt) do { __builtin_amdgcn_s_setprio(1); _Pragma("unroll") for (int m = 0; m < 4; ++m) _Pragma("unroll") for (int n = 0; n < 2; ++n) _Pragma("unroll") for (int k = 0; k < 2; ++k) \
;         acc[ai][bj][m][n] = __builtin_amdgcn_mfma_f32_16x16x32_bf16(Bt[n][k], At[m][k], acc[ai][bj][m][n], 0, 0, 0); __builtin_amdgcn_s_setprio(0); } while (0)
; #define PG8_WAIT_V(n) asm volatile("s_waitcnt vmcnt(" #n ")" ::: "memory")
; #define PG8_WAIT_L(n) asm volatile("s_waitcnt lgkmcnt(" #n ")" ::: "memory")
; #define PG8_BAR __builtin_amdgcn_s_barrier()
; #define PG8_SCHED __builtin_amdgcn_sched_barrier(0)
; template <class Epi>
; __device__ __forceinline__ void gemm_phase(LAS unsigned char* lds, const int tid, const Gemm g, const StaticOrder& S, const Epi& E) {
;     ...
;             PG8_WAIT_V(8); PG8_WAIT_L(0); PG8_BAR; PG8_MMA(1, 0, At, B0); PG8_MMA(1, 1, At, B1); PG8_BAR; PG8_SCHED;
;             PG8_LDB(B0, 1, 0); PG8_LDB(B1, 1, 1); PG8_SCHED; PG8_LDA(At, 1, 0); PG8_STAGE(PG8_SA(0, 1), a2 + hstepA, voffA);
;             PG8_WAIT_V(8); PG8_WAIT_L(0); PG8_BAR; PG8_MMA(0, 0, At, B0); PG8_MMA(0, 1, At, B1); PG8_BAR; PG8_SCHED;
	s_setprio 1
	s_waitcnt lgkmcnt(0)
	v_mfma_f32_16x16x32_bf16 v[78:81], v[18:21], v[198:201], v[78:81]
	v_mfma_f32_16x16x32_bf16 v[74:77], v[26:29], v[198:201], v[74:77]
	v_mfma_f32_16x16x32_bf16 v[62:65], v[18:21], v[214:217], v[62:65]
	v_mfma_f32_16x16x32_bf16 v[58:61], v[26:29], v[214:217], v[58:61]
	v_mfma_f32_16x16x32_bf16 v[46:49], v[18:21], v[222:225], v[46:49]
	v_mfma_f32_16x16x32_bf16 v[42:45], v[26:29], v[222:225], v[42:45]
	v_mfma_f32_16x16x32_bf16 v[14:17], v[18:21], v[230:233], v[14:17]
	v_mfma_f32_16x16x32_bf16 v[10:13], v[26:29], v[230:233], v[10:13]
	v_mfma_f32_16x16x32_bf16 v[78:81], v[22:25], v[210:213], v[78:81]
	v_mfma_f32_16x16x32_bf16 v[74:77], v[30:33], v[210:213], v[74:77]
	v_mfma_f32_16x16x32_bf16 v[62:65], v[22:25], v[218:221], v[62:65]
	v_mfma_f32_16x16x32_bf16 v[58:61], v[30:33], v[218:221], v[58:61]
	v_mfma_f32_16x16x32_bf16 v[46:49], v[22:25], v[226:229], v[46:49]
	v_mfma_f32_16x16x32_bf16 v[42:45], v[30:33], v[226:229], v[42:45]
	v_mfma_f32_16x16x32_bf16 v[14:17], v[22:25], v[234:237], v[14:17]
	v_mfma_f32_16x16x32_bf16 v[10:13], v[30:33], v[234:237], v[10:13]
	v_mfma_f32_16x16x32_bf16 v[38:41], v[170:173], v[222:225], v[38:41]
	v_mfma_f32_16x16x32_bf16 v[34:37], v[190:193], v[222:225], v[34:37]
	v_mfma_f32_16x16x32_bf16 v[6:9], v[170:173], v[230:233], v[6:9]
	v_mfma_f32_16x16x32_bf16 v[2:5], v[190:193], v[230:233], v[2:5]
	v_mfma_f32_16x16x32_bf16 v[18:21], v[170:173], v[198:201], v[70:73]
	v_mfma_f32_16x16x32_bf16 v[22:25], v[190:193], v[198:201], v[66:69]
	v_mfma_f32_16x16x32_bf16 v[26:29], v[170:173], v[214:217], v[54:57]
	v_mfma_f32_16x16x32_bf16 v[30:33], v[190:193], v[214:217], v[50:53]
	v_mfma_f32_16x16x32_bf16 v[38:41], v[174:177], v[226:229], v[38:41]
	v_mfma_f32_16x16x32_bf16 v[34:37], v[194:197], v[226:229], v[34:37]
	v_mfma_f32_16x16x32_bf16 v[6:9], v[174:177], v[234:237], v[6:9]
	v_mfma_f32_16x16x32_bf16 v[2:5], v[194:197], v[234:237], v[2:5]
	v_mfma_f32_16x16x32_bf16 v[18:21], v[174:177], v[210:213], v[18:21]
	v_mfma_f32_16x16x32_bf16 v[22:25], v[194:197], v[210:213], v[22:25]
	v_mfma_f32_16x16x32_bf16 v[26:29], v[174:177], v[218:221], v[26:29]
	v_mfma_f32_16x16x32_bf16 v[30:33], v[194:197], v[218:221], v[30:33]
	s_setprio 0
	s_barrier
	s_add_i32 s0, 0, 0x18000
	v_add_u32_e32 v0, s0, v178
	s_add_i32 s1, 0, 0x1c000
	ds_read_b128 v[50:53], v0
	ds_read_b128 v[54:57], v0 offset:1024
	ds_read_b128 v[66:69], v0 offset:2048
	ds_read_b128 v[70:73], v0 offset:3072
	v_add_u32_e32 v0, s1, v178
	ds_read_b128 v[170:173], v0
	ds_read_b128 v[174:177], v0 offset:1024
	ds_read_b128 v[190:193], v0 offset:2048
	ds_read_b128 v[194:197], v0 offset:3072
	s_add_u32 s74, s74, 0x40000
	s_addc_u32 s75, s75, 0
	s_mov_b32 m0, s83
	v_lshl_add_u64 v[238:239], s[74:75], 0, v[148:149]
	ds_read_b128 v[198:201], v189 offset:32768
	ds_read_b128 v[210:213], v189 offset:33792
	ds_read_b128 v[214:217], v189 offset:34816
	ds_read_b128 v[218:221], v189 offset:35840
	ds_read_b128 v[222:225], v189 offset:36864
	ds_read_b128 v[226:229], v189 offset:37888
	ds_read_b128 v[230:233], v189 offset:38912
	ds_read_b128 v[234:237], v189 offset:39936
	global_load_lds_dwordx4 v[238:239], off
	v_lshl_add_u64 v[238:239], s[74:75], 0, v[152:153]
	s_mov_b32 m0, s16
	s_nop 0
	global_load_lds_dwordx4 v[238:239], off
	s_waitcnt vmcnt(8)
	s_waitcnt lgkmcnt(0)
	s_barrier
	s_setprio 1
	s_waitcnt lgkmcnt(0)
	v_mfma_f32_16x16x32_bf16 v[142:145], v[50:53], v[198:201], v[142:145]
	v_mfma_f32_16x16x32_bf16 v[138:141], v[66:69], v[198:201], v[138:141]
	v_mfma_f32_16x16x32_bf16 v[126:129], v[50:53], v[214:217], v[126:129]
	v_mfma_f32_16x16x32_bf16 v[122:125], v[66:69], v[214:217], v[122:125]
	v_mfma_f32_16x16x32_bf16 v[110:113], v[50:53], v[222:225], v[110:113]
	v_mfma_f32_16x16x32_bf16 v[106:109], v[66:69], v[222:225], v[106:109]
	v_mfma_f32_16x16x32_bf16 v[94:97], v[50:53], v[230:233], v[94:97]
	v_mfma_f32_16x16x32_bf16 v[90:93], v[66:69], v[230:233], v[90:93]
	v_mfma_f32_16x16x32_bf16 v[142:145], v[54:57], v[210:213], v[142:145]
	v_mfma_f32_16x16x32_bf16 v[138:141], v[70:73], v[210:213], v[138:141]
	v_mfma_f32_16x16x32_bf16 v[126:129], v[54:57], v[218:221], v[126:129]
	v_mfma_f32_16x16x32_bf16 v[122:125], v[70:73], v[218:221], v[122:125]
	v_mfma_f32_16x16x32_bf16 v[110:113], v[54:57], v[226:229], v[110:113]
	v_mfma_f32_16x16x32_bf16 v[106:109], v[70:73], v[226:229], v[106:109]
	v_mfma_f32_16x16x32_bf16 v[94:97], v[54:57], v[234:237], v[94:97]
	v_mfma_f32_16x16x32_bf16 v[90:93], v[70:73], v[234:237], v[90:93]
	v_mfma_f32_16x16x32_bf16 v[134:137], v[170:173], v[198:201], v[134:137]
	v_mfma_f32_16x16x32_bf16 v[130:133], v[190:193], v[198:201], v[130:133]
	v_mfma_f32_16x16x32_bf16 v[118:121], v[170:173], v[214:217], v[118:121]
	v_mfma_f32_16x16x32_bf16 v[114:117], v[190:193], v[214:217], v[114:117]
	v_mfma_f32_16x16x32_bf16 v[102:105], v[170:173], v[222:225], v[102:105]
	v_mfma_f32_16x16x32_bf16 v[98:101], v[190:193], v[222:225], v[98:101]
	v_mfma_f32_16x16x32_bf16 v[86:89], v[170:173], v[230:233], v[86:89]
	v_mfma_f32_16x16x32_bf16 v[82:85], v[190:193], v[230:233], v[82:85]
	v_mfma_f32_16x16x32_bf16 v[134:137], v[174:177], v[210:213], v[134:137]
	v_mfma_f32_16x16x32_bf16 v[130:133], v[194:197], v[210:213], v[130:133]
	v_mfma_f32_16x16x32_bf16 v[118:121], v[174:177], v[218:221], v[118:121]
	v_mfma_f32_16x16x32_bf16 v[114:117], v[194:197], v[218:221], v[114:117]
	v_mfma_f32_16x16x32_bf16 v[102:105], v[174:177], v[226:229], v[102:105]
	v_mfma_f32_16x16x32_bf16 v[98:101], v[194:197], v[226:229], v[98:101]
	v_mfma_f32_16x16x32_bf16 v[86:89], v[174:177], v[234:237], v[86:89]
	v_mfma_f32_16x16x32_bf16 v[82:85], v[194:197], v[234:237], v[82:85]
	s_setprio 0
	s_barrier
; #define PG8_STAGE(bufoff, gbase, voff) do { _Pragma("unroll") for (int _i = 0; _i < 2; ++_i) \
;         __builtin_amdgcn_global_load_lds((const unsigned*)((const char*)(gbase) + (voff)[_i]), (LAS unsigned*)(lds + (bufoff) + ldsw + _i * 8192), 16, 0, 0); } while (0)
; #define PG8_LDA(dst, b, h) do { _Pragma("unroll") for (int m = 0; m < 4; ++m) _Pragma("unroll") for (int k = 0; k < 2; ++k) dst[m][k] = *(const LAS bf16x8*)(lds + PG8_SA(b, h) + aoff + m * 2048 + k * 1024); } while (0)
; #define PG8_MMA(ai, bj, At, Bt) do { __builtin_amdgcn_s_setprio(1); _Pragma("unroll") for (int m = 0; m < 4; ++m) _Pragma("unroll") for (int n = 0; n < 2; ++n) _Pragma("unroll") for (int k = 0; k < 2; ++k) \
;         acc[ai][bj][m][n] = __builtin_amdgcn_mfma_f32_16x16x32_bf16(Bt[n][k], At[m][k], acc[ai][bj][m][n], 0, 0, 0); __builtin_amdgcn_s_setprio(0); } while (0)
; #define PG8_WAIT_V(n) asm volatile("s_waitcnt vmcnt(" #n ")" ::: "memory")
; #define PG8_WAIT_L(n) asm volatile("s_waitcnt lgkmcnt(" #n ")" ::: "memory")
; #define PG8_BAR __builtin_amdgcn_s_barrier()
; #define PG8_SCHED __builtin_amdgcn_sched_barrier(0)
; template <class Epi>
; __device__ __forceinline__ void gemm_phase(LAS unsigned char* lds, const int tid, const Gemm g, const StaticOrder& S, const Epi& E) {
;     ...
;             PG8_LDA(At, 1, 1); PG8_STAGE(PG8_SB(1, 0), b3, voffB); PG8_STAGE(PG8_SB(1, 1), b3 + hstepB, voffB); PG8_STAGE(PG8_SA(1, 0), a3, voffA);
;             PG8_WAIT_V(8); PG8_WAIT_L(0); PG8_BAR; PG8_MMA(1, 0, At, B0); PG8_MMA(1, 1, At, B1); PG8_BAR; PG8_SCHED;
;         }
;         if (wr == 0) PG8_BAR;
	s_add_i32 s0, s0, s93
	v_lshl_add_u64 v[162:163], v[162:163], 0, s[36:37]
	s_mov_b32 m0, s0
	ds_read_b128 v[198:201], v189 offset:49152
	ds_read_b128 v[210:213], v189 offset:50176
	ds_read_b128 v[214:217], v189 offset:51200
	ds_read_b128 v[218:221], v189 offset:52224
	ds_read_b128 v[222:225], v189 offset:53248
	ds_read_b128 v[226:229], v189 offset:54272
	ds_read_b128 v[230:233], v189 offset:55296
	ds_read_b128 v[234:237], v189 offset:56320
	global_load_lds_dwordx4 v[162:163], off
	s_add_i32 m0, s0, 0x2000
	s_add_u32 s30, s30, 0x40080
	v_lshl_add_u64 v[162:163], v[164:165], 0, s[36:37]
	s_addc_u32 s31, s31, 0
	s_add_i32 s0, s1, s93
	global_load_lds_dwordx4 v[162:163], off
	v_lshl_add_u64 v[162:163], s[30:31], 0, v[150:151]
	s_mov_b32 m0, s0
	s_nop 0
	global_load_lds_dwordx4 v[162:163], off
	v_lshl_add_u64 v[162:163], s[30:31], 0, v[154:155]
	s_add_i32 m0, s0, 0x2000
	s_nop 0
	global_load_lds_dwordx4 v[162:163], off
	v_lshl_add_u64 v[162:163], v[202:203], 0, s[36:37]
	s_mov_b32 m0, s92
	s_nop 0
	global_load_lds_dwordx4 v[162:163], off
	v_lshl_add_u64 v[162:163], v[206:207], 0, s[36:37]
	s_mov_b32 m0, s89
	s_nop 0
	global_load_lds_dwordx4 v[162:163], off
	s_waitcnt vmcnt(8)
	s_waitcnt lgkmcnt(0)
	s_barrier
	s_setprio 1
	s_waitcnt lgkmcnt(0)
	v_mfma_f32_16x16x32_bf16 v[78:81], v[50:53], v[198:201], v[78:81]
	v_mfma_f32_16x16x32_bf16 v[74:77], v[66:69], v[198:201], v[74:77]
	v_mfma_f32_16x16x32_bf16 v[62:65], v[50:53], v[214:217], v[62:65]
	v_mfma_f32_16x16x32_bf16 v[58:61], v[66:69], v[214:217], v[58:61]
	v_mfma_f32_16x16x32_bf16 v[46:49], v[50:53], v[222:225], v[46:49]
	v_mfma_f32_16x16x32_bf16 v[42:45], v[66:69], v[222:225], v[42:45]
	v_mfma_f32_16x16x32_bf16 v[14:17], v[50:53], v[230:233], v[14:17]
	v_mfma_f32_16x16x32_bf16 v[10:13], v[66:69], v[230:233], v[10:13]
	v_mfma_f32_16x16x32_bf16 v[78:81], v[54:57], v[210:213], v[78:81]
	v_mfma_f32_16x16x32_bf16 v[74:77], v[70:73], v[210:213], v[74:77]
	v_mfma_f32_16x16x32_bf16 v[62:65], v[54:57], v[218:221], v[62:65]
	v_mfma_f32_16x16x32_bf16 v[58:61], v[70:73], v[218:221], v[58:61]
	v_mfma_f32_16x16x32_bf16 v[46:49], v[54:57], v[226:229], v[46:49]
	v_mfma_f32_16x16x32_bf16 v[42:45], v[70:73], v[226:229], v[42:45]
	v_mfma_f32_16x16x32_bf16 v[14:17], v[54:57], v[234:237], v[14:17]
	v_mfma_f32_16x16x32_bf16 v[10:13], v[70:73], v[234:237], v[10:13]
	v_mfma_f32_16x16x32_bf16 v[18:21], v[170:173], v[198:201], v[18:21]
	v_mfma_f32_16x16x32_bf16 v[70:73], v[174:177], v[210:213], v[18:21]
	v_mfma_f32_16x16x32_bf16 v[18:21], v[190:193], v[198:201], v[22:25]
	v_mfma_f32_16x16x32_bf16 v[66:69], v[194:197], v[210:213], v[18:21]
	v_mfma_f32_16x16x32_bf16 v[18:21], v[170:173], v[214:217], v[26:29]
	v_mfma_f32_16x16x32_bf16 v[54:57], v[174:177], v[218:221], v[18:21]
	v_mfma_f32_16x16x32_bf16 v[18:21], v[190:193], v[214:217], v[30:33]
	v_mfma_f32_16x16x32_bf16 v[50:53], v[194:197], v[218:221], v[18:21]
	v_mfma_f32_16x16x32_bf16 v[18:21], v[170:173], v[222:225], v[38:41]
	v_mfma_f32_16x16x32_bf16 v[38:41], v[174:177], v[226:229], v[18:21]
	v_mfma_f32_16x16x32_bf16 v[18:21], v[190:193], v[222:225], v[34:37]
	v_mfma_f32_16x16x32_bf16 v[6:9], v[170:173], v[230:233], v[6:9]
	v_mfma_f32_16x16x32_bf16 v[2:5], v[190:193], v[230:233], v[2:5]
	v_mfma_f32_16x16x32_bf16 v[34:37], v[194:197], v[226:229], v[18:21]
	v_mfma_f32_16x16x32_bf16 v[6:9], v[174:177], v[234:237], v[6:9]
	v_mfma_f32_16x16x32_bf16 v[2:5], v[194:197], v[234:237], v[2:5]
	s_setprio 0
	s_barrier
	s_add_i32 vcc_hi, vcc_hi, 2
	s_add_u32 s72, s72, 0x100
	s_addc_u32 s73, s73, 0
	s_add_u32 s65, s65, 0x100
	s_addc_u32 vcc_lo, vcc_lo, 0
	s_cmp_gt_u32 vcc_hi, 13
	s_cbranch_scc0 .LBB0_945
	s_and_b64 vcc, exec, s[4:5]
	s_cbranch_vccz .LBB0_948
	s_barrier

; #define PG8_STAGE(bufoff, gbase, voff) do { _Pragma("unroll") for (int _i = 0; _i < 2; ++_i) \
;         __builtin_amdgcn_global_load_lds((const unsigned*)((const char*)(gbase) + (voff)[_i]), (LAS unsigned*)(lds + (bufoff) + ldsw + _i * 8192), 16, 0, 0); } while (0)
; #define PG8_LDA(dst, b, h) do { _Pragma("unroll") for (int m = 0; m < 4; ++m) _Pragma("unroll") for (int k = 0; k < 2; ++k) dst[m][k] = *(const LAS bf16x8*)(lds + PG8_SA(b, h) + aoff + m * 2048 + k * 1024); } while (0)
; #define PG8_LDB(dst, b, h) do { _Pragma("unroll") for (int n = 0; n < 2; ++n) _Pragma("unroll") for (int k = 0; k < 2; ++k) dst[n][k] = *(const LAS bf16x8*)(lds + PG8_SB(b, h) + boff + n * 2048 + k * 1024); } while (0)
; #define PG8_MMA(ai, bj, At, Bt) do { __builtin_amdgcn_s_setprio(1); _Pragma("unroll") for (int m = 0; m < 4; ++m) _Pragma("unroll") for (int n = 0; n < 2; ++n) _Pragma("unroll") for (int k = 0; k < 2; ++k) \
;         acc[ai][bj][m][n] = __builtin_amdgcn_mfma_f32_16x16x32_bf16(Bt[n][k], At[m][k], acc[ai][bj][m][n], 0, 0, 0); __builtin_amdgcn_s_setprio(0); } while (0)
; #define PG8_WAIT_V(n) asm volatile("s_waitcnt vmcnt(" #n ")" ::: "memory")
; #define PG8_WAIT_L(n) asm volatile("s_waitcnt lgkmcnt(" #n ")" ::: "memory")
; #define PG8_BAR __builtin_amdgcn_s_barrier()
; #define PG8_SCHED __builtin_amdgcn_sched_barrier(0)
; template <class Epi>
; __device__ __forceinline__ void gemm_phase(LAS unsigned char* lds, const int tid, const Gemm g, const StaticOrder& S, const Epi& E) {
;     ...
;             const bool last = (t == nt - 2);
;             const char* a1 = cA + (size_t)(t + 1) * kstep;
;             const char* a2 = last ? nA : cA + (size_t)(t + 2) * kstep; const char* b2 = last ? nB : cB + (size_t)(t + 2) * kstep;
;             const char* a3 = a2 + kstep; const char* b3 = b2 + kstep;
;             PG8_LDB(B0, 0, 0); PG8_LDB(B1, 0, 1); PG8_SCHED; PG8_LDA(At, 0, 0); PG8_STAGE(PG8_SA(1, 1), a1 + hstepA, voffA);
;             PG8_WAIT_V(8); PG8_WAIT_L(0); PG8_BAR; PG8_MMA(0, 0, At, B0); PG8_MMA(0, 1, At, B1); PG8_BAR; PG8_SCHED;
;             PG8_LDA(At, 0, 1); PG8_STAGE(PG8_SB(0, 0), b2, voffB); PG8_STAGE(PG8_SB(0, 1), b2 + hstepB, voffB); PG8_STAGE(PG8_SA(0, 0), a2, voffA);
;             PG8_WAIT_V(8); PG8_WAIT_L(0); PG8_BAR; PG8_MMA(1, 0, At, B0); PG8_MMA(1, 1, At, B1); PG8_BAR; PG8_SCHED;
.LBB0_1284:
	s_add_u32 s2, s66, 0xfff80080
	s_addc_u32 s3, s67, -1
	s_add_i32 vcc_hi, 0, 0x10000
	s_cmp_eq_u32 vcc_lo, 12
	s_cselect_b32 s69, s11, s3
	s_cselect_b32 s68, s88, s2
	v_add_u32_e32 v144, vcc_hi, v171
	s_cselect_b32 s31, s9, s93
	s_cselect_b32 s30, s89, s92
	s_add_i32 s0, 0, 0x14000
	ds_read_b128 v[140:143], v144
	ds_read_b128 v[176:179], v144 offset:1024
	ds_read_b128 v[180:183], v144 offset:2048
	ds_read_b128 v[184:187], v144 offset:3072
	v_add_u32_e32 v144, s0, v171
	ds_read_b128 v[188:191], v144
	ds_read_b128 v[192:195], v144 offset:1024
	ds_read_b128 v[196:199], v144 offset:2048
	ds_read_b128 v[200:203], v144 offset:3072
	v_lshl_add_u64 v[144:145], s[66:67], 0, v[136:137]
	s_add_i32 m0, s71, 0xc000
	ds_read_b128 v[210:213], v174
	ds_read_b128 v[214:217], v174 offset:1024
	ds_read_b128 v[218:221], v174 offset:2048
	ds_read_b128 v[222:225], v174 offset:3072
	ds_read_b128 v[226:229], v174 offset:4096
	ds_read_b128 v[230:233], v174 offset:5120
	ds_read_b128 v[234:237], v174 offset:6144
	ds_read_b128 v[238:241], v174 offset:7168
	global_load_lds_dwordx4 v[144:145], off
	v_lshl_add_u64 v[144:145], s[66:67], 0, v[138:139]
	s_add_i32 m0, s71, 0xe000
	s_nop 0
	global_load_lds_dwordx4 v[144:145], off
	s_waitcnt vmcnt(8)
	s_waitcnt lgkmcnt(0)
	s_barrier
	s_setprio 1
	s_waitcnt lgkmcnt(0)
	v_mfma_f32_16x16x32_bf16 v[126:129], v[140:143], v[210:213], v[126:129]
	v_mfma_f32_16x16x32_bf16 v[122:125], v[180:183], v[210:213], v[122:125]
	v_mfma_f32_16x16x32_bf16 v[118:121], v[140:143], v[218:221], v[118:121]
	v_mfma_f32_16x16x32_bf16 v[110:113], v[180:183], v[218:221], v[110:113]
	v_mfma_f32_16x16x32_bf16 v[94:97], v[140:143], v[226:229], v[94:97]
	v_mfma_f32_16x16x32_bf16 v[90:93], v[180:183], v[226:229], v[90:93]
	v_mfma_f32_16x16x32_bf16 v[86:89], v[140:143], v[234:237], v[86:89]
	v_mfma_f32_16x16x32_bf16 v[78:81], v[180:183], v[234:237], v[78:81]
	v_mfma_f32_16x16x32_bf16 v[126:129], v[176:179], v[214:217], v[126:129]
	v_mfma_f32_16x16x32_bf16 v[122:125], v[184:187], v[214:217], v[122:125]
	v_mfma_f32_16x16x32_bf16 v[118:121], v[176:179], v[222:225], v[118:121]
	v_mfma_f32_16x16x32_bf16 v[110:113], v[184:187], v[222:225], v[110:113]
	v_mfma_f32_16x16x32_bf16 v[94:97], v[176:179], v[230:233], v[94:97]
	v_mfma_f32_16x16x32_bf16 v[90:93], v[184:187], v[230:233], v[90:93]
	v_mfma_f32_16x16x32_bf16 v[86:89], v[176:179], v[238:241], v[86:89]
	v_mfma_f32_16x16x32_bf16 v[78:81], v[184:187], v[238:241], v[78:81]
	v_mfma_f32_16x16x32_bf16 v[114:117], v[188:191], v[210:213], v[114:117]
	v_mfma_f32_16x16x32_bf16 v[106:109], v[196:199], v[210:213], v[106:109]
	v_mfma_f32_16x16x32_bf16 v[102:105], v[188:191], v[218:221], v[102:105]
	v_mfma_f32_16x16x32_bf16 v[98:101], v[196:199], v[218:221], v[98:101]
	v_mfma_f32_16x16x32_bf16 v[82:85], v[188:191], v[226:229], v[82:85]
	v_mfma_f32_16x16x32_bf16 v[74:77], v[196:199], v[226:229], v[74:77]
	v_mfma_f32_16x16x32_bf16 v[70:73], v[188:191], v[234:237], v[70:73]
	v_mfma_f32_16x16x32_bf16 v[66:69], v[196:199], v[234:237], v[66:69]
	v_mfma_f32_16x16x32_bf16 v[114:117], v[192:195], v[214:217], v[114:117]
	v_mfma_f32_16x16x32_bf16 v[106:109], v[200:203], v[214:217], v[106:109]
	v_mfma_f32_16x16x32_bf16 v[102:105], v[192:195], v[222:225], v[102:105]
	v_mfma_f32_16x16x32_bf16 v[98:101], v[200:203], v[222:225], v[98:101]
	v_mfma_f32_16x16x32_bf16 v[82:85], v[192:195], v[230:233], v[82:85]
	v_mfma_f32_16x16x32_bf16 v[74:77], v[200:203], v[230:233], v[74:77]
	v_mfma_f32_16x16x32_bf16 v[70:73], v[192:195], v[238:241], v[70:73]
	v_mfma_f32_16x16x32_bf16 v[66:69], v[200:203], v[238:241], v[66:69]
	s_setprio 0
	s_barrier
	s_add_i32 s1, vcc_hi, s28
	v_lshl_add_u64 v[144:145], s[30:31], 0, v[0:1]
	s_mov_b32 m0, s1
	ds_read_b128 v[210:213], v174 offset:16384
	ds_read_b128 v[214:217], v174 offset:17408
	ds_read_b128 v[218:221], v174 offset:18432
	ds_read_b128 v[222:225], v174 offset:19456
	ds_read_b128 v[226:229], v174 offset:20480
	ds_read_b128 v[230:233], v174 offset:21504
	ds_read_b128 v[234:237], v174 offset:22528
	ds_read_b128 v[238:241], v174 offset:23552
	global_load_lds_dwordx4 v[144:145], off
	s_add_i32 m0, s1, 0x2000
	s_add_u32 s2, s30, 0x40000
	v_lshl_add_u64 v[162:163], s[30:31], 0, v[130:131]
	s_addc_u32 s3, s31, 0
	s_add_i32 s0, s0, s28
	global_load_lds_dwordx4 v[162:163], off
	v_lshl_add_u64 v[164:165], s[2:3], 0, v[0:1]
	s_mov_b32 m0, s0
	v_lshl_add_u64 v[206:207], s[68:69], 0, v[132:133]
	global_load_lds_dwordx4 v[164:165], off
	v_lshl_add_u64 v[164:165], s[2:3], 0, v[130:131]
	s_add_i32 m0, s0, 0x2000
	s_nop 0
	global_load_lds_dwordx4 v[164:165], off
	v_lshl_add_u64 v[164:165], s[68:69], 0, v[134:135]
	s_mov_b32 m0, s71
	s_nop 0
	global_load_lds_dwordx4 v[164:165], off
	s_mov_b32 m0, s72
	s_nop 0
	global_load_lds_dwordx4 v[206:207], off
	s_waitcnt vmcnt(8)
	s_waitcnt lgkmcnt(0)
	s_barrier
; #define PG8_STAGE(bufoff, gbase, voff) do { _Pragma("unroll") for (int _i = 0; _i < 2; ++_i) \
;         __builtin_amdgcn_global_load_lds((const unsigned*)((const char*)(gbase) + (voff)[_i]), (LAS unsigned*)(lds + (bufoff) + ldsw + _i * 8192), 16, 0, 0); } while (0)
; #define PG8_LDA(dst, b, h) do { _Pragma("unroll") for (int m = 0; m < 4; ++m) _Pragma("unroll") for (int k = 0; k < 2; ++k) dst[m][k] = *(const LAS bf16x8*)(lds + PG8_SA(b, h) + aoff + m * 2048 + k * 1024); } while (0)
; #define PG8_LDB(dst, b, h) do { _Pragma("unroll") for (int n = 0; n < 2; ++n) _Pragma("unroll") for (int k = 0; k < 2; ++k) dst[n][k] = *(const LAS bf16x8*)(lds + PG8_SB(b, h) + boff + n * 2048 + k * 1024); } while (0)
; #define PG8_MMA(ai, bj, At, Bt) do { __builtin_amdgcn_s_setprio(1); _Pragma("unroll") for (int m = 0; m < 4; ++m) _Pragma("unroll") for (int n = 0; n < 2; ++n) _Pragma("unroll") for (int k = 0; k < 2; ++k) \
;         acc[ai][bj][m][n] = __builtin_amdgcn_mfma_f32_16x16x32_bf16(Bt[n][k], At[m][k], acc[ai][bj][m][n], 0, 0, 0); __builtin_amdgcn_s_setprio(0); } while (0)
; #define PG8_WAIT_V(n) asm volatile("s_waitcnt vmcnt(" #n ")" ::: "memory")
; #define PG8_WAIT_L(n) asm volatile("s_waitcnt lgkmcnt(" #n ")" ::: "memory")
; #define PG8_BAR __builtin_amdgcn_s_barrier()
; #define PG8_SCHED __builtin_amdgcn_sched_barrier(0)
; template <class Epi>
; __device__ __forceinline__ void gemm_phase(LAS unsigned char* lds, const int tid, const Gemm g, const StaticOrder& S, const Epi& E) {
;     ...
;             PG8_WAIT_V(8); PG8_WAIT_L(0); PG8_BAR; PG8_MMA(1, 0, At, B0); PG8_MMA(1, 1, At, B1); PG8_BAR; PG8_SCHED;
;             PG8_LDB(B0, 1, 0); PG8_LDB(B1, 1, 1); PG8_SCHED; PG8_LDA(At, 1, 0); PG8_STAGE(PG8_SA(0, 1), a2 + hstepA, voffA);
;             PG8_WAIT_V(8); PG8_WAIT_L(0); PG8_BAR; PG8_MMA(0, 0, At, B0); PG8_MMA(0, 1, At, B1); PG8_BAR; PG8_SCHED;
	s_setprio 1
	s_waitcnt lgkmcnt(0)
	v_mfma_f32_16x16x32_bf16 v[62:65], v[140:143], v[210:213], v[62:65]
	v_mfma_f32_16x16x32_bf16 v[58:61], v[180:183], v[210:213], v[58:61]
	v_mfma_f32_16x16x32_bf16 v[54:57], v[140:143], v[218:221], v[54:57]
	v_mfma_f32_16x16x32_bf16 v[46:49], v[180:183], v[218:221], v[46:49]
	v_mfma_f32_16x16x32_bf16 v[30:33], v[140:143], v[226:229], v[30:33]
	v_mfma_f32_16x16x32_bf16 v[26:29], v[180:183], v[226:229], v[26:29]
	v_mfma_f32_16x16x32_bf16 v[22:25], v[140:143], v[234:237], v[22:25]
	v_mfma_f32_16x16x32_bf16 v[14:17], v[180:183], v[234:237], v[14:17]
	v_mfma_f32_16x16x32_bf16 v[62:65], v[176:179], v[214:217], v[62:65]
	v_mfma_f32_16x16x32_bf16 v[58:61], v[184:187], v[214:217], v[58:61]
	v_mfma_f32_16x16x32_bf16 v[54:57], v[176:179], v[222:225], v[54:57]
	v_mfma_f32_16x16x32_bf16 v[46:49], v[184:187], v[222:225], v[46:49]
	v_mfma_f32_16x16x32_bf16 v[30:33], v[176:179], v[230:233], v[30:33]
	v_mfma_f32_16x16x32_bf16 v[26:29], v[184:187], v[230:233], v[26:29]
	v_mfma_f32_16x16x32_bf16 v[22:25], v[176:179], v[238:241], v[22:25]
	v_mfma_f32_16x16x32_bf16 v[14:17], v[184:187], v[238:241], v[14:17]
	v_mfma_f32_16x16x32_bf16 v[50:53], v[188:191], v[210:213], v[50:53]
	v_mfma_f32_16x16x32_bf16 v[42:45], v[196:199], v[210:213], v[42:45]
	v_mfma_f32_16x16x32_bf16 v[38:41], v[188:191], v[218:221], v[38:41]
	v_mfma_f32_16x16x32_bf16 v[34:37], v[196:199], v[218:221], v[34:37]
	v_mfma_f32_16x16x32_bf16 v[18:21], v[188:191], v[226:229], v[18:21]
	v_mfma_f32_16x16x32_bf16 v[10:13], v[196:199], v[226:229], v[10:13]
	v_mfma_f32_16x16x32_bf16 v[6:9], v[188:191], v[234:237], v[6:9]
	v_mfma_f32_16x16x32_bf16 v[2:5], v[196:199], v[234:237], v[2:5]
	v_mfma_f32_16x16x32_bf16 v[50:53], v[192:195], v[214:217], v[50:53]
	v_mfma_f32_16x16x32_bf16 v[42:45], v[200:203], v[214:217], v[42:45]
	v_mfma_f32_16x16x32_bf16 v[38:41], v[192:195], v[222:225], v[38:41]
	v_mfma_f32_16x16x32_bf16 v[34:37], v[200:203], v[222:225], v[34:37]
	v_mfma_f32_16x16x32_bf16 v[18:21], v[192:195], v[230:233], v[18:21]
	v_mfma_f32_16x16x32_bf16 v[10:13], v[200:203], v[230:233], v[10:13]
	v_mfma_f32_16x16x32_bf16 v[6:9], v[192:195], v[238:241], v[6:9]
	v_mfma_f32_16x16x32_bf16 v[2:5], v[200:203], v[238:241], v[2:5]
	s_setprio 0
	s_barrier
	s_add_i32 s0, 0, 0x18000
	v_add_u32_e32 v175, s0, v171
	s_add_i32 s1, 0, 0x1c000
	ds_read_b128 v[140:143], v175
	ds_read_b128 v[176:179], v175 offset:1024
	ds_read_b128 v[180:183], v175 offset:2048
	ds_read_b128 v[184:187], v175 offset:3072
	v_add_u32_e32 v175, s1, v171
	ds_read_b128 v[188:191], v175
	ds_read_b128 v[192:195], v175 offset:1024
	ds_read_b128 v[196:199], v175 offset:2048
	ds_read_b128 v[200:203], v175 offset:3072
	s_add_u32 s2, s68, 0x80000
	s_addc_u32 s3, s69, 0
	s_mov_b32 m0, s73
	v_lshl_add_u64 v[242:243], s[2:3], 0, v[134:135]
	ds_read_b128 v[210:213], v174 offset:32768
	ds_read_b128 v[214:217], v174 offset:33792
	ds_read_b128 v[218:221], v174 offset:34816
	ds_read_b128 v[222:225], v174 offset:35840
	ds_read_b128 v[226:229], v174 offset:36864
	ds_read_b128 v[230:233], v174 offset:37888
	ds_read_b128 v[234:237], v174 offset:38912
	ds_read_b128 v[238:241], v174 offset:39936
	global_load_lds_dwordx4 v[242:243], off
	v_lshl_add_u64 v[242:243], s[2:3], 0, v[132:133]
	s_mov_b32 m0, s74
	s_nop 0
	global_load_lds_dwordx4 v[242:243], off
	s_waitcnt vmcnt(8)
	s_waitcnt lgkmcnt(0)
	s_barrier
	s_setprio 1
	s_waitcnt lgkmcnt(0)
	v_mfma_f32_16x16x32_bf16 v[126:129], v[140:143], v[210:213], v[126:129]
	v_mfma_f32_16x16x32_bf16 v[122:125], v[180:183], v[210:213], v[122:125]
	v_mfma_f32_16x16x32_bf16 v[118:121], v[140:143], v[218:221], v[118:121]
	v_mfma_f32_16x16x32_bf16 v[110:113], v[180:183], v[218:221], v[110:113]
	v_mfma_f32_16x16x32_bf16 v[94:97], v[140:143], v[226:229], v[94:97]
	v_mfma_f32_16x16x32_bf16 v[90:93], v[180:183], v[226:229], v[90:93]
	v_mfma_f32_16x16x32_bf16 v[86:89], v[140:143], v[234:237], v[86:89]
	v_mfma_f32_16x16x32_bf16 v[78:81], v[180:183], v[234:237], v[78:81]
	v_mfma_f32_16x16x32_bf16 v[126:129], v[176:179], v[214:217], v[126:129]
	v_mfma_f32_16x16x32_bf16 v[122:125], v[184:187], v[214:217], v[122:125]
	v_mfma_f32_16x16x32_bf16 v[118:121], v[176:179], v[222:225], v[118:121]
	v_mfma_f32_16x16x32_bf16 v[110:113], v[184:187], v[222:225], v[110:113]
	v_mfma_f32_16x16x32_bf16 v[94:97], v[176:179], v[230:233], v[94:97]
	v_mfma_f32_16x16x32_bf16 v[90:93], v[184:187], v[230:233], v[90:93]
	v_mfma_f32_16x16x32_bf16 v[86:89], v[176:179], v[238:241], v[86:89]
	v_mfma_f32_16x16x32_bf16 v[78:81], v[184:187], v[238:241], v[78:81]
	v_mfma_f32_16x16x32_bf16 v[114:117], v[188:191], v[210:213], v[114:117]
	v_mfma_f32_16x16x32_bf16 v[106:109], v[196:199], v[210:213], v[106:109]
	v_mfma_f32_16x16x32_bf16 v[102:105], v[188:191], v[218:221], v[102:105]
	v_mfma_f32_16x16x32_bf16 v[98:101], v[196:199], v[218:221], v[98:101]
	v_mfma_f32_16x16x32_bf16 v[82:85], v[188:191], v[226:229], v[82:85]
	v_mfma_f32_16x16x32_bf16 v[74:77], v[196:199], v[226:229], v[74:77]
	v_mfma_f32_16x16x32_bf16 v[70:73], v[188:191], v[234:237], v[70:73]
	v_mfma_f32_16x16x32_bf16 v[66:69], v[196:199], v[234:237], v[66:69]
	v_mfma_f32_16x16x32_bf16 v[114:117], v[192:195], v[214:217], v[114:117]
	v_mfma_f32_16x16x32_bf16 v[106:109], v[200:203], v[214:217], v[106:109]
	v_mfma_f32_16x16x32_bf16 v[102:105], v[192:195], v[222:225], v[102:105]
	v_mfma_f32_16x16x32_bf16 v[98:101], v[200:203], v[222:225], v[98:101]
	v_mfma_f32_16x16x32_bf16 v[82:85], v[192:195], v[230:233], v[82:85]
	v_mfma_f32_16x16x32_bf16 v[74:77], v[200:203], v[230:233], v[74:77]
	v_mfma_f32_16x16x32_bf16 v[70:73], v[192:195], v[238:241], v[70:73]
	v_mfma_f32_16x16x32_bf16 v[66:69], v[200:203], v[238:241], v[66:69]
	s_setprio 0
	s_barrier
; #define PG8_STAGE(bufoff, gbase, voff) do { _Pragma("unroll") for (int _i = 0; _i < 2; ++_i) \
;         __builtin_amdgcn_global_load_lds((const unsigned*)((const char*)(gbase) + (voff)[_i]), (LAS unsigned*)(lds + (bufoff) + ldsw + _i * 8192), 16, 0, 0); } while (0)
; #define PG8_LDA(dst, b, h) do { _Pragma("unroll") for (int m = 0; m < 4; ++m) _Pragma("unroll") for (int k = 0; k < 2; ++k) dst[m][k] = *(const LAS bf16x8*)(lds + PG8_SA(b, h) + aoff + m * 2048 + k * 1024); } while (0)
; #define PG8_MMA(ai, bj, At, Bt) do { __builtin_amdgcn_s_setprio(1); _Pragma("unroll") for (int m = 0; m < 4; ++m) _Pragma("unroll") for (int n = 0; n < 2; ++n) _Pragma("unroll") for (int k = 0; k < 2; ++k) \
;         acc[ai][bj][m][n] = __builtin_amdgcn_mfma_f32_16x16x32_bf16(Bt[n][k], At[m][k], acc[ai][bj][m][n], 0, 0, 0); __builtin_amdgcn_s_setprio(0); } while (0)
; #define PG8_WAIT_V(n) asm volatile("s_waitcnt vmcnt(" #n ")" ::: "memory")
; #define PG8_WAIT_L(n) asm volatile("s_waitcnt lgkmcnt(" #n ")" ::: "memory")
; #define PG8_BAR __builtin_amdgcn_s_barrier()
; #define PG8_SCHED __builtin_amdgcn_sched_barrier(0)
; template <class Epi>
; __device__ __forceinline__ void gemm_phase(LAS unsigned char* lds, const int tid, const Gemm g, const StaticOrder& S, const Epi& E) {
;     ...
;             PG8_LDA(At, 1, 1); PG8_STAGE(PG8_SB(1, 0), b3, voffB); PG8_STAGE(PG8_SB(1, 1), b3 + hstepB, voffB); PG8_STAGE(PG8_SA(1, 0), a3, voffA);
;             PG8_WAIT_V(8); PG8_WAIT_L(0); PG8_BAR; PG8_MMA(1, 0, At, B0); PG8_MMA(1, 1, At, B1); PG8_BAR; PG8_SCHED;
;         }
;         if (wr == 0) PG8_BAR;
	s_add_i32 s0, s0, s28
	v_lshl_add_u64 v[144:145], v[144:145], 0, s[36:37]
	s_mov_b32 m0, s0
	ds_read_b128 v[210:213], v174 offset:49152
	ds_read_b128 v[214:217], v174 offset:50176
	ds_read_b128 v[218:221], v174 offset:51200
	ds_read_b128 v[222:225], v174 offset:52224
	ds_read_b128 v[226:229], v174 offset:53248
	ds_read_b128 v[230:233], v174 offset:54272
	ds_read_b128 v[234:237], v174 offset:55296
	ds_read_b128 v[238:241], v174 offset:56320
	global_load_lds_dwordx4 v[144:145], off
	s_add_i32 m0, s0, 0x2000
	s_add_u32 s2, s30, 0x40080
	v_lshl_add_u64 v[144:145], v[162:163], 0, s[36:37]
	s_addc_u32 s3, s31, 0
	s_add_i32 s0, s1, s28
	global_load_lds_dwordx4 v[144:145], off
	v_lshl_add_u64 v[144:145], s[2:3], 0, v[0:1]
	s_mov_b32 m0, s0
	s_nop 0
	global_load_lds_dwordx4 v[144:145], off
	v_lshl_add_u64 v[144:145], s[2:3], 0, v[130:131]
	s_add_i32 m0, s0, 0x2000
	s_nop 0
	global_load_lds_dwordx4 v[144:145], off
	v_lshl_add_u64 v[144:145], v[164:165], 0, s[36:37]
	s_mov_b32 m0, s75
	s_nop 0
	global_load_lds_dwordx4 v[144:145], off
	v_lshl_add_u64 v[144:145], v[206:207], 0, s[36:37]
	s_mov_b32 m0, s76
	s_nop 0
	global_load_lds_dwordx4 v[144:145], off
	s_waitcnt vmcnt(8)
	s_waitcnt lgkmcnt(0)
	s_barrier
	s_setprio 1
	s_waitcnt lgkmcnt(0)
	v_mfma_f32_16x16x32_bf16 v[62:65], v[140:143], v[210:213], v[62:65]
	v_mfma_f32_16x16x32_bf16 v[58:61], v[180:183], v[210:213], v[58:61]
	v_mfma_f32_16x16x32_bf16 v[54:57], v[140:143], v[218:221], v[54:57]
	v_mfma_f32_16x16x32_bf16 v[46:49], v[180:183], v[218:221], v[46:49]
	v_mfma_f32_16x16x32_bf16 v[30:33], v[140:143], v[226:229], v[30:33]
	v_mfma_f32_16x16x32_bf16 v[26:29], v[180:183], v[226:229], v[26:29]
	v_mfma_f32_16x16x32_bf16 v[22:25], v[140:143], v[234:237], v[22:25]
	v_mfma_f32_16x16x32_bf16 v[14:17], v[180:183], v[234:237], v[14:17]
	v_mfma_f32_16x16x32_bf16 v[62:65], v[176:179], v[214:217], v[62:65]
	v_mfma_f32_16x16x32_bf16 v[58:61], v[184:187], v[214:217], v[58:61]
	v_mfma_f32_16x16x32_bf16 v[54:57], v[176:179], v[222:225], v[54:57]
	v_mfma_f32_16x16x32_bf16 v[46:49], v[184:187], v[222:225], v[46:49]
	v_mfma_f32_16x16x32_bf16 v[30:33], v[176:179], v[230:233], v[30:33]
	v_mfma_f32_16x16x32_bf16 v[26:29], v[184:187], v[230:233], v[26:29]
	v_mfma_f32_16x16x32_bf16 v[22:25], v[176:179], v[238:241], v[22:25]
	v_mfma_f32_16x16x32_bf16 v[14:17], v[184:187], v[238:241], v[14:17]
	v_mfma_f32_16x16x32_bf16 v[50:53], v[188:191], v[210:213], v[50:53]
	v_mfma_f32_16x16x32_bf16 v[42:45], v[196:199], v[210:213], v[42:45]
	v_mfma_f32_16x16x32_bf16 v[38:41], v[188:191], v[218:221], v[38:41]
	v_mfma_f32_16x16x32_bf16 v[34:37], v[196:199], v[218:221], v[34:37]
	v_mfma_f32_16x16x32_bf16 v[18:21], v[188:191], v[226:229], v[18:21]
	v_mfma_f32_16x16x32_bf16 v[10:13], v[196:199], v[226:229], v[10:13]
	v_mfma_f32_16x16x32_bf16 v[6:9], v[188:191], v[234:237], v[6:9]
	v_mfma_f32_16x16x32_bf16 v[2:5], v[196:199], v[234:237], v[2:5]
	v_mfma_f32_16x16x32_bf16 v[50:53], v[192:195], v[214:217], v[50:53]
	v_mfma_f32_16x16x32_bf16 v[42:45], v[200:203], v[214:217], v[42:45]
	v_mfma_f32_16x16x32_bf16 v[38:41], v[192:195], v[222:225], v[38:41]
	v_mfma_f32_16x16x32_bf16 v[34:37], v[200:203], v[222:225], v[34:37]
	v_mfma_f32_16x16x32_bf16 v[18:21], v[192:195], v[230:233], v[18:21]
	v_mfma_f32_16x16x32_bf16 v[10:13], v[200:203], v[230:233], v[10:13]
	v_mfma_f32_16x16x32_bf16 v[6:9], v[192:195], v[238:241], v[6:9]
	v_mfma_f32_16x16x32_bf16 v[2:5], v[200:203], v[238:241], v[2:5]
	s_setprio 0
	s_barrier
	s_add_i32 vcc_lo, vcc_lo, 2
	s_add_u32 s66, s66, 0x100
	s_addc_u32 s67, s67, 0
	s_add_u32 s92, s92, 0x100
	s_addc_u32 s93, s93, 0
	s_cmp_gt_u32 vcc_lo, 13
	s_cbranch_scc0 .LBB0_1284
	s_and_b64 vcc, exec, s[6:7]
	s_mov_b32 s92, 0x2c000
	s_mov_b32 s93, 0x2e000
	s_cbranch_vccz .LBB0_1287
	s_barrier

; #define PG8_STAGE(bufoff, gbase, voff) do { _Pragma("unroll") for (int _i = 0; _i < 2; ++_i) \
;         __builtin_amdgcn_global_load_lds((const unsigned*)((const char*)(gbase) + (voff)[_i]), (LAS unsigned*)(lds + (bufoff) + ldsw + _i * 8192), 16, 0, 0); } while (0)
; #define PG8_LDA(dst, b, h) do { _Pragma("unroll") for (int m = 0; m < 4; ++m) _Pragma("unroll") for (int k = 0; k < 2; ++k) dst[m][k] = *(const LAS bf16x8*)(lds + PG8_SA(b, h) + aoff + m * 2048 + k * 1024); } while (0)
; #define PG8_LDB(dst, b, h) do { _Pragma("unroll") for (int n = 0; n < 2; ++n) _Pragma("unroll") for (int k = 0; k < 2; ++k) dst[n][k] = *(const LAS bf16x8*)(lds + PG8_SB(b, h) + boff + n * 2048 + k * 1024); } while (0)
; #define PG8_MMA(ai, bj, At, Bt) do { __builtin_amdgcn_s_setprio(1); _Pragma("unroll") for (int m = 0; m < 4; ++m) _Pragma("unroll") for (int n = 0; n < 2; ++n) _Pragma("unroll") for (int k = 0; k < 2; ++k) \
;         acc[ai][bj][m][n] = __builtin_amdgcn_mfma_f32_16x16x32_bf16(Bt[n][k], At[m][k], acc[ai][bj][m][n], 0, 0, 0); __builtin_amdgcn_s_setprio(0); } while (0)
; #define PG8_WAIT_V(n) asm volatile("s_waitcnt vmcnt(" #n ")" ::: "memory")
; #define PG8_WAIT_L(n) asm volatile("s_waitcnt lgkmcnt(" #n ")" ::: "memory")
; #define PG8_BAR __builtin_amdgcn_s_barrier()
; #define PG8_SCHED __builtin_amdgcn_sched_barrier(0)
; template <class Epi>
; __device__ __forceinline__ void gemm_phase(LAS unsigned char* lds, const int tid, const Gemm g, const StaticOrder& S, const Epi& E) {
;     ...
;             const bool last = (t == nt - 2);
;             const char* a1 = cA + (size_t)(t + 1) * kstep;
;             const char* a2 = last ? nA : cA + (size_t)(t + 2) * kstep; const char* b2 = last ? nB : cB + (size_t)(t + 2) * kstep;
;             const char* a3 = a2 + kstep; const char* b3 = b2 + kstep;
;             PG8_LDB(B0, 0, 0); PG8_LDB(B1, 0, 1); PG8_SCHED; PG8_LDA(At, 0, 0); PG8_STAGE(PG8_SA(1, 1), a1 + hstepA, voffA);
;             PG8_WAIT_V(8); PG8_WAIT_L(0); PG8_BAR; PG8_MMA(0, 0, At, B0); PG8_MMA(0, 1, At, B1); PG8_BAR; PG8_SCHED;
;             PG8_LDA(At, 0, 1); PG8_STAGE(PG8_SB(0, 0), b2, voffB); PG8_STAGE(PG8_SB(0, 1), b2 + hstepB, voffB); PG8_STAGE(PG8_SA(0, 0), a2, voffA);
;             PG8_WAIT_V(8); PG8_WAIT_L(0); PG8_BAR; PG8_MMA(1, 0, At, B0); PG8_MMA(1, 1, At, B1); PG8_BAR; PG8_SCHED;
.LBB0_1333:
	s_add_u32 s0, s66, 0xfff80080
	s_addc_u32 s1, s67, -1
	s_add_i32 s2, 0, 0x10000
	s_cmp_eq_u32 vcc_lo, 12
	s_cselect_b32 s69, s11, s1
	s_cselect_b32 s68, s88, s0
	s_cselect_b32 s31, s9, s93
	s_cselect_b32 s30, s89, s92
	s_add_i32 s0, 0, 0x14000
	v_add_u32_e32 v142, s2, v189
	v_add_u32_e32 v162, s0, v189
	ds_read_b128 v[130:133], v142
	ds_read_b128 v[134:137], v142 offset:1024
	ds_read_b128 v[138:141], v142 offset:2048
	ds_read_b128 v[142:145], v142 offset:3072
	ds_read_b128 v[158:161], v162
	ds_read_b128 v[192:195], v162 offset:1024
	ds_read_b128 v[196:199], v162 offset:2048
	ds_read_b128 v[200:203], v162 offset:3072
	v_lshl_add_u64 v[162:163], s[66:67], 0, v[154:155]
	s_add_i32 m0, s71, 0xc000
	ds_read_b128 v[210:213], v191
	ds_read_b128 v[214:217], v191 offset:1024
	ds_read_b128 v[218:221], v191 offset:2048
	ds_read_b128 v[222:225], v191 offset:3072
	ds_read_b128 v[226:229], v191 offset:4096
	ds_read_b128 v[230:233], v191 offset:5120
	ds_read_b128 v[234:237], v191 offset:6144
	ds_read_b128 v[238:241], v191 offset:7168
	global_load_lds_dwordx4 v[162:163], off
	v_lshl_add_u64 v[162:163], s[66:67], 0, v[156:157]
	s_add_i32 m0, s71, 0xe000
	s_nop 0
	global_load_lds_dwordx4 v[162:163], off
	s_waitcnt vmcnt(8)
	s_waitcnt lgkmcnt(0)
	s_barrier
	s_setprio 1
	s_waitcnt lgkmcnt(0)
	v_mfma_f32_16x16x32_bf16 v[126:129], v[130:133], v[210:213], v[126:129]
	v_mfma_f32_16x16x32_bf16 v[122:125], v[138:141], v[210:213], v[122:125]
	v_mfma_f32_16x16x32_bf16 v[110:113], v[130:133], v[218:221], v[110:113]
	v_mfma_f32_16x16x32_bf16 v[106:109], v[138:141], v[218:221], v[106:109]
	v_mfma_f32_16x16x32_bf16 v[94:97], v[130:133], v[226:229], v[94:97]
	v_mfma_f32_16x16x32_bf16 v[90:93], v[138:141], v[226:229], v[90:93]
	v_mfma_f32_16x16x32_bf16 v[78:81], v[130:133], v[234:237], v[78:81]
	v_mfma_f32_16x16x32_bf16 v[74:77], v[138:141], v[234:237], v[74:77]
	v_mfma_f32_16x16x32_bf16 v[126:129], v[134:137], v[214:217], v[126:129]
	v_mfma_f32_16x16x32_bf16 v[122:125], v[142:145], v[214:217], v[122:125]
	v_mfma_f32_16x16x32_bf16 v[110:113], v[134:137], v[222:225], v[110:113]
	v_mfma_f32_16x16x32_bf16 v[106:109], v[142:145], v[222:225], v[106:109]
	v_mfma_f32_16x16x32_bf16 v[94:97], v[134:137], v[230:233], v[94:97]
	v_mfma_f32_16x16x32_bf16 v[90:93], v[142:145], v[230:233], v[90:93]
	v_mfma_f32_16x16x32_bf16 v[78:81], v[134:137], v[238:241], v[78:81]
	v_mfma_f32_16x16x32_bf16 v[74:77], v[142:145], v[238:241], v[74:77]
	v_mfma_f32_16x16x32_bf16 v[118:121], v[158:161], v[210:213], v[118:121]
	v_mfma_f32_16x16x32_bf16 v[114:117], v[196:199], v[210:213], v[114:117]
	v_mfma_f32_16x16x32_bf16 v[102:105], v[158:161], v[218:221], v[102:105]
	v_mfma_f32_16x16x32_bf16 v[98:101], v[196:199], v[218:221], v[98:101]
	v_mfma_f32_16x16x32_bf16 v[86:89], v[158:161], v[226:229], v[86:89]
	v_mfma_f32_16x16x32_bf16 v[82:85], v[196:199], v[226:229], v[82:85]
	v_mfma_f32_16x16x32_bf16 v[70:73], v[158:161], v[234:237], v[70:73]
	v_mfma_f32_16x16x32_bf16 v[66:69], v[196:199], v[234:237], v[66:69]
	v_mfma_f32_16x16x32_bf16 v[118:121], v[192:195], v[214:217], v[118:121]
	v_mfma_f32_16x16x32_bf16 v[114:117], v[200:203], v[214:217], v[114:117]
	v_mfma_f32_16x16x32_bf16 v[102:105], v[192:195], v[222:225], v[102:105]
	v_mfma_f32_16x16x32_bf16 v[98:101], v[200:203], v[222:225], v[98:101]
	v_mfma_f32_16x16x32_bf16 v[86:89], v[192:195], v[230:233], v[86:89]
	v_mfma_f32_16x16x32_bf16 v[82:85], v[200:203], v[230:233], v[82:85]
	v_mfma_f32_16x16x32_bf16 v[70:73], v[192:195], v[238:241], v[70:73]
	v_mfma_f32_16x16x32_bf16 v[66:69], v[200:203], v[238:241], v[66:69]
	s_setprio 0
	s_barrier
	s_add_i32 s1, s2, s28
	v_lshl_add_u64 v[162:163], s[30:31], 0, v[0:1]
	s_mov_b32 m0, s1
	ds_read_b128 v[210:213], v191 offset:16384
	ds_read_b128 v[214:217], v191 offset:17408
	ds_read_b128 v[218:221], v191 offset:18432
	ds_read_b128 v[222:225], v191 offset:19456
	ds_read_b128 v[226:229], v191 offset:20480
	ds_read_b128 v[230:233], v191 offset:21504
	ds_read_b128 v[234:237], v191 offset:22528
	ds_read_b128 v[238:241], v191 offset:23552
	global_load_lds_dwordx4 v[162:163], off
	s_add_i32 m0, s1, 0x2000
	s_add_u32 s2, s30, 0x40000
	v_lshl_add_u64 v[164:165], s[30:31], 0, v[148:149]
	s_addc_u32 s3, s31, 0
	s_add_i32 s0, s0, s28
	global_load_lds_dwordx4 v[164:165], off
	v_lshl_add_u64 v[170:171], s[2:3], 0, v[0:1]
	s_mov_b32 m0, s0
	v_lshl_add_u64 v[206:207], s[68:69], 0, v[150:151]
	global_load_lds_dwordx4 v[170:171], off
	v_lshl_add_u64 v[170:171], s[2:3], 0, v[148:149]
	s_add_i32 m0, s0, 0x2000
	s_nop 0
	global_load_lds_dwordx4 v[170:171], off
	v_lshl_add_u64 v[170:171], s[68:69], 0, v[152:153]
	s_mov_b32 m0, s71
	s_nop 0
	global_load_lds_dwordx4 v[170:171], off
	s_mov_b32 m0, s72
	s_nop 0
	global_load_lds_dwordx4 v[206:207], off
	s_waitcnt vmcnt(8)
	s_waitcnt lgkmcnt(0)
	s_barrier
; #define PG8_STAGE(bufoff, gbase, voff) do { _Pragma("unroll") for (int _i = 0; _i < 2; ++_i) \
;         __builtin_amdgcn_global_load_lds((const unsigned*)((const char*)(gbase) + (voff)[_i]), (LAS unsigned*)(lds + (bufoff) + ldsw + _i * 8192), 16, 0, 0); } while (0)
; #define PG8_LDA(dst, b, h) do { _Pragma("unroll") for (int m = 0; m < 4; ++m) _Pragma("unroll") for (int k = 0; k < 2; ++k) dst[m][k] = *(const LAS bf16x8*)(lds + PG8_SA(b, h) + aoff + m * 2048 + k * 1024); } while (0)
; #define PG8_LDB(dst, b, h) do { _Pragma("unroll") for (int n = 0; n < 2; ++n) _Pragma("unroll") for (int k = 0; k < 2; ++k) dst[n][k] = *(const LAS bf16x8*)(lds + PG8_SB(b, h) + boff + n * 2048 + k * 1024); } while (0)
; #define PG8_MMA(ai, bj, At, Bt) do { __builtin_amdgcn_s_setprio(1); _Pragma("unroll") for (int m = 0; m < 4; ++m) _Pragma("unroll") for (int n = 0; n < 2; ++n) _Pragma("unroll") for (int k = 0; k < 2; ++k) \
;         acc[ai][bj][m][n] = __builtin_amdgcn_mfma_f32_16x16x32_bf16(Bt[n][k], At[m][k], acc[ai][bj][m][n], 0, 0, 0); __builtin_amdgcn_s_setprio(0); } while (0)
; #define PG8_WAIT_V(n) asm volatile("s_waitcnt vmcnt(" #n ")" ::: "memory")
; #define PG8_WAIT_L(n) asm volatile("s_waitcnt lgkmcnt(" #n ")" ::: "memory")
; #define PG8_BAR __builtin_amdgcn_s_barrier()
; #define PG8_SCHED __builtin_amdgcn_sched_barrier(0)
; template <class Epi>
; __device__ __forceinline__ void gemm_phase(LAS unsigned char* lds, const int tid, const Gemm g, const StaticOrder& S, const Epi& E) {
;     ...
;             PG8_WAIT_V(8); PG8_WAIT_L(0); PG8_BAR; PG8_MMA(1, 0, At, B0); PG8_MMA(1, 1, At, B1); PG8_BAR; PG8_SCHED;
;             PG8_LDB(B0, 1, 0); PG8_LDB(B1, 1, 1); PG8_SCHED; PG8_LDA(At, 1, 0); PG8_STAGE(PG8_SA(0, 1), a2 + hstepA, voffA);
;             PG8_WAIT_V(8); PG8_WAIT_L(0); PG8_BAR; PG8_MMA(0, 0, At, B0); PG8_MMA(0, 1, At, B1); PG8_BAR; PG8_SCHED;
	s_setprio 1
	s_waitcnt lgkmcnt(0)
	v_mfma_f32_16x16x32_bf16 v[62:65], v[130:133], v[210:213], v[62:65]
	v_mfma_f32_16x16x32_bf16 v[58:61], v[138:141], v[210:213], v[58:61]
	v_mfma_f32_16x16x32_bf16 v[46:49], v[130:133], v[218:221], v[46:49]
	v_mfma_f32_16x16x32_bf16 v[42:45], v[138:141], v[218:221], v[42:45]
	v_mfma_f32_16x16x32_bf16 v[30:33], v[130:133], v[226:229], v[30:33]
	v_mfma_f32_16x16x32_bf16 v[26:29], v[138:141], v[226:229], v[26:29]
	v_mfma_f32_16x16x32_bf16 v[14:17], v[130:133], v[234:237], v[14:17]
	v_mfma_f32_16x16x32_bf16 v[10:13], v[138:141], v[234:237], v[10:13]
	v_mfma_f32_16x16x32_bf16 v[62:65], v[134:137], v[214:217], v[62:65]
	v_mfma_f32_16x16x32_bf16 v[58:61], v[142:145], v[214:217], v[58:61]
	v_mfma_f32_16x16x32_bf16 v[46:49], v[134:137], v[222:225], v[46:49]
	v_mfma_f32_16x16x32_bf16 v[42:45], v[142:145], v[222:225], v[42:45]
	v_mfma_f32_16x16x32_bf16 v[30:33], v[134:137], v[230:233], v[30:33]
	v_mfma_f32_16x16x32_bf16 v[26:29], v[142:145], v[230:233], v[26:29]
	v_mfma_f32_16x16x32_bf16 v[14:17], v[134:137], v[238:241], v[14:17]
	v_mfma_f32_16x16x32_bf16 v[10:13], v[142:145], v[238:241], v[10:13]
	v_mfma_f32_16x16x32_bf16 v[54:57], v[158:161], v[210:213], v[54:57]
	v_mfma_f32_16x16x32_bf16 v[50:53], v[196:199], v[210:213], v[50:53]
	v_mfma_f32_16x16x32_bf16 v[38:41], v[158:161], v[218:221], v[38:41]
	v_mfma_f32_16x16x32_bf16 v[34:37], v[196:199], v[218:221], v[34:37]
	v_mfma_f32_16x16x32_bf16 v[22:25], v[158:161], v[226:229], v[22:25]
	v_mfma_f32_16x16x32_bf16 v[18:21], v[196:199], v[226:229], v[18:21]
	v_mfma_f32_16x16x32_bf16 v[6:9], v[158:161], v[234:237], v[6:9]
	v_mfma_f32_16x16x32_bf16 v[2:5], v[196:199], v[234:237], v[2:5]
	v_mfma_f32_16x16x32_bf16 v[54:57], v[192:195], v[214:217], v[54:57]
	v_mfma_f32_16x16x32_bf16 v[50:53], v[200:203], v[214:217], v[50:53]
	v_mfma_f32_16x16x32_bf16 v[38:41], v[192:195], v[222:225], v[38:41]
	v_mfma_f32_16x16x32_bf16 v[34:37], v[200:203], v[222:225], v[34:37]
	v_mfma_f32_16x16x32_bf16 v[22:25], v[192:195], v[230:233], v[22:25]
	v_mfma_f32_16x16x32_bf16 v[18:21], v[200:203], v[230:233], v[18:21]
	v_mfma_f32_16x16x32_bf16 v[6:9], v[192:195], v[238:241], v[6:9]
	v_mfma_f32_16x16x32_bf16 v[2:5], v[200:203], v[238:241], v[2:5]
	s_setprio 0
	s_barrier
	s_add_i32 s0, 0, 0x18000
	s_add_i32 s1, 0, 0x1c000
	v_add_u32_e32 v142, s0, v189
	v_add_u32_e32 v200, s1, v189
	ds_read_b128 v[130:133], v142
	ds_read_b128 v[134:137], v142 offset:1024
	ds_read_b128 v[138:141], v142 offset:2048
	ds_read_b128 v[142:145], v142 offset:3072
	ds_read_b128 v[158:161], v200
	ds_read_b128 v[192:195], v200 offset:1024
	ds_read_b128 v[196:199], v200 offset:2048
	ds_read_b128 v[200:203], v200 offset:3072
	s_add_u32 s2, s68, 0x80000
	s_addc_u32 s3, s69, 0
	s_mov_b32 m0, s73
	v_lshl_add_u64 v[242:243], s[2:3], 0, v[152:153]
	ds_read_b128 v[210:213], v191 offset:32768
	ds_read_b128 v[214:217], v191 offset:33792
	ds_read_b128 v[218:221], v191 offset:34816
	ds_read_b128 v[222:225], v191 offset:35840
	ds_read_b128 v[226:229], v191 offset:36864
	ds_read_b128 v[230:233], v191 offset:37888
	ds_read_b128 v[234:237], v191 offset:38912
	ds_read_b128 v[238:241], v191 offset:39936
	global_load_lds_dwordx4 v[242:243], off
	v_lshl_add_u64 v[242:243], s[2:3], 0, v[150:151]
	s_mov_b32 m0, s74
	s_nop 0
	global_load_lds_dwordx4 v[242:243], off
	s_waitcnt vmcnt(8)
	s_waitcnt lgkmcnt(0)
	s_barrier
	s_setprio 1
	s_waitcnt lgkmcnt(0)
	v_mfma_f32_16x16x32_bf16 v[126:129], v[130:133], v[210:213], v[126:129]
	v_mfma_f32_16x16x32_bf16 v[122:125], v[138:141], v[210:213], v[122:125]
	v_mfma_f32_16x16x32_bf16 v[110:113], v[130:133], v[218:221], v[110:113]
	v_mfma_f32_16x16x32_bf16 v[106:109], v[138:141], v[218:221], v[106:109]
	v_mfma_f32_16x16x32_bf16 v[94:97], v[130:133], v[226:229], v[94:97]
	v_mfma_f32_16x16x32_bf16 v[90:93], v[138:141], v[226:229], v[90:93]
	v_mfma_f32_16x16x32_bf16 v[78:81], v[130:133], v[234:237], v[78:81]
	v_mfma_f32_16x16x32_bf16 v[74:77], v[138:141], v[234:237], v[74:77]
	v_mfma_f32_16x16x32_bf16 v[126:129], v[134:137], v[214:217], v[126:129]
	v_mfma_f32_16x16x32_bf16 v[122:125], v[142:145], v[214:217], v[122:125]
	v_mfma_f32_16x16x32_bf16 v[110:113], v[134:137], v[222:225], v[110:113]
	v_mfma_f32_16x16x32_bf16 v[106:109], v[142:145], v[222:225], v[106:109]
	v_mfma_f32_16x16x32_bf16 v[94:97], v[134:137], v[230:233], v[94:97]
	v_mfma_f32_16x16x32_bf16 v[90:93], v[142:145], v[230:233], v[90:93]
	v_mfma_f32_16x16x32_bf16 v[78:81], v[134:137], v[238:241], v[78:81]
	v_mfma_f32_16x16x32_bf16 v[74:77], v[142:145], v[238:241], v[74:77]
	v_mfma_f32_16x16x32_bf16 v[118:121], v[158:161], v[210:213], v[118:121]
	v_mfma_f32_16x16x32_bf16 v[114:117], v[196:199], v[210:213], v[114:117]
	v_mfma_f32_16x16x32_bf16 v[102:105], v[158:161], v[218:221], v[102:105]
	v_mfma_f32_16x16x32_bf16 v[98:101], v[196:199], v[218:221], v[98:101]
	v_mfma_f32_16x16x32_bf16 v[86:89], v[158:161], v[226:229], v[86:89]
	v_mfma_f32_16x16x32_bf16 v[82:85], v[196:199], v[226:229], v[82:85]
	v_mfma_f32_16x16x32_bf16 v[70:73], v[158:161], v[234:237], v[70:73]
	v_mfma_f32_16x16x32_bf16 v[66:69], v[196:199], v[234:237], v[66:69]
	v_mfma_f32_16x16x32_bf16 v[118:121], v[192:195], v[214:217], v[118:121]
	v_mfma_f32_16x16x32_bf16 v[114:117], v[200:203], v[214:217], v[114:117]
	v_mfma_f32_16x16x32_bf16 v[102:105], v[192:195], v[222:225], v[102:105]
	v_mfma_f32_16x16x32_bf16 v[98:101], v[200:203], v[222:225], v[98:101]
	v_mfma_f32_16x16x32_bf16 v[86:89], v[192:195], v[230:233], v[86:89]
	v_mfma_f32_16x16x32_bf16 v[82:85], v[200:203], v[230:233], v[82:85]
	v_mfma_f32_16x16x32_bf16 v[70:73], v[192:195], v[238:241], v[70:73]
	v_mfma_f32_16x16x32_bf16 v[66:69], v[200:203], v[238:241], v[66:69]
	s_setprio 0
	s_barrier
; #define PG8_STAGE(bufoff, gbase, voff) do { _Pragma("unroll") for (int _i = 0; _i < 2; ++_i) \
;         __builtin_amdgcn_global_load_lds((const unsigned*)((const char*)(gbase) + (voff)[_i]), (LAS unsigned*)(lds + (bufoff) + ldsw + _i * 8192), 16, 0, 0); } while (0)
; #define PG8_LDA(dst, b, h) do { _Pragma("unroll") for (int m = 0; m < 4; ++m) _Pragma("unroll") for (int k = 0; k < 2; ++k) dst[m][k] = *(const LAS bf16x8*)(lds + PG8_SA(b, h) + aoff + m * 2048 + k * 1024); } while (0)
; #define PG8_MMA(ai, bj, At, Bt) do { __builtin_amdgcn_s_setprio(1); _Pragma("unroll") for (int m = 0; m < 4; ++m) _Pragma("unroll") for (int n = 0; n < 2; ++n) _Pragma("unroll") for (int k = 0; k < 2; ++k) \
;         acc[ai][bj][m][n] = __builtin_amdgcn_mfma_f32_16x16x32_bf16(Bt[n][k], At[m][k], acc[ai][bj][m][n], 0, 0, 0); __builtin_amdgcn_s_setprio(0); } while (0)
; #define PG8_WAIT_V(n) asm volatile("s_waitcnt vmcnt(" #n ")" ::: "memory")
; #define PG8_WAIT_L(n) asm volatile("s_waitcnt lgkmcnt(" #n ")" ::: "memory")
; #define PG8_BAR __builtin_amdgcn_s_barrier()
; #define PG8_SCHED __builtin_amdgcn_sched_barrier(0)
; template <class Epi>
; __device__ __forceinline__ void gemm_phase(LAS unsigned char* lds, const int tid, const Gemm g, const StaticOrder& S, const Epi& E) {
;     ...
;             PG8_LDA(At, 1, 1); PG8_STAGE(PG8_SB(1, 0), b3, voffB); PG8_STAGE(PG8_SB(1, 1), b3 + hstepB, voffB); PG8_STAGE(PG8_SA(1, 0), a3, voffA);
;             PG8_WAIT_V(8); PG8_WAIT_L(0); PG8_BAR; PG8_MMA(1, 0, At, B0); PG8_MMA(1, 1, At, B1); PG8_BAR; PG8_SCHED;
;         }
;         if (wr == 0) PG8_BAR;
	s_add_i32 s0, s0, s28
	v_lshl_add_u64 v[162:163], v[162:163], 0, s[36:37]
	s_mov_b32 m0, s0
	ds_read_b128 v[210:213], v191 offset:49152
	ds_read_b128 v[214:217], v191 offset:50176
	ds_read_b128 v[218:221], v191 offset:51200
	ds_read_b128 v[222:225], v191 offset:52224
	ds_read_b128 v[226:229], v191 offset:53248
	ds_read_b128 v[230:233], v191 offset:54272
	ds_read_b128 v[234:237], v191 offset:55296
	ds_read_b128 v[238:241], v191 offset:56320
	global_load_lds_dwordx4 v[162:163], off
	s_add_i32 m0, s0, 0x2000
	s_add_u32 s2, s30, 0x40080
	v_lshl_add_u64 v[162:163], v[164:165], 0, s[36:37]
	s_addc_u32 s3, s31, 0
	s_add_i32 s0, s1, s28
	global_load_lds_dwordx4 v[162:163], off
	v_lshl_add_u64 v[162:163], s[2:3], 0, v[0:1]
	s_mov_b32 m0, s0
	s_nop 0
	global_load_lds_dwordx4 v[162:163], off
	v_lshl_add_u64 v[162:163], s[2:3], 0, v[148:149]
	s_add_i32 m0, s0, 0x2000
	s_nop 0
	global_load_lds_dwordx4 v[162:163], off
	v_lshl_add_u64 v[162:163], v[170:171], 0, s[36:37]
	s_mov_b32 m0, s75
	s_nop 0
	global_load_lds_dwordx4 v[162:163], off
	v_lshl_add_u64 v[162:163], v[206:207], 0, s[36:37]
	s_mov_b32 m0, s76
	s_nop 0
	global_load_lds_dwordx4 v[162:163], off
	s_waitcnt vmcnt(8)
	s_waitcnt lgkmcnt(0)
	s_barrier
	s_setprio 1
	s_waitcnt lgkmcnt(0)
	v_mfma_f32_16x16x32_bf16 v[62:65], v[130:133], v[210:213], v[62:65]
	v_mfma_f32_16x16x32_bf16 v[58:61], v[138:141], v[210:213], v[58:61]
	v_mfma_f32_16x16x32_bf16 v[46:49], v[130:133], v[218:221], v[46:49]
	v_mfma_f32_16x16x32_bf16 v[42:45], v[138:141], v[218:221], v[42:45]
	v_mfma_f32_16x16x32_bf16 v[30:33], v[130:133], v[226:229], v[30:33]
	v_mfma_f32_16x16x32_bf16 v[26:29], v[138:141], v[226:229], v[26:29]
	v_mfma_f32_16x16x32_bf16 v[14:17], v[130:133], v[234:237], v[14:17]
	v_mfma_f32_16x16x32_bf16 v[10:13], v[138:141], v[234:237], v[10:13]
	v_mfma_f32_16x16x32_bf16 v[62:65], v[134:137], v[214:217], v[62:65]
	v_mfma_f32_16x16x32_bf16 v[58:61], v[142:145], v[214:217], v[58:61]
	v_mfma_f32_16x16x32_bf16 v[46:49], v[134:137], v[222:225], v[46:49]
	v_mfma_f32_16x16x32_bf16 v[42:45], v[142:145], v[222:225], v[42:45]
	v_mfma_f32_16x16x32_bf16 v[30:33], v[134:137], v[230:233], v[30:33]
	v_mfma_f32_16x16x32_bf16 v[26:29], v[142:145], v[230:233], v[26:29]
	v_mfma_f32_16x16x32_bf16 v[14:17], v[134:137], v[238:241], v[14:17]
	v_mfma_f32_16x16x32_bf16 v[10:13], v[142:145], v[238:241], v[10:13]
	v_mfma_f32_16x16x32_bf16 v[54:57], v[158:161], v[210:213], v[54:57]
	v_mfma_f32_16x16x32_bf16 v[50:53], v[196:199], v[210:213], v[50:53]
	v_mfma_f32_16x16x32_bf16 v[38:41], v[158:161], v[218:221], v[38:41]
	v_mfma_f32_16x16x32_bf16 v[34:37], v[196:199], v[218:221], v[34:37]
	v_mfma_f32_16x16x32_bf16 v[22:25], v[158:161], v[226:229], v[22:25]
	v_mfma_f32_16x16x32_bf16 v[18:21], v[196:199], v[226:229], v[18:21]
	v_mfma_f32_16x16x32_bf16 v[6:9], v[158:161], v[234:237], v[6:9]
	v_mfma_f32_16x16x32_bf16 v[2:5], v[196:199], v[234:237], v[2:5]
	v_mfma_f32_16x16x32_bf16 v[54:57], v[192:195], v[214:217], v[54:57]
	v_mfma_f32_16x16x32_bf16 v[50:53], v[200:203], v[214:217], v[50:53]
	v_mfma_f32_16x16x32_bf16 v[38:41], v[192:195], v[222:225], v[38:41]
	v_mfma_f32_16x16x32_bf16 v[34:37], v[200:203], v[222:225], v[34:37]
	v_mfma_f32_16x16x32_bf16 v[22:25], v[192:195], v[230:233], v[22:25]
	v_mfma_f32_16x16x32_bf16 v[18:21], v[200:203], v[230:233], v[18:21]
	v_mfma_f32_16x16x32_bf16 v[6:9], v[192:195], v[238:241], v[6:9]
	v_mfma_f32_16x16x32_bf16 v[2:5], v[200:203], v[238:241], v[2:5]
	s_setprio 0
	s_barrier
	s_add_i32 vcc_lo, vcc_lo, 2
	s_add_u32 s66, s66, 0x100
	s_addc_u32 s67, s67, 0
	s_add_u32 s92, s92, 0x100
	s_addc_u32 s93, s93, 0
	s_cmp_gt_u32 vcc_lo, 13
	s_cbranch_scc0 .LBB0_1333
	s_and_b64 vcc, exec, s[6:7]
	s_cbranch_vccz .LBB0_1336
	s_barrier

; #define PG8_STAGE(bufoff, gbase, voff) do { _Pragma("unroll") for (int _i = 0; _i < 2; ++_i) \
;         __builtin_amdgcn_global_load_lds((const unsigned*)((const char*)(gbase) + (voff)[_i]), (LAS unsigned*)(lds + (bufoff) + ldsw + _i * 8192), 16, 0, 0); } while (0)
; #define PG8_LDA(dst, b, h) do { _Pragma("unroll") for (int m = 0; m < 4; ++m) _Pragma("unroll") for (int k = 0; k < 2; ++k) dst[m][k] = *(const LAS bf16x8*)(lds + PG8_SA(b, h) + aoff + m * 2048 + k * 1024); } while (0)
; #define PG8_LDB(dst, b, h) do { _Pragma("unroll") for (int n = 0; n < 2; ++n) _Pragma("unroll") for (int k = 0; k < 2; ++k) dst[n][k] = *(const LAS bf16x8*)(lds + PG8_SB(b, h) + boff + n * 2048 + k * 1024); } while (0)
; #define PG8_MMA(ai, bj, At, Bt) do { __builtin_amdgcn_s_setprio(1); _Pragma("unroll") for (int m = 0; m < 4; ++m) _Pragma("unroll") for (int n = 0; n < 2; ++n) _Pragma("unroll") for (int k = 0; k < 2; ++k) \
;         acc[ai][bj][m][n] = __builtin_amdgcn_mfma_f32_16x16x32_bf16(Bt[n][k], At[m][k], acc[ai][bj][m][n], 0, 0, 0); __builtin_amdgcn_s_setprio(0); } while (0)
; #define PG8_WAIT_V(n) asm volatile("s_waitcnt vmcnt(" #n ")" ::: "memory")
; #define PG8_WAIT_L(n) asm volatile("s_waitcnt lgkmcnt(" #n ")" ::: "memory")
; #define PG8_BAR __builtin_amdgcn_s_barrier()
; #define PG8_SCHED __builtin_amdgcn_sched_barrier(0)
; template <class Epi>
; __device__ __forceinline__ void gemm_phase(LAS unsigned char* lds, const int tid, const Gemm g, const StaticOrder& S, const Epi& E) {
;     ...
;             const bool last = (t == nt - 2);
;             const char* a1 = cA + (size_t)(t + 1) * kstep;
;             const char* a2 = last ? nA : cA + (size_t)(t + 2) * kstep; const char* b2 = last ? nB : cB + (size_t)(t + 2) * kstep;
;             const char* a3 = a2 + kstep; const char* b3 = b2 + kstep;
;             PG8_LDB(B0, 0, 0); PG8_LDB(B1, 0, 1); PG8_SCHED; PG8_LDA(At, 0, 0); PG8_STAGE(PG8_SA(1, 1), a1 + hstepA, voffA);
;             PG8_WAIT_V(8); PG8_WAIT_L(0); PG8_BAR; PG8_MMA(0, 0, At, B0); PG8_MMA(0, 1, At, B1); PG8_BAR; PG8_SCHED;
;             PG8_LDA(At, 0, 1); PG8_STAGE(PG8_SB(0, 0), b2, voffB); PG8_STAGE(PG8_SB(0, 1), b2 + hstepB, voffB); PG8_STAGE(PG8_SA(0, 0), a2, voffA);
;             PG8_WAIT_V(8); PG8_WAIT_L(0); PG8_BAR; PG8_MMA(1, 0, At, B0); PG8_MMA(1, 1, At, B1); PG8_BAR; PG8_SCHED;
.LBB0_1487:
	s_add_u32 s27, s68, 0xfffc0080
	s_addc_u32 s30, s69, -1
	s_add_i32 s62, 0, 0x10000
	s_cmp_eq_u32 s26, 12
	s_cselect_b32 vcc_hi, s28, s30
	s_cselect_b32 vcc_lo, s71, s27
	s_cselect_b32 s31, s5, s83
	s_cselect_b32 s30, s73, s75
	s_add_i32 s27, 0, 0x14000
	v_add_u32_e32 v142, s62, v216
	v_add_u32_e32 v158, s27, v216
	ds_read_b128 v[130:133], v142
	ds_read_b128 v[134:137], v142 offset:1024
	ds_read_b128 v[138:141], v142 offset:2048
	ds_read_b128 v[142:145], v142 offset:3072
	ds_read_b128 v[146:149], v158
	ds_read_b128 v[150:153], v158 offset:1024
	ds_read_b128 v[154:157], v158 offset:2048
	ds_read_b128 v[158:161], v158 offset:3072
	v_lshl_add_u64 v[162:163], s[68:69], 0, v[176:177]
	s_add_i32 m0, s1, 0xc000
	ds_read_b128 v[180:183], v218
	ds_read_b128 v[184:187], v218 offset:1024
	ds_read_b128 v[220:223], v218 offset:2048
	ds_read_b128 v[224:227], v218 offset:3072
	ds_read_b128 v[228:231], v218 offset:4096
	ds_read_b128 v[232:235], v218 offset:5120
	ds_read_b128 v[236:239], v218 offset:6144
	ds_read_b128 v[240:243], v218 offset:7168
	global_load_lds_dwordx4 v[162:163], off
	v_lshl_add_u64 v[162:163], s[68:69], 0, v[178:179]
	s_add_i32 m0, s1, 0xe000
	s_nop 0
	global_load_lds_dwordx4 v[162:163], off
	s_waitcnt vmcnt(8)
	s_waitcnt lgkmcnt(0)
	s_barrier
	s_setprio 1
	s_waitcnt lgkmcnt(0)
	v_mfma_f32_16x16x32_bf16 v[126:129], v[130:133], v[180:183], v[126:129]
	v_mfma_f32_16x16x32_bf16 v[122:125], v[138:141], v[180:183], v[122:125]
	v_mfma_f32_16x16x32_bf16 v[110:113], v[130:133], v[220:223], v[110:113]
	v_mfma_f32_16x16x32_bf16 v[106:109], v[138:141], v[220:223], v[106:109]
	v_mfma_f32_16x16x32_bf16 v[94:97], v[130:133], v[228:231], v[94:97]
	v_mfma_f32_16x16x32_bf16 v[90:93], v[138:141], v[228:231], v[90:93]
	v_mfma_f32_16x16x32_bf16 v[78:81], v[130:133], v[236:239], v[78:81]
	v_mfma_f32_16x16x32_bf16 v[74:77], v[138:141], v[236:239], v[74:77]
	v_mfma_f32_16x16x32_bf16 v[126:129], v[134:137], v[184:187], v[126:129]
	v_mfma_f32_16x16x32_bf16 v[122:125], v[142:145], v[184:187], v[122:125]
	v_mfma_f32_16x16x32_bf16 v[110:113], v[134:137], v[224:227], v[110:113]
	v_mfma_f32_16x16x32_bf16 v[106:109], v[142:145], v[224:227], v[106:109]
	v_mfma_f32_16x16x32_bf16 v[94:97], v[134:137], v[232:235], v[94:97]
	v_mfma_f32_16x16x32_bf16 v[90:93], v[142:145], v[232:235], v[90:93]
	v_mfma_f32_16x16x32_bf16 v[78:81], v[134:137], v[240:243], v[78:81]
	v_mfma_f32_16x16x32_bf16 v[74:77], v[142:145], v[240:243], v[74:77]
	v_mfma_f32_16x16x32_bf16 v[118:121], v[146:149], v[180:183], v[118:121]
	v_mfma_f32_16x16x32_bf16 v[114:117], v[154:157], v[180:183], v[114:117]
	v_mfma_f32_16x16x32_bf16 v[102:105], v[146:149], v[220:223], v[102:105]
	v_mfma_f32_16x16x32_bf16 v[98:101], v[154:157], v[220:223], v[98:101]
	v_mfma_f32_16x16x32_bf16 v[86:89], v[146:149], v[228:231], v[86:89]
	v_mfma_f32_16x16x32_bf16 v[82:85], v[154:157], v[228:231], v[82:85]
	v_mfma_f32_16x16x32_bf16 v[70:73], v[146:149], v[236:239], v[70:73]
	v_mfma_f32_16x16x32_bf16 v[66:69], v[154:157], v[236:239], v[66:69]
	v_mfma_f32_16x16x32_bf16 v[118:121], v[150:153], v[184:187], v[118:121]
	v_mfma_f32_16x16x32_bf16 v[114:117], v[158:161], v[184:187], v[114:117]
	v_mfma_f32_16x16x32_bf16 v[102:105], v[150:153], v[224:227], v[102:105]
	v_mfma_f32_16x16x32_bf16 v[98:101], v[158:161], v[224:227], v[98:101]
	v_mfma_f32_16x16x32_bf16 v[86:89], v[150:153], v[232:235], v[86:89]
	v_mfma_f32_16x16x32_bf16 v[82:85], v[158:161], v[232:235], v[82:85]
	v_mfma_f32_16x16x32_bf16 v[70:73], v[150:153], v[240:243], v[70:73]
	v_mfma_f32_16x16x32_bf16 v[66:69], v[158:161], v[240:243], v[66:69]
	s_setprio 0
	s_barrier
	s_add_i32 s62, s62, s0
	v_lshl_add_u64 v[162:163], s[30:31], 0, v[0:1]
	s_mov_b32 m0, s62
	ds_read_b128 v[180:183], v218 offset:16384
	ds_read_b128 v[184:187], v218 offset:17408
	ds_read_b128 v[220:223], v218 offset:18432
	ds_read_b128 v[224:227], v218 offset:19456
	ds_read_b128 v[228:231], v218 offset:20480
	ds_read_b128 v[232:235], v218 offset:21504
	ds_read_b128 v[236:239], v218 offset:22528
	ds_read_b128 v[240:243], v218 offset:23552
	global_load_lds_dwordx4 v[162:163], off
	s_add_i32 m0, s62, 0x2000
	s_add_u32 s62, s30, 0x40000
	v_lshl_add_u64 v[164:165], s[30:31], 0, v[170:171]
	s_addc_u32 s63, s31, 0
	s_add_i32 s27, s27, s0
	global_load_lds_dwordx4 v[164:165], off
	v_lshl_add_u64 v[206:207], s[62:63], 0, v[0:1]
	s_mov_b32 m0, s27
	v_lshl_add_u64 v[244:245], vcc, 0, v[174:175]
	global_load_lds_dwordx4 v[206:207], off
	v_lshl_add_u64 v[206:207], s[62:63], 0, v[170:171]
	s_add_i32 m0, s27, 0x2000
	s_nop 0
	global_load_lds_dwordx4 v[206:207], off
	v_lshl_add_u64 v[206:207], vcc, 0, v[172:173]
	s_mov_b32 m0, s1
	s_nop 0
	global_load_lds_dwordx4 v[206:207], off
	s_mov_b32 m0, s2
	s_nop 0
	global_load_lds_dwordx4 v[244:245], off
	s_waitcnt vmcnt(8)
	s_waitcnt lgkmcnt(0)
	s_barrier
; #define PG8_STAGE(bufoff, gbase, voff) do { _Pragma("unroll") for (int _i = 0; _i < 2; ++_i) \
;         __builtin_amdgcn_global_load_lds((const unsigned*)((const char*)(gbase) + (voff)[_i]), (LAS unsigned*)(lds + (bufoff) + ldsw + _i * 8192), 16, 0, 0); } while (0)
; #define PG8_LDA(dst, b, h) do { _Pragma("unroll") for (int m = 0; m < 4; ++m) _Pragma("unroll") for (int k = 0; k < 2; ++k) dst[m][k] = *(const LAS bf16x8*)(lds + PG8_SA(b, h) + aoff + m * 2048 + k * 1024); } while (0)
; #define PG8_LDB(dst, b, h) do { _Pragma("unroll") for (int n = 0; n < 2; ++n) _Pragma("unroll") for (int k = 0; k < 2; ++k) dst[n][k] = *(const LAS bf16x8*)(lds + PG8_SB(b, h) + boff + n * 2048 + k * 1024); } while (0)
; #define PG8_MMA(ai, bj, At, Bt) do { __builtin_amdgcn_s_setprio(1); _Pragma("unroll") for (int m = 0; m < 4; ++m) _Pragma("unroll") for (int n = 0; n < 2; ++n) _Pragma("unroll") for (int k = 0; k < 2; ++k) \
;         acc[ai][bj][m][n] = __builtin_amdgcn_mfma_f32_16x16x32_bf16(Bt[n][k], At[m][k], acc[ai][bj][m][n], 0, 0, 0); __builtin_amdgcn_s_setprio(0); } while (0)
; #define PG8_WAIT_V(n) asm volatile("s_waitcnt vmcnt(" #n ")" ::: "memory")
; #define PG8_WAIT_L(n) asm volatile("s_waitcnt lgkmcnt(" #n ")" ::: "memory")
; #define PG8_BAR __builtin_amdgcn_s_barrier()
; #define PG8_SCHED __builtin_amdgcn_sched_barrier(0)
; template <class Epi>
; __device__ __forceinline__ void gemm_phase(LAS unsigned char* lds, const int tid, const Gemm g, const StaticOrder& S, const Epi& E) {
;     ...
;             PG8_WAIT_V(8); PG8_WAIT_L(0); PG8_BAR; PG8_MMA(1, 0, At, B0); PG8_MMA(1, 1, At, B1); PG8_BAR; PG8_SCHED;
;             PG8_LDB(B0, 1, 0); PG8_LDB(B1, 1, 1); PG8_SCHED; PG8_LDA(At, 1, 0); PG8_STAGE(PG8_SA(0, 1), a2 + hstepA, voffA);
;             PG8_WAIT_V(8); PG8_WAIT_L(0); PG8_BAR; PG8_MMA(0, 0, At, B0); PG8_MMA(0, 1, At, B1); PG8_BAR; PG8_SCHED;
	s_setprio 1
	s_waitcnt lgkmcnt(0)
	v_mfma_f32_16x16x32_bf16 v[62:65], v[130:133], v[180:183], v[62:65]
	v_mfma_f32_16x16x32_bf16 v[58:61], v[138:141], v[180:183], v[58:61]
	v_mfma_f32_16x16x32_bf16 v[46:49], v[130:133], v[220:223], v[46:49]
	v_mfma_f32_16x16x32_bf16 v[42:45], v[138:141], v[220:223], v[42:45]
	v_mfma_f32_16x16x32_bf16 v[30:33], v[130:133], v[228:231], v[30:33]
	v_mfma_f32_16x16x32_bf16 v[26:29], v[138:141], v[228:231], v[26:29]
	v_mfma_f32_16x16x32_bf16 v[14:17], v[130:133], v[236:239], v[14:17]
	v_mfma_f32_16x16x32_bf16 v[10:13], v[138:141], v[236:239], v[10:13]
	v_mfma_f32_16x16x32_bf16 v[62:65], v[134:137], v[184:187], v[62:65]
	v_mfma_f32_16x16x32_bf16 v[58:61], v[142:145], v[184:187], v[58:61]
	v_mfma_f32_16x16x32_bf16 v[46:49], v[134:137], v[224:227], v[46:49]
	v_mfma_f32_16x16x32_bf16 v[42:45], v[142:145], v[224:227], v[42:45]
	v_mfma_f32_16x16x32_bf16 v[30:33], v[134:137], v[232:235], v[30:33]
	v_mfma_f32_16x16x32_bf16 v[26:29], v[142:145], v[232:235], v[26:29]
	v_mfma_f32_16x16x32_bf16 v[14:17], v[134:137], v[240:243], v[14:17]
	v_mfma_f32_16x16x32_bf16 v[10:13], v[142:145], v[240:243], v[10:13]
	v_mfma_f32_16x16x32_bf16 v[54:57], v[146:149], v[180:183], v[54:57]
	v_mfma_f32_16x16x32_bf16 v[50:53], v[154:157], v[180:183], v[50:53]
	v_mfma_f32_16x16x32_bf16 v[38:41], v[146:149], v[220:223], v[38:41]
	v_mfma_f32_16x16x32_bf16 v[34:37], v[154:157], v[220:223], v[34:37]
	v_mfma_f32_16x16x32_bf16 v[22:25], v[146:149], v[228:231], v[22:25]
	v_mfma_f32_16x16x32_bf16 v[18:21], v[154:157], v[228:231], v[18:21]
	v_mfma_f32_16x16x32_bf16 v[6:9], v[146:149], v[236:239], v[6:9]
	v_mfma_f32_16x16x32_bf16 v[2:5], v[154:157], v[236:239], v[2:5]
	v_mfma_f32_16x16x32_bf16 v[54:57], v[150:153], v[184:187], v[54:57]
	v_mfma_f32_16x16x32_bf16 v[50:53], v[158:161], v[184:187], v[50:53]
	v_mfma_f32_16x16x32_bf16 v[38:41], v[150:153], v[224:227], v[38:41]
	v_mfma_f32_16x16x32_bf16 v[34:37], v[158:161], v[224:227], v[34:37]
	v_mfma_f32_16x16x32_bf16 v[22:25], v[150:153], v[232:235], v[22:25]
	v_mfma_f32_16x16x32_bf16 v[18:21], v[158:161], v[232:235], v[18:21]
	v_mfma_f32_16x16x32_bf16 v[6:9], v[150:153], v[240:243], v[6:9]
	v_mfma_f32_16x16x32_bf16 v[2:5], v[158:161], v[240:243], v[2:5]
	s_setprio 0
	s_barrier
	s_add_i32 s27, 0, 0x18000
	s_add_i32 s17, 0, 0x1c000
	v_add_u32_e32 v142, s27, v216
	v_add_u32_e32 v158, s17, v216
	ds_read_b128 v[130:133], v142
	ds_read_b128 v[134:137], v142 offset:1024
	ds_read_b128 v[138:141], v142 offset:2048
	ds_read_b128 v[142:145], v142 offset:3072
	ds_read_b128 v[146:149], v158
	ds_read_b128 v[150:153], v158 offset:1024
	ds_read_b128 v[154:157], v158 offset:2048
	ds_read_b128 v[158:161], v158 offset:3072
	s_add_u32 s62, vcc_lo, 0x40000
	s_addc_u32 s63, vcc_hi, 0
	s_mov_b32 m0, s3
	v_lshl_add_u64 v[246:247], s[62:63], 0, v[172:173]
	ds_read_b128 v[180:183], v218 offset:32768
	ds_read_b128 v[184:187], v218 offset:33792
	ds_read_b128 v[220:223], v218 offset:34816
	ds_read_b128 v[224:227], v218 offset:35840
	ds_read_b128 v[228:231], v218 offset:36864
	ds_read_b128 v[232:235], v218 offset:37888
	ds_read_b128 v[236:239], v218 offset:38912
	ds_read_b128 v[240:243], v218 offset:39936
	global_load_lds_dwordx4 v[246:247], off
	v_lshl_add_u64 v[246:247], s[62:63], 0, v[174:175]
	s_mov_b32 m0, s16
	s_nop 0
	global_load_lds_dwordx4 v[246:247], off
	s_waitcnt vmcnt(8)
	s_waitcnt lgkmcnt(0)
	s_barrier
	s_setprio 1
	s_waitcnt lgkmcnt(0)
	v_mfma_f32_16x16x32_bf16 v[126:129], v[130:133], v[180:183], v[126:129]
	v_mfma_f32_16x16x32_bf16 v[122:125], v[138:141], v[180:183], v[122:125]
	v_mfma_f32_16x16x32_bf16 v[110:113], v[130:133], v[220:223], v[110:113]
	v_mfma_f32_16x16x32_bf16 v[106:109], v[138:141], v[220:223], v[106:109]
	v_mfma_f32_16x16x32_bf16 v[94:97], v[130:133], v[228:231], v[94:97]
	v_mfma_f32_16x16x32_bf16 v[90:93], v[138:141], v[228:231], v[90:93]
	v_mfma_f32_16x16x32_bf16 v[78:81], v[130:133], v[236:239], v[78:81]
	v_mfma_f32_16x16x32_bf16 v[74:77], v[138:141], v[236:239], v[74:77]
	v_mfma_f32_16x16x32_bf16 v[126:129], v[134:137], v[184:187], v[126:129]
	v_mfma_f32_16x16x32_bf16 v[122:125], v[142:145], v[184:187], v[122:125]
	v_mfma_f32_16x16x32_bf16 v[110:113], v[134:137], v[224:227], v[110:113]
	v_mfma_f32_16x16x32_bf16 v[106:109], v[142:145], v[224:227], v[106:109]
	v_mfma_f32_16x16x32_bf16 v[94:97], v[134:137], v[232:235], v[94:97]
	v_mfma_f32_16x16x32_bf16 v[90:93], v[142:145], v[232:235], v[90:93]
	v_mfma_f32_16x16x32_bf16 v[78:81], v[134:137], v[240:243], v[78:81]
	v_mfma_f32_16x16x32_bf16 v[74:77], v[142:145], v[240:243], v[74:77]
	v_mfma_f32_16x16x32_bf16 v[118:121], v[146:149], v[180:183], v[118:121]
	v_mfma_f32_16x16x32_bf16 v[114:117], v[154:157], v[180:183], v[114:117]
	v_mfma_f32_16x16x32_bf16 v[102:105], v[146:149], v[220:223], v[102:105]
	v_mfma_f32_16x16x32_bf16 v[98:101], v[154:157], v[220:223], v[98:101]
	v_mfma_f32_16x16x32_bf16 v[86:89], v[146:149], v[228:231], v[86:89]
	v_mfma_f32_16x16x32_bf16 v[82:85], v[154:157], v[228:231], v[82:85]
	v_mfma_f32_16x16x32_bf16 v[70:73], v[146:149], v[236:239], v[70:73]
	v_mfma_f32_16x16x32_bf16 v[66:69], v[154:157], v[236:239], v[66:69]
	v_mfma_f32_16x16x32_bf16 v[118:121], v[150:153], v[184:187], v[118:121]
	v_mfma_f32_16x16x32_bf16 v[114:117], v[158:161], v[184:187], v[114:117]
	v_mfma_f32_16x16x32_bf16 v[102:105], v[150:153], v[224:227], v[102:105]
	v_mfma_f32_16x16x32_bf16 v[98:101], v[158:161], v[224:227], v[98:101]
	v_mfma_f32_16x16x32_bf16 v[86:89], v[150:153], v[232:235], v[86:89]
	v_mfma_f32_16x16x32_bf16 v[82:85], v[158:161], v[232:235], v[82:85]
	v_mfma_f32_16x16x32_bf16 v[70:73], v[150:153], v[240:243], v[70:73]
	v_mfma_f32_16x16x32_bf16 v[66:69], v[158:161], v[240:243], v[66:69]
	s_setprio 0
	s_barrier
; #define PG8_STAGE(bufoff, gbase, voff) do { _Pragma("unroll") for (int _i = 0; _i < 2; ++_i) \
;         __builtin_amdgcn_global_load_lds((const unsigned*)((const char*)(gbase) + (voff)[_i]), (LAS unsigned*)(lds + (bufoff) + ldsw + _i * 8192), 16, 0, 0); } while (0)
; #define PG8_LDA(dst, b, h) do { _Pragma("unroll") for (int m = 0; m < 4; ++m) _Pragma("unroll") for (int k = 0; k < 2; ++k) dst[m][k] = *(const LAS bf16x8*)(lds + PG8_SA(b, h) + aoff + m * 2048 + k * 1024); } while (0)
; #define PG8_MMA(ai, bj, At, Bt) do { __builtin_amdgcn_s_setprio(1); _Pragma("unroll") for (int m = 0; m < 4; ++m) _Pragma("unroll") for (int n = 0; n < 2; ++n) _Pragma("unroll") for (int k = 0; k < 2; ++k) \
;         acc[ai][bj][m][n] = __builtin_amdgcn_mfma_f32_16x16x32_bf16(Bt[n][k], At[m][k], acc[ai][bj][m][n], 0, 0, 0); __builtin_amdgcn_s_setprio(0); } while (0)
; #define PG8_WAIT_V(n) asm volatile("s_waitcnt vmcnt(" #n ")" ::: "memory")
; #define PG8_WAIT_L(n) asm volatile("s_waitcnt lgkmcnt(" #n ")" ::: "memory")
; #define PG8_BAR __builtin_amdgcn_s_barrier()
; #define PG8_SCHED __builtin_amdgcn_sched_barrier(0)
; template <class Epi>
; __device__ __forceinline__ void gemm_phase(LAS unsigned char* lds, const int tid, const Gemm g, const StaticOrder& S, const Epi& E) {
;     ...
;             PG8_LDA(At, 1, 1); PG8_STAGE(PG8_SB(1, 0), b3, voffB); PG8_STAGE(PG8_SB(1, 1), b3 + hstepB, voffB); PG8_STAGE(PG8_SA(1, 0), a3, voffA);
;             PG8_WAIT_V(8); PG8_WAIT_L(0); PG8_BAR; PG8_MMA(1, 0, At, B0); PG8_MMA(1, 1, At, B1); PG8_BAR; PG8_SCHED;
;         }
;         if (wr == 0) PG8_BAR;
	s_add_i32 s27, s27, s0
	v_lshl_add_u64 v[162:163], v[162:163], 0, s[36:37]
	s_mov_b32 m0, s27
	ds_read_b128 v[180:183], v218 offset:49152
	ds_read_b128 v[184:187], v218 offset:50176
	ds_read_b128 v[220:223], v218 offset:51200
	ds_read_b128 v[224:227], v218 offset:52224
	ds_read_b128 v[228:231], v218 offset:53248
	ds_read_b128 v[232:235], v218 offset:54272
	ds_read_b128 v[236:239], v218 offset:55296
	ds_read_b128 v[240:243], v218 offset:56320
	global_load_lds_dwordx4 v[162:163], off
	s_add_i32 m0, s27, 0x2000
	s_add_u32 s30, s30, 0x40080
	v_lshl_add_u64 v[162:163], v[164:165], 0, s[36:37]
	s_addc_u32 s31, s31, 0
	s_add_i32 s17, s17, s0
	global_load_lds_dwordx4 v[162:163], off
	v_lshl_add_u64 v[162:163], s[30:31], 0, v[0:1]
	s_mov_b32 m0, s17
	s_nop 0
	global_load_lds_dwordx4 v[162:163], off
	v_lshl_add_u64 v[162:163], s[30:31], 0, v[170:171]
	s_add_i32 m0, s17, 0x2000
	s_nop 0
	global_load_lds_dwordx4 v[162:163], off
	v_lshl_add_u64 v[162:163], v[206:207], 0, s[36:37]
	s_mov_b32 m0, s10
	s_nop 0
	global_load_lds_dwordx4 v[162:163], off
	v_lshl_add_u64 v[162:163], v[244:245], 0, s[36:37]
	s_mov_b32 m0, s11
	s_nop 0
	global_load_lds_dwordx4 v[162:163], off
	s_waitcnt vmcnt(8)
	s_waitcnt lgkmcnt(0)
	s_barrier
	s_setprio 1
	s_waitcnt lgkmcnt(0)
	v_mfma_f32_16x16x32_bf16 v[62:65], v[130:133], v[180:183], v[62:65]
	v_mfma_f32_16x16x32_bf16 v[58:61], v[138:141], v[180:183], v[58:61]
	v_mfma_f32_16x16x32_bf16 v[46:49], v[130:133], v[220:223], v[46:49]
	v_mfma_f32_16x16x32_bf16 v[42:45], v[138:141], v[220:223], v[42:45]
	v_mfma_f32_16x16x32_bf16 v[30:33], v[130:133], v[228:231], v[30:33]
	v_mfma_f32_16x16x32_bf16 v[26:29], v[138:141], v[228:231], v[26:29]
	v_mfma_f32_16x16x32_bf16 v[14:17], v[130:133], v[236:239], v[14:17]
	v_mfma_f32_16x16x32_bf16 v[10:13], v[138:141], v[236:239], v[10:13]
	v_mfma_f32_16x16x32_bf16 v[62:65], v[134:137], v[184:187], v[62:65]
	v_mfma_f32_16x16x32_bf16 v[58:61], v[142:145], v[184:187], v[58:61]
	v_mfma_f32_16x16x32_bf16 v[46:49], v[134:137], v[224:227], v[46:49]
	v_mfma_f32_16x16x32_bf16 v[42:45], v[142:145], v[224:227], v[42:45]
	v_mfma_f32_16x16x32_bf16 v[30:33], v[134:137], v[232:235], v[30:33]
	v_mfma_f32_16x16x32_bf16 v[26:29], v[142:145], v[232:235], v[26:29]
	v_mfma_f32_16x16x32_bf16 v[14:17], v[134:137], v[240:243], v[14:17]
	v_mfma_f32_16x16x32_bf16 v[10:13], v[142:145], v[240:243], v[10:13]
	v_mfma_f32_16x16x32_bf16 v[54:57], v[146:149], v[180:183], v[54:57]
	v_mfma_f32_16x16x32_bf16 v[50:53], v[154:157], v[180:183], v[50:53]
	v_mfma_f32_16x16x32_bf16 v[38:41], v[146:149], v[220:223], v[38:41]
	v_mfma_f32_16x16x32_bf16 v[34:37], v[154:157], v[220:223], v[34:37]
	v_mfma_f32_16x16x32_bf16 v[22:25], v[146:149], v[228:231], v[22:25]
	v_mfma_f32_16x16x32_bf16 v[18:21], v[154:157], v[228:231], v[18:21]
	v_mfma_f32_16x16x32_bf16 v[6:9], v[146:149], v[236:239], v[6:9]
	v_mfma_f32_16x16x32_bf16 v[2:5], v[154:157], v[236:239], v[2:5]
	v_mfma_f32_16x16x32_bf16 v[54:57], v[150:153], v[184:187], v[54:57]
	v_mfma_f32_16x16x32_bf16 v[50:53], v[158:161], v[184:187], v[50:53]
	v_mfma_f32_16x16x32_bf16 v[38:41], v[150:153], v[224:227], v[38:41]
	v_mfma_f32_16x16x32_bf16 v[34:37], v[158:161], v[224:227], v[34:37]
	v_mfma_f32_16x16x32_bf16 v[22:25], v[150:153], v[232:235], v[22:25]
	v_mfma_f32_16x16x32_bf16 v[18:21], v[158:161], v[232:235], v[18:21]
	v_mfma_f32_16x16x32_bf16 v[6:9], v[150:153], v[240:243], v[6:9]
	v_mfma_f32_16x16x32_bf16 v[2:5], v[158:161], v[240:243], v[2:5]
	s_setprio 0
	s_barrier
	s_add_i32 s26, s26, 2
	s_add_u32 s68, s68, 0x100
	s_addc_u32 s69, s69, 0
	s_add_u32 s75, s75, 0x100
	s_addc_u32 s83, s83, 0
	s_cmp_gt_u32 s26, 13
	s_cbranch_scc0 .LBB0_1487
	v_readlane_b32 s26, v255, 55
	v_readlane_b32 s27, v255, 56
	s_and_b64 vcc, exec, s[26:27]
	s_cbranch_vccz .LBB0_1490
	s_barrier

; #define PG8_STAGE(bufoff, gbase, voff) do { _Pragma("unroll") for (int _i = 0; _i < 2; ++_i) \
;         __builtin_amdgcn_global_load_lds((const unsigned*)((const char*)(gbase) + (voff)[_i]), (LAS unsigned*)(lds + (bufoff) + ldsw + _i * 8192), 16, 0, 0); } while (0)
; #define PG8_LDA(dst, b, h) do { _Pragma("unroll") for (int m = 0; m < 4; ++m) _Pragma("unroll") for (int k = 0; k < 2; ++k) dst[m][k] = *(const LAS bf16x8*)(lds + PG8_SA(b, h) + aoff + m * 2048 + k * 1024); } while (0)
; #define PG8_LDB(dst, b, h) do { _Pragma("unroll") for (int n = 0; n < 2; ++n) _Pragma("unroll") for (int k = 0; k < 2; ++k) dst[n][k] = *(const LAS bf16x8*)(lds + PG8_SB(b, h) + boff + n * 2048 + k * 1024); } while (0)
; #define PG8_MMA(ai, bj, At, Bt) do { __builtin_amdgcn_s_setprio(1); _Pragma("unroll") for (int m = 0; m < 4; ++m) _Pragma("unroll") for (int n = 0; n < 2; ++n) _Pragma("unroll") for (int k = 0; k < 2; ++k) \
;         acc[ai][bj][m][n] = __builtin_amdgcn_mfma_f32_16x16x32_bf16(Bt[n][k], At[m][k], acc[ai][bj][m][n], 0, 0, 0); __builtin_amdgcn_s_setprio(0); } while (0)
; #define PG8_WAIT_V(n) asm volatile("s_waitcnt vmcnt(" #n ")" ::: "memory")
; #define PG8_WAIT_L(n) asm volatile("s_waitcnt lgkmcnt(" #n ")" ::: "memory")
; #define PG8_BAR __builtin_amdgcn_s_barrier()
; #define PG8_SCHED __builtin_amdgcn_sched_barrier(0)
; template <class Epi>
; __device__ __forceinline__ void gemm_phase(LAS unsigned char* lds, const int tid, const Gemm g, const StaticOrder& S, const Epi& E) {
;     ...
;             const bool last = (t == nt - 2);
;             const char* a1 = cA + (size_t)(t + 1) * kstep;
;             const char* a2 = last ? nA : cA + (size_t)(t + 2) * kstep; const char* b2 = last ? nB : cB + (size_t)(t + 2) * kstep;
;             const char* a3 = a2 + kstep; const char* b3 = b2 + kstep;
;             PG8_LDB(B0, 0, 0); PG8_LDB(B1, 0, 1); PG8_SCHED; PG8_LDA(At, 0, 0); PG8_STAGE(PG8_SA(1, 1), a1 + hstepA, voffA);
;             PG8_WAIT_V(8); PG8_WAIT_L(0); PG8_BAR; PG8_MMA(0, 0, At, B0); PG8_MMA(0, 1, At, B1); PG8_BAR; PG8_SCHED;
;             PG8_LDA(At, 0, 1); PG8_STAGE(PG8_SB(0, 0), b2, voffB); PG8_STAGE(PG8_SB(0, 1), b2 + hstepB, voffB); PG8_STAGE(PG8_SA(0, 0), a2, voffA);
;             PG8_WAIT_V(8); PG8_WAIT_L(0); PG8_BAR; PG8_MMA(1, 0, At, B0); PG8_MMA(1, 1, At, B1); PG8_BAR; PG8_SCHED;
.LBB0_1912:
	s_add_u32 s30, s82, 0xfffc0080
	s_addc_u32 s31, s83, -1
	s_add_i32 s92, 0, 0x10000
	s_cmp_eq_u32 s17, 12
	s_cselect_b32 s89, s7, s31
	s_cselect_b32 s88, s65, s30
	s_cselect_b32 s31, s5, s27
	s_cselect_b32 s30, vcc_lo, vcc_hi
	s_add_i32 s11, 0, 0x14000
	v_add_u32_e32 v110, s92, v158
	v_add_u32_e32 v162, s11, v158
	ds_read_b128 v[98:101], v110
	ds_read_b128 v[102:105], v110 offset:1024
	ds_read_b128 v[106:109], v110 offset:2048
	ds_read_b128 v[110:113], v110 offset:3072
	ds_read_b128 v[174:177], v162
	ds_read_b128 v[178:181], v162 offset:1024
	ds_read_b128 v[182:185], v162 offset:2048
	ds_read_b128 v[186:189], v162 offset:3072
	v_lshl_add_u64 v[162:163], s[82:83], 0, v[152:153]
	s_add_i32 m0, s66, 0xc000
	ds_read_b128 v[190:193], v172
	ds_read_b128 v[194:197], v172 offset:1024
	ds_read_b128 v[198:201], v172 offset:2048
	ds_read_b128 v[210:213], v172 offset:3072
	ds_read_b128 v[214:217], v172 offset:4096
	ds_read_b128 v[218:221], v172 offset:5120
	ds_read_b128 v[222:225], v172 offset:6144
	ds_read_b128 v[226:229], v172 offset:7168
	global_load_lds_dwordx4 v[162:163], off
	v_lshl_add_u64 v[162:163], s[82:83], 0, v[154:155]
	s_add_i32 m0, s66, 0xe000
	s_nop 0
	global_load_lds_dwordx4 v[162:163], off
	s_waitcnt vmcnt(8)
	s_waitcnt lgkmcnt(0)
	s_barrier
	s_setprio 1
	s_waitcnt lgkmcnt(0)
	v_mfma_f32_16x16x32_bf16 v[142:145], v[98:101], v[190:193], v[142:145]
	v_mfma_f32_16x16x32_bf16 v[138:141], v[106:109], v[190:193], v[138:141]
	v_mfma_f32_16x16x32_bf16 v[134:137], v[98:101], v[198:201], v[134:137]
	v_mfma_f32_16x16x32_bf16 v[130:133], v[106:109], v[198:201], v[130:133]
	v_mfma_f32_16x16x32_bf16 v[94:97], v[98:101], v[214:217], v[94:97]
	v_mfma_f32_16x16x32_bf16 v[90:93], v[106:109], v[214:217], v[90:93]
	v_mfma_f32_16x16x32_bf16 v[78:81], v[98:101], v[222:225], v[78:81]
	v_mfma_f32_16x16x32_bf16 v[74:77], v[106:109], v[222:225], v[74:77]
	v_mfma_f32_16x16x32_bf16 v[142:145], v[102:105], v[194:197], v[142:145]
	v_mfma_f32_16x16x32_bf16 v[138:141], v[110:113], v[194:197], v[138:141]
	v_mfma_f32_16x16x32_bf16 v[134:137], v[102:105], v[210:213], v[134:137]
	v_mfma_f32_16x16x32_bf16 v[130:133], v[110:113], v[210:213], v[130:133]
	v_mfma_f32_16x16x32_bf16 v[94:97], v[102:105], v[218:221], v[94:97]
	v_mfma_f32_16x16x32_bf16 v[90:93], v[110:113], v[218:221], v[90:93]
	v_mfma_f32_16x16x32_bf16 v[78:81], v[102:105], v[226:229], v[78:81]
	v_mfma_f32_16x16x32_bf16 v[74:77], v[110:113], v[226:229], v[74:77]
	v_mfma_f32_16x16x32_bf16 v[126:129], v[174:177], v[190:193], v[126:129]
	v_mfma_f32_16x16x32_bf16 v[122:125], v[182:185], v[190:193], v[122:125]
	v_mfma_f32_16x16x32_bf16 v[118:121], v[174:177], v[198:201], v[118:121]
	v_mfma_f32_16x16x32_bf16 v[114:117], v[182:185], v[198:201], v[114:117]
	v_mfma_f32_16x16x32_bf16 v[86:89], v[174:177], v[214:217], v[86:89]
	v_mfma_f32_16x16x32_bf16 v[82:85], v[182:185], v[214:217], v[82:85]
	v_mfma_f32_16x16x32_bf16 v[70:73], v[174:177], v[222:225], v[70:73]
	v_mfma_f32_16x16x32_bf16 v[66:69], v[182:185], v[222:225], v[66:69]
	v_mfma_f32_16x16x32_bf16 v[126:129], v[178:181], v[194:197], v[126:129]
	v_mfma_f32_16x16x32_bf16 v[122:125], v[186:189], v[194:197], v[122:125]
	v_mfma_f32_16x16x32_bf16 v[118:121], v[178:181], v[210:213], v[118:121]
	v_mfma_f32_16x16x32_bf16 v[114:117], v[186:189], v[210:213], v[114:117]
	v_mfma_f32_16x16x32_bf16 v[86:89], v[178:181], v[218:221], v[86:89]
	v_mfma_f32_16x16x32_bf16 v[82:85], v[186:189], v[218:221], v[82:85]
	v_mfma_f32_16x16x32_bf16 v[70:73], v[178:181], v[226:229], v[70:73]
	v_mfma_f32_16x16x32_bf16 v[66:69], v[186:189], v[226:229], v[66:69]
	s_setprio 0
	s_barrier
	s_add_i32 s92, s92, s28
	v_lshl_add_u64 v[162:163], s[30:31], 0, v[0:1]
	s_mov_b32 m0, s92
	ds_read_b128 v[190:193], v172 offset:16384
	ds_read_b128 v[194:197], v172 offset:17408
	ds_read_b128 v[198:201], v172 offset:18432
	ds_read_b128 v[210:213], v172 offset:19456
	ds_read_b128 v[214:217], v172 offset:20480
	ds_read_b128 v[218:221], v172 offset:21504
	ds_read_b128 v[222:225], v172 offset:22528
	ds_read_b128 v[226:229], v172 offset:23552
	global_load_lds_dwordx4 v[162:163], off
	s_add_i32 m0, s92, 0x2000
	s_add_u32 s92, s30, 0x40000
	v_lshl_add_u64 v[164:165], s[30:31], 0, v[146:147]
	s_addc_u32 s93, s31, 0
	s_add_i32 s11, s11, s28
	global_load_lds_dwordx4 v[164:165], off
	v_lshl_add_u64 v[202:203], s[92:93], 0, v[0:1]
	s_mov_b32 m0, s11
	v_lshl_add_u64 v[206:207], s[88:89], 0, v[148:149]
	global_load_lds_dwordx4 v[202:203], off
	v_lshl_add_u64 v[202:203], s[92:93], 0, v[146:147]
	s_add_i32 m0, s11, 0x2000
	s_nop 0
	global_load_lds_dwordx4 v[202:203], off
	v_lshl_add_u64 v[202:203], s[88:89], 0, v[150:151]
	s_mov_b32 m0, s66
	s_nop 0
	global_load_lds_dwordx4 v[202:203], off
	s_mov_b32 m0, s67
	s_nop 0
	global_load_lds_dwordx4 v[206:207], off
	s_waitcnt vmcnt(8)
	s_waitcnt lgkmcnt(0)
	s_barrier
; #define PG8_STAGE(bufoff, gbase, voff) do { _Pragma("unroll") for (int _i = 0; _i < 2; ++_i) \
;         __builtin_amdgcn_global_load_lds((const unsigned*)((const char*)(gbase) + (voff)[_i]), (LAS unsigned*)(lds + (bufoff) + ldsw + _i * 8192), 16, 0, 0); } while (0)
; #define PG8_LDA(dst, b, h) do { _Pragma("unroll") for (int m = 0; m < 4; ++m) _Pragma("unroll") for (int k = 0; k < 2; ++k) dst[m][k] = *(const LAS bf16x8*)(lds + PG8_SA(b, h) + aoff + m * 2048 + k * 1024); } while (0)
; #define PG8_LDB(dst, b, h) do { _Pragma("unroll") for (int n = 0; n < 2; ++n) _Pragma("unroll") for (int k = 0; k < 2; ++k) dst[n][k] = *(const LAS bf16x8*)(lds + PG8_SB(b, h) + boff + n * 2048 + k * 1024); } while (0)
; #define PG8_MMA(ai, bj, At, Bt) do { __builtin_amdgcn_s_setprio(1); _Pragma("unroll") for (int m = 0; m < 4; ++m) _Pragma("unroll") for (int n = 0; n < 2; ++n) _Pragma("unroll") for (int k = 0; k < 2; ++k) \
;         acc[ai][bj][m][n] = __builtin_amdgcn_mfma_f32_16x16x32_bf16(Bt[n][k], At[m][k], acc[ai][bj][m][n], 0, 0, 0); __builtin_amdgcn_s_setprio(0); } while (0)
; #define PG8_WAIT_V(n) asm volatile("s_waitcnt vmcnt(" #n ")" ::: "memory")
; #define PG8_WAIT_L(n) asm volatile("s_waitcnt lgkmcnt(" #n ")" ::: "memory")
; #define PG8_BAR __builtin_amdgcn_s_barrier()
; #define PG8_SCHED __builtin_amdgcn_sched_barrier(0)
; template <class Epi>
; __device__ __forceinline__ void gemm_phase(LAS unsigned char* lds, const int tid, const Gemm g, const StaticOrder& S, const Epi& E) {
;     ...
;             PG8_WAIT_V(8); PG8_WAIT_L(0); PG8_BAR; PG8_MMA(1, 0, At, B0); PG8_MMA(1, 1, At, B1); PG8_BAR; PG8_SCHED;
;             PG8_LDB(B0, 1, 0); PG8_LDB(B1, 1, 1); PG8_SCHED; PG8_LDA(At, 1, 0); PG8_STAGE(PG8_SA(0, 1), a2 + hstepA, voffA);
;             PG8_WAIT_V(8); PG8_WAIT_L(0); PG8_BAR; PG8_MMA(0, 0, At, B0); PG8_MMA(0, 1, At, B1); PG8_BAR; PG8_SCHED;
	s_setprio 1
	s_waitcnt lgkmcnt(0)
	v_mfma_f32_16x16x32_bf16 v[62:65], v[98:101], v[190:193], v[62:65]
	v_mfma_f32_16x16x32_bf16 v[58:61], v[106:109], v[190:193], v[58:61]
	v_mfma_f32_16x16x32_bf16 v[54:57], v[98:101], v[198:201], v[54:57]
	v_mfma_f32_16x16x32_bf16 v[46:49], v[106:109], v[198:201], v[46:49]
	v_mfma_f32_16x16x32_bf16 v[30:33], v[98:101], v[214:217], v[30:33]
	v_mfma_f32_16x16x32_bf16 v[26:29], v[106:109], v[214:217], v[26:29]
	v_mfma_f32_16x16x32_bf16 v[22:25], v[98:101], v[222:225], v[22:25]
	v_mfma_f32_16x16x32_bf16 v[14:17], v[106:109], v[222:225], v[14:17]
	v_mfma_f32_16x16x32_bf16 v[62:65], v[102:105], v[194:197], v[62:65]
	v_mfma_f32_16x16x32_bf16 v[58:61], v[110:113], v[194:197], v[58:61]
	v_mfma_f32_16x16x32_bf16 v[54:57], v[102:105], v[210:213], v[54:57]
	v_mfma_f32_16x16x32_bf16 v[46:49], v[110:113], v[210:213], v[46:49]
	v_mfma_f32_16x16x32_bf16 v[30:33], v[102:105], v[218:221], v[30:33]
	v_mfma_f32_16x16x32_bf16 v[26:29], v[110:113], v[218:221], v[26:29]
	v_mfma_f32_16x16x32_bf16 v[22:25], v[102:105], v[226:229], v[22:25]
	v_mfma_f32_16x16x32_bf16 v[14:17], v[110:113], v[226:229], v[14:17]
	v_mfma_f32_16x16x32_bf16 v[50:53], v[174:177], v[190:193], v[50:53]
	v_mfma_f32_16x16x32_bf16 v[42:45], v[182:185], v[190:193], v[42:45]
	v_mfma_f32_16x16x32_bf16 v[38:41], v[174:177], v[198:201], v[38:41]
	v_mfma_f32_16x16x32_bf16 v[34:37], v[182:185], v[198:201], v[34:37]
	v_mfma_f32_16x16x32_bf16 v[18:21], v[174:177], v[214:217], v[18:21]
	v_mfma_f32_16x16x32_bf16 v[10:13], v[182:185], v[214:217], v[10:13]
	v_mfma_f32_16x16x32_bf16 v[6:9], v[174:177], v[222:225], v[6:9]
	v_mfma_f32_16x16x32_bf16 v[2:5], v[182:185], v[222:225], v[2:5]
	v_mfma_f32_16x16x32_bf16 v[50:53], v[178:181], v[194:197], v[50:53]
	v_mfma_f32_16x16x32_bf16 v[42:45], v[186:189], v[194:197], v[42:45]
	v_mfma_f32_16x16x32_bf16 v[38:41], v[178:181], v[210:213], v[38:41]
	v_mfma_f32_16x16x32_bf16 v[34:37], v[186:189], v[210:213], v[34:37]
	v_mfma_f32_16x16x32_bf16 v[18:21], v[178:181], v[218:221], v[18:21]
	v_mfma_f32_16x16x32_bf16 v[10:13], v[186:189], v[218:221], v[10:13]
	v_mfma_f32_16x16x32_bf16 v[6:9], v[178:181], v[226:229], v[6:9]
	v_mfma_f32_16x16x32_bf16 v[2:5], v[186:189], v[226:229], v[2:5]
	s_setprio 0
	s_barrier
	s_add_i32 s11, 0, 0x18000
	s_add_i32 s92, 0, 0x1c000
	v_add_u32_e32 v110, s11, v158
	v_add_u32_e32 v173, s92, v158
	ds_read_b128 v[98:101], v110
	ds_read_b128 v[102:105], v110 offset:1024
	ds_read_b128 v[106:109], v110 offset:2048
	ds_read_b128 v[110:113], v110 offset:3072
	ds_read_b128 v[174:177], v173
	ds_read_b128 v[178:181], v173 offset:1024
	ds_read_b128 v[182:185], v173 offset:2048
	ds_read_b128 v[186:189], v173 offset:3072
	s_add_u32 s88, s88, 0x40000
	s_addc_u32 s89, s89, 0
	s_mov_b32 m0, s70
	v_lshl_add_u64 v[230:231], s[88:89], 0, v[150:151]
	ds_read_b128 v[190:193], v172 offset:32768
	ds_read_b128 v[194:197], v172 offset:33792
	ds_read_b128 v[198:201], v172 offset:34816
	ds_read_b128 v[210:213], v172 offset:35840
	ds_read_b128 v[214:217], v172 offset:36864
	ds_read_b128 v[218:221], v172 offset:37888
	ds_read_b128 v[222:225], v172 offset:38912
	ds_read_b128 v[226:229], v172 offset:39936
	global_load_lds_dwordx4 v[230:231], off
	v_lshl_add_u64 v[230:231], s[88:89], 0, v[148:149]
	s_mov_b32 m0, s71
	s_nop 0
	global_load_lds_dwordx4 v[230:231], off
	s_waitcnt vmcnt(8)
	s_waitcnt lgkmcnt(0)
	s_barrier
	s_setprio 1
	s_waitcnt lgkmcnt(0)
	v_mfma_f32_16x16x32_bf16 v[142:145], v[98:101], v[190:193], v[142:145]
	v_mfma_f32_16x16x32_bf16 v[138:141], v[106:109], v[190:193], v[138:141]
	v_mfma_f32_16x16x32_bf16 v[134:137], v[98:101], v[198:201], v[134:137]
	v_mfma_f32_16x16x32_bf16 v[130:133], v[106:109], v[198:201], v[130:133]
	v_mfma_f32_16x16x32_bf16 v[94:97], v[98:101], v[214:217], v[94:97]
	v_mfma_f32_16x16x32_bf16 v[90:93], v[106:109], v[214:217], v[90:93]
	v_mfma_f32_16x16x32_bf16 v[78:81], v[98:101], v[222:225], v[78:81]
	v_mfma_f32_16x16x32_bf16 v[74:77], v[106:109], v[222:225], v[74:77]
	v_mfma_f32_16x16x32_bf16 v[142:145], v[102:105], v[194:197], v[142:145]
	v_mfma_f32_16x16x32_bf16 v[138:141], v[110:113], v[194:197], v[138:141]
	v_mfma_f32_16x16x32_bf16 v[134:137], v[102:105], v[210:213], v[134:137]
	v_mfma_f32_16x16x32_bf16 v[130:133], v[110:113], v[210:213], v[130:133]
	v_mfma_f32_16x16x32_bf16 v[94:97], v[102:105], v[218:221], v[94:97]
	v_mfma_f32_16x16x32_bf16 v[90:93], v[110:113], v[218:221], v[90:93]
	v_mfma_f32_16x16x32_bf16 v[78:81], v[102:105], v[226:229], v[78:81]
	v_mfma_f32_16x16x32_bf16 v[74:77], v[110:113], v[226:229], v[74:77]
	v_mfma_f32_16x16x32_bf16 v[126:129], v[174:177], v[190:193], v[126:129]
	v_mfma_f32_16x16x32_bf16 v[122:125], v[182:185], v[190:193], v[122:125]
	v_mfma_f32_16x16x32_bf16 v[118:121], v[174:177], v[198:201], v[118:121]
	v_mfma_f32_16x16x32_bf16 v[114:117], v[182:185], v[198:201], v[114:117]
	v_mfma_f32_16x16x32_bf16 v[86:89], v[174:177], v[214:217], v[86:89]
	v_mfma_f32_16x16x32_bf16 v[82:85], v[182:185], v[214:217], v[82:85]
	v_mfma_f32_16x16x32_bf16 v[70:73], v[174:177], v[222:225], v[70:73]
	v_mfma_f32_16x16x32_bf16 v[66:69], v[182:185], v[222:225], v[66:69]
	v_mfma_f32_16x16x32_bf16 v[126:129], v[178:181], v[194:197], v[126:129]
	v_mfma_f32_16x16x32_bf16 v[122:125], v[186:189], v[194:197], v[122:125]
	v_mfma_f32_16x16x32_bf16 v[118:121], v[178:181], v[210:213], v[118:121]
	v_mfma_f32_16x16x32_bf16 v[114:117], v[186:189], v[210:213], v[114:117]
	v_mfma_f32_16x16x32_bf16 v[86:89], v[178:181], v[218:221], v[86:89]
	v_mfma_f32_16x16x32_bf16 v[82:85], v[186:189], v[218:221], v[82:85]
	v_mfma_f32_16x16x32_bf16 v[70:73], v[178:181], v[226:229], v[70:73]
	v_mfma_f32_16x16x32_bf16 v[66:69], v[186:189], v[226:229], v[66:69]
	s_setprio 0
	s_barrier
; #define PG8_STAGE(bufoff, gbase, voff) do { _Pragma("unroll") for (int _i = 0; _i < 2; ++_i) \
;         __builtin_amdgcn_global_load_lds((const unsigned*)((const char*)(gbase) + (voff)[_i]), (LAS unsigned*)(lds + (bufoff) + ldsw + _i * 8192), 16, 0, 0); } while (0)
; #define PG8_LDA(dst, b, h) do { _Pragma("unroll") for (int m = 0; m < 4; ++m) _Pragma("unroll") for (int k = 0; k < 2; ++k) dst[m][k] = *(const LAS bf16x8*)(lds + PG8_SA(b, h) + aoff + m * 2048 + k * 1024); } while (0)
; #define PG8_MMA(ai, bj, At, Bt) do { __builtin_amdgcn_s_setprio(1); _Pragma("unroll") for (int m = 0; m < 4; ++m) _Pragma("unroll") for (int n = 0; n < 2; ++n) _Pragma("unroll") for (int k = 0; k < 2; ++k) \
;         acc[ai][bj][m][n] = __builtin_amdgcn_mfma_f32_16x16x32_bf16(Bt[n][k], At[m][k], acc[ai][bj][m][n], 0, 0, 0); __builtin_amdgcn_s_setprio(0); } while (0)
; #define PG8_WAIT_V(n) asm volatile("s_waitcnt vmcnt(" #n ")" ::: "memory")
; #define PG8_WAIT_L(n) asm volatile("s_waitcnt lgkmcnt(" #n ")" ::: "memory")
; #define PG8_BAR __builtin_amdgcn_s_barrier()
; #define PG8_SCHED __builtin_amdgcn_sched_barrier(0)
; template <class Epi>
; __device__ __forceinline__ void gemm_phase(LAS unsigned char* lds, const int tid, const Gemm g, const StaticOrder& S, const Epi& E) {
;     ...
;             PG8_LDA(At, 1, 1); PG8_STAGE(PG8_SB(1, 0), b3, voffB); PG8_STAGE(PG8_SB(1, 1), b3 + hstepB, voffB); PG8_STAGE(PG8_SA(1, 0), a3, voffA);
;             PG8_WAIT_V(8); PG8_WAIT_L(0); PG8_BAR; PG8_MMA(1, 0, At, B0); PG8_MMA(1, 1, At, B1); PG8_BAR; PG8_SCHED;
;         }
;         if (wr == 0) PG8_BAR;
	s_add_i32 s11, s11, s28
	v_lshl_add_u64 v[162:163], v[162:163], 0, s[36:37]
	s_mov_b32 m0, s11
	ds_read_b128 v[190:193], v172 offset:49152
	ds_read_b128 v[194:197], v172 offset:50176
	ds_read_b128 v[198:201], v172 offset:51200
	ds_read_b128 v[210:213], v172 offset:52224
	ds_read_b128 v[214:217], v172 offset:53248
	ds_read_b128 v[218:221], v172 offset:54272
	ds_read_b128 v[222:225], v172 offset:55296
	ds_read_b128 v[226:229], v172 offset:56320
	global_load_lds_dwordx4 v[162:163], off
	s_add_i32 m0, s11, 0x2000
	s_add_u32 s30, s30, 0x40080
	v_lshl_add_u64 v[162:163], v[164:165], 0, s[36:37]
	s_addc_u32 s31, s31, 0
	s_add_i32 s11, s92, s28
	global_load_lds_dwordx4 v[162:163], off
	v_lshl_add_u64 v[162:163], s[30:31], 0, v[0:1]
	s_mov_b32 m0, s11
	s_nop 0
	global_load_lds_dwordx4 v[162:163], off
	v_lshl_add_u64 v[162:163], s[30:31], 0, v[146:147]
	s_add_i32 m0, s11, 0x2000
	s_nop 0
	global_load_lds_dwordx4 v[162:163], off
	v_lshl_add_u64 v[162:163], v[202:203], 0, s[36:37]
	s_mov_b32 m0, s72
	s_nop 0
	global_load_lds_dwordx4 v[162:163], off
	v_lshl_add_u64 v[162:163], v[206:207], 0, s[36:37]
	s_mov_b32 m0, s73
	s_nop 0
	global_load_lds_dwordx4 v[162:163], off
	s_waitcnt vmcnt(8)
	s_waitcnt lgkmcnt(0)
	s_barrier
	s_setprio 1
	s_waitcnt lgkmcnt(0)
	v_mfma_f32_16x16x32_bf16 v[62:65], v[98:101], v[190:193], v[62:65]
	v_mfma_f32_16x16x32_bf16 v[58:61], v[106:109], v[190:193], v[58:61]
	v_mfma_f32_16x16x32_bf16 v[54:57], v[98:101], v[198:201], v[54:57]
	v_mfma_f32_16x16x32_bf16 v[46:49], v[106:109], v[198:201], v[46:49]
	v_mfma_f32_16x16x32_bf16 v[30:33], v[98:101], v[214:217], v[30:33]
	v_mfma_f32_16x16x32_bf16 v[26:29], v[106:109], v[214:217], v[26:29]
	v_mfma_f32_16x16x32_bf16 v[22:25], v[98:101], v[222:225], v[22:25]
	v_mfma_f32_16x16x32_bf16 v[14:17], v[106:109], v[222:225], v[14:17]
	v_mfma_f32_16x16x32_bf16 v[62:65], v[102:105], v[194:197], v[62:65]
	v_mfma_f32_16x16x32_bf16 v[58:61], v[110:113], v[194:197], v[58:61]
	v_mfma_f32_16x16x32_bf16 v[54:57], v[102:105], v[210:213], v[54:57]
	v_mfma_f32_16x16x32_bf16 v[46:49], v[110:113], v[210:213], v[46:49]
	v_mfma_f32_16x16x32_bf16 v[30:33], v[102:105], v[218:221], v[30:33]
	v_mfma_f32_16x16x32_bf16 v[26:29], v[110:113], v[218:221], v[26:29]
	v_mfma_f32_16x16x32_bf16 v[22:25], v[102:105], v[226:229], v[22:25]
	v_mfma_f32_16x16x32_bf16 v[14:17], v[110:113], v[226:229], v[14:17]
	v_mfma_f32_16x16x32_bf16 v[50:53], v[174:177], v[190:193], v[50:53]
	v_mfma_f32_16x16x32_bf16 v[42:45], v[182:185], v[190:193], v[42:45]
	v_mfma_f32_16x16x32_bf16 v[38:41], v[174:177], v[198:201], v[38:41]
	v_mfma_f32_16x16x32_bf16 v[34:37], v[182:185], v[198:201], v[34:37]
	v_mfma_f32_16x16x32_bf16 v[18:21], v[174:177], v[214:217], v[18:21]
	v_mfma_f32_16x16x32_bf16 v[10:13], v[182:185], v[214:217], v[10:13]
	v_mfma_f32_16x16x32_bf16 v[6:9], v[174:177], v[222:225], v[6:9]
	v_mfma_f32_16x16x32_bf16 v[2:5], v[182:185], v[222:225], v[2:5]
	v_mfma_f32_16x16x32_bf16 v[50:53], v[178:181], v[194:197], v[50:53]
	v_mfma_f32_16x16x32_bf16 v[42:45], v[186:189], v[194:197], v[42:45]
	v_mfma_f32_16x16x32_bf16 v[38:41], v[178:181], v[210:213], v[38:41]
	v_mfma_f32_16x16x32_bf16 v[34:37], v[186:189], v[210:213], v[34:37]
	v_mfma_f32_16x16x32_bf16 v[18:21], v[178:181], v[218:221], v[18:21]
	v_mfma_f32_16x16x32_bf16 v[10:13], v[186:189], v[218:221], v[10:13]
	v_mfma_f32_16x16x32_bf16 v[6:9], v[178:181], v[226:229], v[6:9]
	v_mfma_f32_16x16x32_bf16 v[2:5], v[186:189], v[226:229], v[2:5]
	s_setprio 0
	s_barrier
	s_add_i32 s17, s17, 2
	s_add_u32 s82, s82, 0x100
	s_addc_u32 s83, s83, 0
	s_add_u32 vcc_hi, vcc_hi, 0x100
	s_addc_u32 s27, s27, 0
	s_cmp_gt_u32 s17, 13
	s_cbranch_scc0 .LBB0_1912
	s_and_b64 vcc, exec, s[2:3]
	s_cbranch_vccz .LBB0_1915
	s_barrier

; #define PG8_STAGE(bufoff, gbase, voff) do { _Pragma("unroll") for (int _i = 0; _i < 2; ++_i) \
;         __builtin_amdgcn_global_load_lds((const unsigned*)((const char*)(gbase) + (voff)[_i]), (LAS unsigned*)(lds + (bufoff) + ldsw + _i * 8192), 16, 0, 0); } while (0)
; #define PG8_LDA(dst, b, h) do { _Pragma("unroll") for (int m = 0; m < 4; ++m) _Pragma("unroll") for (int k = 0; k < 2; ++k) dst[m][k] = *(const LAS bf16x8*)(lds + PG8_SA(b, h) + aoff + m * 2048 + k * 1024); } while (0)
; #define PG8_LDB(dst, b, h) do { _Pragma("unroll") for (int n = 0; n < 2; ++n) _Pragma("unroll") for (int k = 0; k < 2; ++k) dst[n][k] = *(const LAS bf16x8*)(lds + PG8_SB(b, h) + boff + n * 2048 + k * 1024); } while (0)
; #define PG8_MMA(ai, bj, At, Bt) do { __builtin_amdgcn_s_setprio(1); _Pragma("unroll") for (int m = 0; m < 4; ++m) _Pragma("unroll") for (int n = 0; n < 2; ++n) _Pragma("unroll") for (int k = 0; k < 2; ++k) \
;         acc[ai][bj][m][n] = __builtin_amdgcn_mfma_f32_16x16x32_bf16(Bt[n][k], At[m][k], acc[ai][bj][m][n], 0, 0, 0); __builtin_amdgcn_s_setprio(0); } while (0)
; #define PG8_WAIT_V(n) asm volatile("s_waitcnt vmcnt(" #n ")" ::: "memory")
; #define PG8_WAIT_L(n) asm volatile("s_waitcnt lgkmcnt(" #n ")" ::: "memory")
; #define PG8_BAR __builtin_amdgcn_s_barrier()
; #define PG8_SCHED __builtin_amdgcn_sched_barrier(0)
; template <class Epi>
; __device__ __forceinline__ void gemm_phase(LAS unsigned char* lds, const int tid, const Gemm g, const StaticOrder& S, const Epi& E) {
;     ...
;             const bool last = (t == nt - 2);
;             const char* a1 = cA + (size_t)(t + 1) * kstep;
;             const char* a2 = last ? nA : cA + (size_t)(t + 2) * kstep; const char* b2 = last ? nB : cB + (size_t)(t + 2) * kstep;
;             const char* a3 = a2 + kstep; const char* b3 = b2 + kstep;
;             PG8_LDB(B0, 0, 0); PG8_LDB(B1, 0, 1); PG8_SCHED; PG8_LDA(At, 0, 0); PG8_STAGE(PG8_SA(1, 1), a1 + hstepA, voffA);
;             PG8_WAIT_V(8); PG8_WAIT_L(0); PG8_BAR; PG8_MMA(0, 0, At, B0); PG8_MMA(0, 1, At, B1); PG8_BAR; PG8_SCHED;
;             PG8_LDA(At, 0, 1); PG8_STAGE(PG8_SB(0, 0), b2, voffB); PG8_STAGE(PG8_SB(0, 1), b2 + hstepB, voffB); PG8_STAGE(PG8_SA(0, 0), a2, voffA);
;             PG8_WAIT_V(8); PG8_WAIT_L(0); PG8_BAR; PG8_MMA(1, 0, At, B0); PG8_MMA(1, 1, At, B1); PG8_BAR; PG8_SCHED;
.LBB0_2193:
	s_add_u32 s70, s30, 0x100
	s_addc_u32 s71, s31, 0
	s_add_i32 s76, 0, 0x10000
	s_cmp_eq_u32 vcc_hi, 40
	s_cselect_b32 s75, s1, s71
	s_cselect_b32 s74, s0, s70
	s_cselect_b32 s73, s69, vcc_lo
	s_cselect_b32 s72, s68, s28
	s_add_i32 s2, 0, 0x14000
	v_add_u32_e32 v154, s76, v179
	v_add_u32_e32 v162, s2, v179
	ds_read_b128 v[130:133], v154
	ds_read_b128 v[134:137], v154 offset:1024
	ds_read_b128 v[138:141], v154 offset:2048
	ds_read_b128 v[154:157], v154 offset:3072
	ds_read_b128 v[158:161], v162
	ds_read_b128 v[170:173], v162 offset:1024
	ds_read_b128 v[174:177], v162 offset:2048
	ds_read_b128 v[184:187], v162 offset:3072
	v_lshl_add_u64 v[162:163], s[30:31], 0, v[150:151]
	s_add_i32 m0, s5, 0xc000
	ds_read_b128 v[188:191], v181
	ds_read_b128 v[192:195], v181 offset:1024
	ds_read_b128 v[196:199], v181 offset:2048
	ds_read_b128 v[200:203], v181 offset:3072
	ds_read_b128 v[212:215], v181 offset:4096
	ds_read_b128 v[216:219], v181 offset:5120
	ds_read_b128 v[220:223], v181 offset:6144
	ds_read_b128 v[224:227], v181 offset:7168
	global_load_lds_dwordx4 v[162:163], off
	v_lshl_add_u64 v[162:163], s[30:31], 0, v[152:153]
	s_add_i32 m0, s5, 0xe000
	s_nop 0
	global_load_lds_dwordx4 v[162:163], off
	s_waitcnt vmcnt(8)
	s_waitcnt lgkmcnt(0)
	s_barrier
	s_setprio 1
	s_waitcnt lgkmcnt(0)
	v_mfma_f32_16x16x32_bf16 v[126:129], v[130:133], v[188:191], v[126:129]
	v_mfma_f32_16x16x32_bf16 v[122:125], v[138:141], v[188:191], v[122:125]
	v_mfma_f32_16x16x32_bf16 v[110:113], v[130:133], v[196:199], v[110:113]
	v_mfma_f32_16x16x32_bf16 v[106:109], v[138:141], v[196:199], v[106:109]
	v_mfma_f32_16x16x32_bf16 v[94:97], v[130:133], v[212:215], v[94:97]
	v_mfma_f32_16x16x32_bf16 v[90:93], v[138:141], v[212:215], v[90:93]
	v_mfma_f32_16x16x32_bf16 v[78:81], v[130:133], v[220:223], v[78:81]
	v_mfma_f32_16x16x32_bf16 v[74:77], v[138:141], v[220:223], v[74:77]
	v_mfma_f32_16x16x32_bf16 v[126:129], v[134:137], v[192:195], v[126:129]
	v_mfma_f32_16x16x32_bf16 v[122:125], v[154:157], v[192:195], v[122:125]
	v_mfma_f32_16x16x32_bf16 v[110:113], v[134:137], v[200:203], v[110:113]
	v_mfma_f32_16x16x32_bf16 v[106:109], v[154:157], v[200:203], v[106:109]
	v_mfma_f32_16x16x32_bf16 v[94:97], v[134:137], v[216:219], v[94:97]
	v_mfma_f32_16x16x32_bf16 v[90:93], v[154:157], v[216:219], v[90:93]
	v_mfma_f32_16x16x32_bf16 v[78:81], v[134:137], v[224:227], v[78:81]
	v_mfma_f32_16x16x32_bf16 v[74:77], v[154:157], v[224:227], v[74:77]
	v_mfma_f32_16x16x32_bf16 v[118:121], v[158:161], v[188:191], v[118:121]
	v_mfma_f32_16x16x32_bf16 v[114:117], v[174:177], v[188:191], v[114:117]
	v_mfma_f32_16x16x32_bf16 v[102:105], v[158:161], v[196:199], v[102:105]
	v_mfma_f32_16x16x32_bf16 v[98:101], v[174:177], v[196:199], v[98:101]
	v_mfma_f32_16x16x32_bf16 v[86:89], v[158:161], v[212:215], v[86:89]
	v_mfma_f32_16x16x32_bf16 v[82:85], v[174:177], v[212:215], v[82:85]
	v_mfma_f32_16x16x32_bf16 v[70:73], v[158:161], v[220:223], v[70:73]
	v_mfma_f32_16x16x32_bf16 v[66:69], v[174:177], v[220:223], v[66:69]
	v_mfma_f32_16x16x32_bf16 v[118:121], v[170:173], v[192:195], v[118:121]
	v_mfma_f32_16x16x32_bf16 v[114:117], v[184:187], v[192:195], v[114:117]
	v_mfma_f32_16x16x32_bf16 v[102:105], v[170:173], v[200:203], v[102:105]
	v_mfma_f32_16x16x32_bf16 v[98:101], v[184:187], v[200:203], v[98:101]
	v_mfma_f32_16x16x32_bf16 v[86:89], v[170:173], v[216:219], v[86:89]
	v_mfma_f32_16x16x32_bf16 v[82:85], v[184:187], v[216:219], v[82:85]
	v_mfma_f32_16x16x32_bf16 v[70:73], v[170:173], v[224:227], v[70:73]
	v_mfma_f32_16x16x32_bf16 v[66:69], v[184:187], v[224:227], v[66:69]
	s_setprio 0
	s_barrier
	s_add_i32 s3, s76, s4
	v_lshl_add_u64 v[162:163], s[72:73], 0, v[0:1]
	s_mov_b32 m0, s3
	ds_read_b128 v[188:191], v181 offset:16384
	ds_read_b128 v[192:195], v181 offset:17408
	ds_read_b128 v[196:199], v181 offset:18432
	ds_read_b128 v[200:203], v181 offset:19456
	ds_read_b128 v[212:215], v181 offset:20480
	ds_read_b128 v[216:219], v181 offset:21504
	ds_read_b128 v[220:223], v181 offset:22528
	ds_read_b128 v[224:227], v181 offset:23552
	global_load_lds_dwordx4 v[162:163], off
	s_add_i32 m0, s3, 0x2000
	s_add_u32 s30, s72, 0xb0000
	v_lshl_add_u64 v[164:165], s[72:73], 0, v[148:149]
	s_addc_u32 s31, s73, 0
	s_add_i32 s2, s2, s4
	global_load_lds_dwordx4 v[164:165], off
	v_lshl_add_u64 v[206:207], s[30:31], 0, v[0:1]
	s_mov_b32 m0, s2
	v_lshl_add_u64 v[228:229], s[74:75], 0, v[144:145]
	global_load_lds_dwordx4 v[206:207], off
	v_lshl_add_u64 v[206:207], s[30:31], 0, v[148:149]
	s_add_i32 m0, s2, 0x2000
	s_nop 0
	global_load_lds_dwordx4 v[206:207], off
	v_lshl_add_u64 v[206:207], s[74:75], 0, v[142:143]
	s_mov_b32 m0, s5
	s_nop 0
	global_load_lds_dwordx4 v[206:207], off
	s_mov_b32 m0, s6
	s_nop 0
	global_load_lds_dwordx4 v[228:229], off
	s_waitcnt vmcnt(8)
	s_waitcnt lgkmcnt(0)
	s_barrier
; #define PG8_STAGE(bufoff, gbase, voff) do { _Pragma("unroll") for (int _i = 0; _i < 2; ++_i) \
;         __builtin_amdgcn_global_load_lds((const unsigned*)((const char*)(gbase) + (voff)[_i]), (LAS unsigned*)(lds + (bufoff) + ldsw + _i * 8192), 16, 0, 0); } while (0)
; #define PG8_LDA(dst, b, h) do { _Pragma("unroll") for (int m = 0; m < 4; ++m) _Pragma("unroll") for (int k = 0; k < 2; ++k) dst[m][k] = *(const LAS bf16x8*)(lds + PG8_SA(b, h) + aoff + m * 2048 + k * 1024); } while (0)
; #define PG8_LDB(dst, b, h) do { _Pragma("unroll") for (int n = 0; n < 2; ++n) _Pragma("unroll") for (int k = 0; k < 2; ++k) dst[n][k] = *(const LAS bf16x8*)(lds + PG8_SB(b, h) + boff + n * 2048 + k * 1024); } while (0)
; #define PG8_MMA(ai, bj, At, Bt) do { __builtin_amdgcn_s_setprio(1); _Pragma("unroll") for (int m = 0; m < 4; ++m) _Pragma("unroll") for (int n = 0; n < 2; ++n) _Pragma("unroll") for (int k = 0; k < 2; ++k) \
;         acc[ai][bj][m][n] = __builtin_amdgcn_mfma_f32_16x16x32_bf16(Bt[n][k], At[m][k], acc[ai][bj][m][n], 0, 0, 0); __builtin_amdgcn_s_setprio(0); } while (0)
; #define PG8_WAIT_V(n) asm volatile("s_waitcnt vmcnt(" #n ")" ::: "memory")
; #define PG8_WAIT_L(n) asm volatile("s_waitcnt lgkmcnt(" #n ")" ::: "memory")
; #define PG8_BAR __builtin_amdgcn_s_barrier()
; #define PG8_SCHED __builtin_amdgcn_sched_barrier(0)
; template <class Epi>
; __device__ __forceinline__ void gemm_phase(LAS unsigned char* lds, const int tid, const Gemm g, const StaticOrder& S, const Epi& E) {
;     ...
;             PG8_WAIT_V(8); PG8_WAIT_L(0); PG8_BAR; PG8_MMA(1, 0, At, B0); PG8_MMA(1, 1, At, B1); PG8_BAR; PG8_SCHED;
;             PG8_LDB(B0, 1, 0); PG8_LDB(B1, 1, 1); PG8_SCHED; PG8_LDA(At, 1, 0); PG8_STAGE(PG8_SA(0, 1), a2 + hstepA, voffA);
;             PG8_WAIT_V(8); PG8_WAIT_L(0); PG8_BAR; PG8_MMA(0, 0, At, B0); PG8_MMA(0, 1, At, B1); PG8_BAR; PG8_SCHED;
	s_setprio 1
	s_waitcnt lgkmcnt(0)
	v_mfma_f32_16x16x32_bf16 v[62:65], v[130:133], v[188:191], v[62:65]
	v_mfma_f32_16x16x32_bf16 v[58:61], v[138:141], v[188:191], v[58:61]
	v_mfma_f32_16x16x32_bf16 v[46:49], v[130:133], v[196:199], v[46:49]
	v_mfma_f32_16x16x32_bf16 v[42:45], v[138:141], v[196:199], v[42:45]
	v_mfma_f32_16x16x32_bf16 v[30:33], v[130:133], v[212:215], v[30:33]
	v_mfma_f32_16x16x32_bf16 v[26:29], v[138:141], v[212:215], v[26:29]
	v_mfma_f32_16x16x32_bf16 v[14:17], v[130:133], v[220:223], v[14:17]
	v_mfma_f32_16x16x32_bf16 v[10:13], v[138:141], v[220:223], v[10:13]
	v_mfma_f32_16x16x32_bf16 v[62:65], v[134:137], v[192:195], v[62:65]
	v_mfma_f32_16x16x32_bf16 v[58:61], v[154:157], v[192:195], v[58:61]
	v_mfma_f32_16x16x32_bf16 v[46:49], v[134:137], v[200:203], v[46:49]
	v_mfma_f32_16x16x32_bf16 v[42:45], v[154:157], v[200:203], v[42:45]
	v_mfma_f32_16x16x32_bf16 v[30:33], v[134:137], v[216:219], v[30:33]
	v_mfma_f32_16x16x32_bf16 v[26:29], v[154:157], v[216:219], v[26:29]
	v_mfma_f32_16x16x32_bf16 v[14:17], v[134:137], v[224:227], v[14:17]
	v_mfma_f32_16x16x32_bf16 v[10:13], v[154:157], v[224:227], v[10:13]
	v_mfma_f32_16x16x32_bf16 v[54:57], v[158:161], v[188:191], v[54:57]
	v_mfma_f32_16x16x32_bf16 v[50:53], v[174:177], v[188:191], v[50:53]
	v_mfma_f32_16x16x32_bf16 v[38:41], v[158:161], v[196:199], v[38:41]
	v_mfma_f32_16x16x32_bf16 v[34:37], v[174:177], v[196:199], v[34:37]
	v_mfma_f32_16x16x32_bf16 v[22:25], v[158:161], v[212:215], v[22:25]
	v_mfma_f32_16x16x32_bf16 v[18:21], v[174:177], v[212:215], v[18:21]
	v_mfma_f32_16x16x32_bf16 v[6:9], v[158:161], v[220:223], v[6:9]
	v_mfma_f32_16x16x32_bf16 v[2:5], v[174:177], v[220:223], v[2:5]
	v_mfma_f32_16x16x32_bf16 v[54:57], v[170:173], v[192:195], v[54:57]
	v_mfma_f32_16x16x32_bf16 v[50:53], v[184:187], v[192:195], v[50:53]
	v_mfma_f32_16x16x32_bf16 v[38:41], v[170:173], v[200:203], v[38:41]
	v_mfma_f32_16x16x32_bf16 v[34:37], v[184:187], v[200:203], v[34:37]
	v_mfma_f32_16x16x32_bf16 v[22:25], v[170:173], v[216:219], v[22:25]
	v_mfma_f32_16x16x32_bf16 v[18:21], v[184:187], v[216:219], v[18:21]
	v_mfma_f32_16x16x32_bf16 v[6:9], v[170:173], v[224:227], v[6:9]
	v_mfma_f32_16x16x32_bf16 v[2:5], v[184:187], v[224:227], v[2:5]
	s_setprio 0
	s_barrier
	s_add_i32 s2, 0, 0x18000
	s_add_i32 s3, 0, 0x1c000
	v_add_u32_e32 v154, s2, v179
	v_add_u32_e32 v183, s3, v179
	ds_read_b128 v[130:133], v154
	ds_read_b128 v[134:137], v154 offset:1024
	ds_read_b128 v[138:141], v154 offset:2048
	ds_read_b128 v[154:157], v154 offset:3072
	ds_read_b128 v[158:161], v183
	ds_read_b128 v[170:173], v183 offset:1024
	ds_read_b128 v[174:177], v183 offset:2048
	ds_read_b128 v[184:187], v183 offset:3072
	s_add_u32 s30, s74, 0x160000
	s_addc_u32 s31, s75, 0
	s_mov_b32 m0, s7
	v_lshl_add_u64 v[230:231], s[30:31], 0, v[142:143]
	ds_read_b128 v[188:191], v181 offset:32768
	ds_read_b128 v[192:195], v181 offset:33792
	ds_read_b128 v[196:199], v181 offset:34816
	ds_read_b128 v[200:203], v181 offset:35840
	ds_read_b128 v[212:215], v181 offset:36864
	ds_read_b128 v[216:219], v181 offset:37888
	ds_read_b128 v[220:223], v181 offset:38912
	ds_read_b128 v[224:227], v181 offset:39936
	global_load_lds_dwordx4 v[230:231], off
	v_lshl_add_u64 v[230:231], s[30:31], 0, v[144:145]
	s_mov_b32 m0, s77
	s_nop 0
	global_load_lds_dwordx4 v[230:231], off
	s_waitcnt vmcnt(8)
	s_waitcnt lgkmcnt(0)
	s_barrier
	s_setprio 1
	s_waitcnt lgkmcnt(0)
	v_mfma_f32_16x16x32_bf16 v[126:129], v[130:133], v[188:191], v[126:129]
	v_mfma_f32_16x16x32_bf16 v[122:125], v[138:141], v[188:191], v[122:125]
	v_mfma_f32_16x16x32_bf16 v[110:113], v[130:133], v[196:199], v[110:113]
	v_mfma_f32_16x16x32_bf16 v[106:109], v[138:141], v[196:199], v[106:109]
	v_mfma_f32_16x16x32_bf16 v[94:97], v[130:133], v[212:215], v[94:97]
	v_mfma_f32_16x16x32_bf16 v[90:93], v[138:141], v[212:215], v[90:93]
	v_mfma_f32_16x16x32_bf16 v[78:81], v[130:133], v[220:223], v[78:81]
	v_mfma_f32_16x16x32_bf16 v[74:77], v[138:141], v[220:223], v[74:77]
	v_mfma_f32_16x16x32_bf16 v[126:129], v[134:137], v[192:195], v[126:129]
	v_mfma_f32_16x16x32_bf16 v[122:125], v[154:157], v[192:195], v[122:125]
	v_mfma_f32_16x16x32_bf16 v[110:113], v[134:137], v[200:203], v[110:113]
	v_mfma_f32_16x16x32_bf16 v[106:109], v[154:157], v[200:203], v[106:109]
	v_mfma_f32_16x16x32_bf16 v[94:97], v[134:137], v[216:219], v[94:97]
	v_mfma_f32_16x16x32_bf16 v[90:93], v[154:157], v[216:219], v[90:93]
	v_mfma_f32_16x16x32_bf16 v[78:81], v[134:137], v[224:227], v[78:81]
	v_mfma_f32_16x16x32_bf16 v[74:77], v[154:157], v[224:227], v[74:77]
	v_mfma_f32_16x16x32_bf16 v[118:121], v[158:161], v[188:191], v[118:121]
	v_mfma_f32_16x16x32_bf16 v[114:117], v[174:177], v[188:191], v[114:117]
	v_mfma_f32_16x16x32_bf16 v[102:105], v[158:161], v[196:199], v[102:105]
	v_mfma_f32_16x16x32_bf16 v[98:101], v[174:177], v[196:199], v[98:101]
	v_mfma_f32_16x16x32_bf16 v[86:89], v[158:161], v[212:215], v[86:89]
	v_mfma_f32_16x16x32_bf16 v[82:85], v[174:177], v[212:215], v[82:85]
	v_mfma_f32_16x16x32_bf16 v[70:73], v[158:161], v[220:223], v[70:73]
	v_mfma_f32_16x16x32_bf16 v[66:69], v[174:177], v[220:223], v[66:69]
	v_mfma_f32_16x16x32_bf16 v[118:121], v[170:173], v[192:195], v[118:121]
	v_mfma_f32_16x16x32_bf16 v[114:117], v[184:187], v[192:195], v[114:117]
	v_mfma_f32_16x16x32_bf16 v[102:105], v[170:173], v[200:203], v[102:105]
	v_mfma_f32_16x16x32_bf16 v[98:101], v[184:187], v[200:203], v[98:101]
	v_mfma_f32_16x16x32_bf16 v[86:89], v[170:173], v[216:219], v[86:89]
	v_mfma_f32_16x16x32_bf16 v[82:85], v[184:187], v[216:219], v[82:85]
	v_mfma_f32_16x16x32_bf16 v[70:73], v[170:173], v[224:227], v[70:73]
	v_mfma_f32_16x16x32_bf16 v[66:69], v[184:187], v[224:227], v[66:69]
	s_setprio 0
	s_barrier
; #define PG8_STAGE(bufoff, gbase, voff) do { _Pragma("unroll") for (int _i = 0; _i < 2; ++_i) \
;         __builtin_amdgcn_global_load_lds((const unsigned*)((const char*)(gbase) + (voff)[_i]), (LAS unsigned*)(lds + (bufoff) + ldsw + _i * 8192), 16, 0, 0); } while (0)
; #define PG8_LDA(dst, b, h) do { _Pragma("unroll") for (int m = 0; m < 4; ++m) _Pragma("unroll") for (int k = 0; k < 2; ++k) dst[m][k] = *(const LAS bf16x8*)(lds + PG8_SA(b, h) + aoff + m * 2048 + k * 1024); } while (0)
; #define PG8_MMA(ai, bj, At, Bt) do { __builtin_amdgcn_s_setprio(1); _Pragma("unroll") for (int m = 0; m < 4; ++m) _Pragma("unroll") for (int n = 0; n < 2; ++n) _Pragma("unroll") for (int k = 0; k < 2; ++k) \
;         acc[ai][bj][m][n] = __builtin_amdgcn_mfma_f32_16x16x32_bf16(Bt[n][k], At[m][k], acc[ai][bj][m][n], 0, 0, 0); __builtin_amdgcn_s_setprio(0); } while (0)
; #define PG8_WAIT_V(n) asm volatile("s_waitcnt vmcnt(" #n ")" ::: "memory")
; #define PG8_WAIT_L(n) asm volatile("s_waitcnt lgkmcnt(" #n ")" ::: "memory")
; #define PG8_BAR __builtin_amdgcn_s_barrier()
; #define PG8_SCHED __builtin_amdgcn_sched_barrier(0)
; template <class Epi>
; __device__ __forceinline__ void gemm_phase(LAS unsigned char* lds, const int tid, const Gemm g, const StaticOrder& S, const Epi& E) {
;     ...
;             PG8_LDA(At, 1, 1); PG8_STAGE(PG8_SB(1, 0), b3, voffB); PG8_STAGE(PG8_SB(1, 1), b3 + hstepB, voffB); PG8_STAGE(PG8_SA(1, 0), a3, voffA);
;             PG8_WAIT_V(8); PG8_WAIT_L(0); PG8_BAR; PG8_MMA(1, 0, At, B0); PG8_MMA(1, 1, At, B1); PG8_BAR; PG8_SCHED;
;         }
;         if (wr == 0) PG8_BAR;
	s_add_i32 s2, s2, s4
	v_lshl_add_u64 v[162:163], v[162:163], 0, s[36:37]
	s_mov_b32 m0, s2
	ds_read_b128 v[188:191], v181 offset:49152
	ds_read_b128 v[192:195], v181 offset:50176
	ds_read_b128 v[196:199], v181 offset:51200
	ds_read_b128 v[200:203], v181 offset:52224
	ds_read_b128 v[212:215], v181 offset:53248
	ds_read_b128 v[216:219], v181 offset:54272
	ds_read_b128 v[220:223], v181 offset:55296
	ds_read_b128 v[224:227], v181 offset:56320
	global_load_lds_dwordx4 v[162:163], off
	s_add_i32 m0, s2, 0x2000
	s_add_u32 s30, s72, 0xb0080
	v_lshl_add_u64 v[162:163], v[164:165], 0, s[36:37]
	s_addc_u32 s31, s73, 0
	s_add_i32 s2, s3, s4
	global_load_lds_dwordx4 v[162:163], off
	v_lshl_add_u64 v[162:163], s[30:31], 0, v[0:1]
	s_mov_b32 m0, s2
	s_nop 0
	global_load_lds_dwordx4 v[162:163], off
	v_lshl_add_u64 v[162:163], s[30:31], 0, v[148:149]
	s_add_i32 m0, s2, 0x2000
	s_nop 0
	global_load_lds_dwordx4 v[162:163], off
	v_lshl_add_u64 v[162:163], v[206:207], 0, s[36:37]
	s_mov_b32 m0, s83
	s_nop 0
	global_load_lds_dwordx4 v[162:163], off
	v_lshl_add_u64 v[162:163], v[228:229], 0, s[36:37]
	s_mov_b32 m0, s88
	s_nop 0
	global_load_lds_dwordx4 v[162:163], off
	s_waitcnt vmcnt(8)
	s_waitcnt lgkmcnt(0)
	s_barrier
	s_setprio 1
	s_waitcnt lgkmcnt(0)
	v_mfma_f32_16x16x32_bf16 v[62:65], v[130:133], v[188:191], v[62:65]
	v_mfma_f32_16x16x32_bf16 v[58:61], v[138:141], v[188:191], v[58:61]
	v_mfma_f32_16x16x32_bf16 v[46:49], v[130:133], v[196:199], v[46:49]
	v_mfma_f32_16x16x32_bf16 v[42:45], v[138:141], v[196:199], v[42:45]
	v_mfma_f32_16x16x32_bf16 v[30:33], v[130:133], v[212:215], v[30:33]
	v_mfma_f32_16x16x32_bf16 v[26:29], v[138:141], v[212:215], v[26:29]
	v_mfma_f32_16x16x32_bf16 v[14:17], v[130:133], v[220:223], v[14:17]
	v_mfma_f32_16x16x32_bf16 v[10:13], v[138:141], v[220:223], v[10:13]
	v_mfma_f32_16x16x32_bf16 v[62:65], v[134:137], v[192:195], v[62:65]
	v_mfma_f32_16x16x32_bf16 v[58:61], v[154:157], v[192:195], v[58:61]
	v_mfma_f32_16x16x32_bf16 v[46:49], v[134:137], v[200:203], v[46:49]
	v_mfma_f32_16x16x32_bf16 v[42:45], v[154:157], v[200:203], v[42:45]
	v_mfma_f32_16x16x32_bf16 v[30:33], v[134:137], v[216:219], v[30:33]
	v_mfma_f32_16x16x32_bf16 v[26:29], v[154:157], v[216:219], v[26:29]
	v_mfma_f32_16x16x32_bf16 v[14:17], v[134:137], v[224:227], v[14:17]
	v_mfma_f32_16x16x32_bf16 v[10:13], v[154:157], v[224:227], v[10:13]
	v_mfma_f32_16x16x32_bf16 v[54:57], v[158:161], v[188:191], v[54:57]
	v_mfma_f32_16x16x32_bf16 v[50:53], v[174:177], v[188:191], v[50:53]
	v_mfma_f32_16x16x32_bf16 v[38:41], v[158:161], v[196:199], v[38:41]
	v_mfma_f32_16x16x32_bf16 v[34:37], v[174:177], v[196:199], v[34:37]
	v_mfma_f32_16x16x32_bf16 v[22:25], v[158:161], v[212:215], v[22:25]
	v_mfma_f32_16x16x32_bf16 v[18:21], v[174:177], v[212:215], v[18:21]
	v_mfma_f32_16x16x32_bf16 v[6:9], v[158:161], v[220:223], v[6:9]
	v_mfma_f32_16x16x32_bf16 v[2:5], v[174:177], v[220:223], v[2:5]
	v_mfma_f32_16x16x32_bf16 v[54:57], v[170:173], v[192:195], v[54:57]
	v_mfma_f32_16x16x32_bf16 v[50:53], v[184:187], v[192:195], v[50:53]
	v_mfma_f32_16x16x32_bf16 v[38:41], v[170:173], v[200:203], v[38:41]
	v_mfma_f32_16x16x32_bf16 v[34:37], v[184:187], v[200:203], v[34:37]
	v_mfma_f32_16x16x32_bf16 v[22:25], v[170:173], v[216:219], v[22:25]
	v_mfma_f32_16x16x32_bf16 v[18:21], v[184:187], v[216:219], v[18:21]
	v_mfma_f32_16x16x32_bf16 v[6:9], v[170:173], v[224:227], v[6:9]
	v_mfma_f32_16x16x32_bf16 v[2:5], v[184:187], v[224:227], v[2:5]
	s_setprio 0
	s_barrier
	s_add_i32 vcc_hi, vcc_hi, 2
	s_add_u32 s28, s28, 0x100
	s_addc_u32 vcc_lo, vcc_lo, 0
	s_cmp_gt_u32 vcc_hi, 41
	s_mov_b64 s[30:31], s[70:71]
	s_cbranch_scc0 .LBB0_2193
	s_and_b64 vcc, exec, s[26:27]
	s_cbranch_vccz .LBB0_2196
	s_barrier

; #define PG8_STAGE(bufoff, gbase, voff) do { _Pragma("unroll") for (int _i = 0; _i < 2; ++_i) \
;         __builtin_amdgcn_global_load_lds((const unsigned*)((const char*)(gbase) + (voff)[_i]), (LAS unsigned*)(lds + (bufoff) + ldsw + _i * 8192), 16, 0, 0); } while (0)
; #define PG8_LDA(dst, b, h) do { _Pragma("unroll") for (int m = 0; m < 4; ++m) _Pragma("unroll") for (int k = 0; k < 2; ++k) dst[m][k] = *(const LAS bf16x8*)(lds + PG8_SA(b, h) + aoff + m * 2048 + k * 1024); } while (0)
; #define PG8_LDB(dst, b, h) do { _Pragma("unroll") for (int n = 0; n < 2; ++n) _Pragma("unroll") for (int k = 0; k < 2; ++k) dst[n][k] = *(const LAS bf16x8*)(lds + PG8_SB(b, h) + boff + n * 2048 + k * 1024); } while (0)
; #define PG8_MMA(ai, bj, At, Bt) do { __builtin_amdgcn_s_setprio(1); _Pragma("unroll") for (int m = 0; m < 4; ++m) _Pragma("unroll") for (int n = 0; n < 2; ++n) _Pragma("unroll") for (int k = 0; k < 2; ++k) \
;         acc[ai][bj][m][n] = __builtin_amdgcn_mfma_f32_16x16x32_bf16(Bt[n][k], At[m][k], acc[ai][bj][m][n], 0, 0, 0); __builtin_amdgcn_s_setprio(0); } while (0)
; #define PG8_WAIT_V(n) asm volatile("s_waitcnt vmcnt(" #n ")" ::: "memory")
; #define PG8_WAIT_L(n) asm volatile("s_waitcnt lgkmcnt(" #n ")" ::: "memory")
; #define PG8_BAR __builtin_amdgcn_s_barrier()
; #define PG8_SCHED __builtin_amdgcn_sched_barrier(0)
; template <class Epi>
; __device__ __forceinline__ void gemm_phase(LAS unsigned char* lds, const int tid, const Gemm g, const StaticOrder& S, const Epi& E) {
;     ...
;             const bool last = (t == nt - 2);
;             const char* a1 = cA + (size_t)(t + 1) * kstep;
;             const char* a2 = last ? nA : cA + (size_t)(t + 2) * kstep; const char* b2 = last ? nB : cB + (size_t)(t + 2) * kstep;
;             const char* a3 = a2 + kstep; const char* b3 = b2 + kstep;
;             PG8_LDB(B0, 0, 0); PG8_LDB(B1, 0, 1); PG8_SCHED; PG8_LDA(At, 0, 0); PG8_STAGE(PG8_SA(1, 1), a1 + hstepA, voffA);
;             PG8_WAIT_V(8); PG8_WAIT_L(0); PG8_BAR; PG8_MMA(0, 0, At, B0); PG8_MMA(0, 1, At, B1); PG8_BAR; PG8_SCHED;
;             PG8_LDA(At, 0, 1); PG8_STAGE(PG8_SB(0, 0), b2, voffB); PG8_STAGE(PG8_SB(0, 1), b2 + hstepB, voffB); PG8_STAGE(PG8_SA(0, 0), a2, voffA);
;             PG8_WAIT_V(8); PG8_WAIT_L(0); PG8_BAR; PG8_MMA(1, 0, At, B0); PG8_MMA(1, 1, At, B1); PG8_BAR; PG8_SCHED;
.LBB0_2303:
	s_add_u32 s68, s66, 0x100
	s_addc_u32 s69, s67, 0
	s_add_i32 s76, 0, 0x10000
	s_cmp_eq_u32 s93, 40
	s_cselect_b32 s73, s1, s69
	s_cselect_b32 s72, s0, s68
	s_cselect_b32 s71, s31, s28
	s_cselect_b32 s70, s30, s11
	s_add_i32 vcc_lo, 0, 0x14000
	v_add_u32_e32 v70, s76, v212
	v_add_u32_e32 v162, vcc_lo, v212
	ds_read_b128 v[42:45], v70
	ds_read_b128 v[46:49], v70 offset:1024
	ds_read_b128 v[66:69], v70 offset:2048
	ds_read_b128 v[70:73], v70 offset:3072
	ds_read_b128 v[158:161], v162
	ds_read_b128 v[170:173], v162 offset:1024
	ds_read_b128 v[174:177], v162 offset:2048
	ds_read_b128 v[178:181], v162 offset:3072
	v_lshl_add_u64 v[162:163], s[66:67], 0, v[154:155]
	s_add_i32 m0, s5, 0xc000
	ds_read_b128 v[182:185], v214
	ds_read_b128 v[186:189], v214 offset:1024
	ds_read_b128 v[190:193], v214 offset:2048
	ds_read_b128 v[194:197], v214 offset:3072
	ds_read_b128 v[198:201], v214 offset:4096
	ds_read_b128 v[216:219], v214 offset:5120
	ds_read_b128 v[220:223], v214 offset:6144
	ds_read_b128 v[224:227], v214 offset:7168
	global_load_lds_dwordx4 v[162:163], off
	v_lshl_add_u64 v[162:163], s[66:67], 0, v[156:157]
	s_add_i32 m0, s5, 0xe000
	s_nop 0
	global_load_lds_dwordx4 v[162:163], off
	s_waitcnt vmcnt(8)
	s_waitcnt lgkmcnt(0)
	s_barrier
	s_setprio 1
	s_waitcnt lgkmcnt(0)
	v_mfma_f32_16x16x32_bf16 v[142:145], v[42:45], v[182:185], v[142:145]
	v_mfma_f32_16x16x32_bf16 v[138:141], v[66:69], v[182:185], v[138:141]
	v_mfma_f32_16x16x32_bf16 v[126:129], v[42:45], v[190:193], v[126:129]
	v_mfma_f32_16x16x32_bf16 v[122:125], v[66:69], v[190:193], v[122:125]
	v_mfma_f32_16x16x32_bf16 v[110:113], v[42:45], v[198:201], v[110:113]
	v_mfma_f32_16x16x32_bf16 v[106:109], v[66:69], v[198:201], v[106:109]
	v_mfma_f32_16x16x32_bf16 v[94:97], v[42:45], v[220:223], v[94:97]
	v_mfma_f32_16x16x32_bf16 v[90:93], v[66:69], v[220:223], v[90:93]
	v_mfma_f32_16x16x32_bf16 v[142:145], v[46:49], v[186:189], v[142:145]
	v_mfma_f32_16x16x32_bf16 v[138:141], v[70:73], v[186:189], v[138:141]
	v_mfma_f32_16x16x32_bf16 v[126:129], v[46:49], v[194:197], v[126:129]
	v_mfma_f32_16x16x32_bf16 v[122:125], v[70:73], v[194:197], v[122:125]
	v_mfma_f32_16x16x32_bf16 v[110:113], v[46:49], v[216:219], v[110:113]
	v_mfma_f32_16x16x32_bf16 v[106:109], v[70:73], v[216:219], v[106:109]
	v_mfma_f32_16x16x32_bf16 v[94:97], v[46:49], v[224:227], v[94:97]
	v_mfma_f32_16x16x32_bf16 v[90:93], v[70:73], v[224:227], v[90:93]
	v_mfma_f32_16x16x32_bf16 v[134:137], v[158:161], v[182:185], v[134:137]
	v_mfma_f32_16x16x32_bf16 v[130:133], v[174:177], v[182:185], v[130:133]
	v_mfma_f32_16x16x32_bf16 v[118:121], v[158:161], v[190:193], v[118:121]
	v_mfma_f32_16x16x32_bf16 v[114:117], v[174:177], v[190:193], v[114:117]
	v_mfma_f32_16x16x32_bf16 v[102:105], v[158:161], v[198:201], v[102:105]
	v_mfma_f32_16x16x32_bf16 v[98:101], v[174:177], v[198:201], v[98:101]
	v_mfma_f32_16x16x32_bf16 v[86:89], v[158:161], v[220:223], v[86:89]
	v_mfma_f32_16x16x32_bf16 v[82:85], v[174:177], v[220:223], v[82:85]
	v_mfma_f32_16x16x32_bf16 v[134:137], v[170:173], v[186:189], v[134:137]
	v_mfma_f32_16x16x32_bf16 v[130:133], v[178:181], v[186:189], v[130:133]
	v_mfma_f32_16x16x32_bf16 v[118:121], v[170:173], v[194:197], v[118:121]
	v_mfma_f32_16x16x32_bf16 v[114:117], v[178:181], v[194:197], v[114:117]
	v_mfma_f32_16x16x32_bf16 v[102:105], v[170:173], v[216:219], v[102:105]
	v_mfma_f32_16x16x32_bf16 v[98:101], v[178:181], v[216:219], v[98:101]
	v_mfma_f32_16x16x32_bf16 v[86:89], v[170:173], v[224:227], v[86:89]
	v_mfma_f32_16x16x32_bf16 v[82:85], v[178:181], v[224:227], v[82:85]
	s_setprio 0
	s_barrier
	s_add_i32 s66, s76, s4
	v_lshl_add_u64 v[162:163], s[70:71], 0, v[0:1]
	s_mov_b32 m0, s66
	ds_read_b128 v[182:185], v214 offset:16384
	ds_read_b128 v[186:189], v214 offset:17408
	ds_read_b128 v[190:193], v214 offset:18432
	ds_read_b128 v[194:197], v214 offset:19456
	ds_read_b128 v[198:201], v214 offset:20480
	ds_read_b128 v[216:219], v214 offset:21504
	ds_read_b128 v[220:223], v214 offset:22528
	ds_read_b128 v[224:227], v214 offset:23552
	global_load_lds_dwordx4 v[162:163], off
	s_add_i32 m0, s66, 0x2000
	s_add_u32 s66, s70, 0xb0000
	v_lshl_add_u64 v[164:165], s[70:71], 0, v[152:153]
	s_addc_u32 s67, s71, 0
	s_add_i32 s76, vcc_lo, s4
	global_load_lds_dwordx4 v[164:165], off
	v_lshl_add_u64 v[202:203], s[66:67], 0, v[0:1]
	s_mov_b32 m0, s76
	v_lshl_add_u64 v[206:207], s[72:73], 0, v[150:151]
	global_load_lds_dwordx4 v[202:203], off
	v_lshl_add_u64 v[202:203], s[66:67], 0, v[152:153]
	s_add_i32 m0, s76, 0x2000
	s_nop 0
	global_load_lds_dwordx4 v[202:203], off
	v_lshl_add_u64 v[202:203], s[72:73], 0, v[148:149]
	s_mov_b32 m0, s5
	s_nop 0
	global_load_lds_dwordx4 v[202:203], off
	s_mov_b32 m0, s6
	s_nop 0
	global_load_lds_dwordx4 v[206:207], off
	s_waitcnt vmcnt(8)
	s_waitcnt lgkmcnt(0)
	s_barrier
; #define PG8_STAGE(bufoff, gbase, voff) do { _Pragma("unroll") for (int _i = 0; _i < 2; ++_i) \
;         __builtin_amdgcn_global_load_lds((const unsigned*)((const char*)(gbase) + (voff)[_i]), (LAS unsigned*)(lds + (bufoff) + ldsw + _i * 8192), 16, 0, 0); } while (0)
; #define PG8_LDA(dst, b, h) do { _Pragma("unroll") for (int m = 0; m < 4; ++m) _Pragma("unroll") for (int k = 0; k < 2; ++k) dst[m][k] = *(const LAS bf16x8*)(lds + PG8_SA(b, h) + aoff + m * 2048 + k * 1024); } while (0)
; #define PG8_LDB(dst, b, h) do { _Pragma("unroll") for (int n = 0; n < 2; ++n) _Pragma("unroll") for (int k = 0; k < 2; ++k) dst[n][k] = *(const LAS bf16x8*)(lds + PG8_SB(b, h) + boff + n * 2048 + k * 1024); } while (0)
; #define PG8_MMA(ai, bj, At, Bt) do { __builtin_amdgcn_s_setprio(1); _Pragma("unroll") for (int m = 0; m < 4; ++m) _Pragma("unroll") for (int n = 0; n < 2; ++n) _Pragma("unroll") for (int k = 0; k < 2; ++k) \
;         acc[ai][bj][m][n] = __builtin_amdgcn_mfma_f32_16x16x32_bf16(Bt[n][k], At[m][k], acc[ai][bj][m][n], 0, 0, 0); __builtin_amdgcn_s_setprio(0); } while (0)
; #define PG8_WAIT_V(n) asm volatile("s_waitcnt vmcnt(" #n ")" ::: "memory")
; #define PG8_WAIT_L(n) asm volatile("s_waitcnt lgkmcnt(" #n ")" ::: "memory")
; #define PG8_BAR __builtin_amdgcn_s_barrier()
; #define PG8_SCHED __builtin_amdgcn_sched_barrier(0)
; template <class Epi>
; __device__ __forceinline__ void gemm_phase(LAS unsigned char* lds, const int tid, const Gemm g, const StaticOrder& S, const Epi& E) {
;     ...
;             PG8_WAIT_V(8); PG8_WAIT_L(0); PG8_BAR; PG8_MMA(1, 0, At, B0); PG8_MMA(1, 1, At, B1); PG8_BAR; PG8_SCHED;
;             PG8_LDB(B0, 1, 0); PG8_LDB(B1, 1, 1); PG8_SCHED; PG8_LDA(At, 1, 0); PG8_STAGE(PG8_SA(0, 1), a2 + hstepA, voffA);
;             PG8_WAIT_V(8); PG8_WAIT_L(0); PG8_BAR; PG8_MMA(0, 0, At, B0); PG8_MMA(0, 1, At, B1); PG8_BAR; PG8_SCHED;
	s_setprio 1
	s_waitcnt lgkmcnt(0)
	v_mfma_f32_16x16x32_bf16 v[78:81], v[42:45], v[182:185], v[78:81]
	v_mfma_f32_16x16x32_bf16 v[74:77], v[66:69], v[182:185], v[74:77]
	v_mfma_f32_16x16x32_bf16 v[54:57], v[42:45], v[190:193], v[54:57]
	v_mfma_f32_16x16x32_bf16 v[50:53], v[66:69], v[190:193], v[50:53]
	v_mfma_f32_16x16x32_bf16 v[30:33], v[42:45], v[198:201], v[30:33]
	v_mfma_f32_16x16x32_bf16 v[26:29], v[66:69], v[198:201], v[26:29]
	v_mfma_f32_16x16x32_bf16 v[14:17], v[42:45], v[220:223], v[14:17]
	v_mfma_f32_16x16x32_bf16 v[10:13], v[66:69], v[220:223], v[10:13]
	v_mfma_f32_16x16x32_bf16 v[78:81], v[46:49], v[186:189], v[78:81]
	v_mfma_f32_16x16x32_bf16 v[74:77], v[70:73], v[186:189], v[74:77]
	v_mfma_f32_16x16x32_bf16 v[54:57], v[46:49], v[194:197], v[54:57]
	v_mfma_f32_16x16x32_bf16 v[50:53], v[70:73], v[194:197], v[50:53]
	v_mfma_f32_16x16x32_bf16 v[30:33], v[46:49], v[216:219], v[30:33]
	v_mfma_f32_16x16x32_bf16 v[26:29], v[70:73], v[216:219], v[26:29]
	v_mfma_f32_16x16x32_bf16 v[14:17], v[46:49], v[224:227], v[14:17]
	v_mfma_f32_16x16x32_bf16 v[10:13], v[70:73], v[224:227], v[10:13]
	v_mfma_f32_16x16x32_bf16 v[38:41], v[158:161], v[190:193], v[38:41]
	v_mfma_f32_16x16x32_bf16 v[34:37], v[174:177], v[190:193], v[34:37]
	v_mfma_f32_16x16x32_bf16 v[22:25], v[158:161], v[198:201], v[22:25]
	v_mfma_f32_16x16x32_bf16 v[18:21], v[174:177], v[198:201], v[18:21]
	v_mfma_f32_16x16x32_bf16 v[6:9], v[158:161], v[220:223], v[6:9]
	v_mfma_f32_16x16x32_bf16 v[2:5], v[174:177], v[220:223], v[2:5]
	v_mfma_f32_16x16x32_bf16 v[42:45], v[158:161], v[182:185], v[62:65]
	v_mfma_f32_16x16x32_bf16 v[46:49], v[174:177], v[182:185], v[58:61]
	v_mfma_f32_16x16x32_bf16 v[38:41], v[170:173], v[194:197], v[38:41]
	v_mfma_f32_16x16x32_bf16 v[34:37], v[178:181], v[194:197], v[34:37]
	v_mfma_f32_16x16x32_bf16 v[22:25], v[170:173], v[216:219], v[22:25]
	v_mfma_f32_16x16x32_bf16 v[18:21], v[178:181], v[216:219], v[18:21]
	v_mfma_f32_16x16x32_bf16 v[6:9], v[170:173], v[224:227], v[6:9]
	v_mfma_f32_16x16x32_bf16 v[2:5], v[178:181], v[224:227], v[2:5]
	v_mfma_f32_16x16x32_bf16 v[42:45], v[170:173], v[186:189], v[42:45]
	v_mfma_f32_16x16x32_bf16 v[46:49], v[178:181], v[186:189], v[46:49]
	s_setprio 0
	s_barrier
	s_add_i32 s76, 0, 0x18000
	s_add_i32 vcc_lo, 0, 0x1c000
	v_add_u32_e32 v70, s76, v212
	v_add_u32_e32 v178, vcc_lo, v212
	ds_read_b128 v[58:61], v70
	ds_read_b128 v[62:65], v70 offset:1024
	ds_read_b128 v[66:69], v70 offset:2048
	ds_read_b128 v[70:73], v70 offset:3072
	ds_read_b128 v[158:161], v178
	ds_read_b128 v[170:173], v178 offset:1024
	ds_read_b128 v[174:177], v178 offset:2048
	ds_read_b128 v[178:181], v178 offset:3072
	s_add_u32 s66, s72, 0x160000
	s_addc_u32 s67, s73, 0
	s_mov_b32 m0, s7
	v_lshl_add_u64 v[228:229], s[66:67], 0, v[148:149]
	ds_read_b128 v[182:185], v214 offset:32768
	ds_read_b128 v[186:189], v214 offset:33792
	ds_read_b128 v[190:193], v214 offset:34816
	ds_read_b128 v[194:197], v214 offset:35840
	ds_read_b128 v[198:201], v214 offset:36864
	ds_read_b128 v[216:219], v214 offset:37888
	ds_read_b128 v[220:223], v214 offset:38912
	ds_read_b128 v[224:227], v214 offset:39936
	global_load_lds_dwordx4 v[228:229], off
	v_lshl_add_u64 v[228:229], s[66:67], 0, v[150:151]
	s_mov_b32 m0, s74
	s_nop 0
	global_load_lds_dwordx4 v[228:229], off
	s_waitcnt vmcnt(8)
	s_waitcnt lgkmcnt(0)
	s_barrier
	s_setprio 1
	s_waitcnt lgkmcnt(0)
	v_mfma_f32_16x16x32_bf16 v[142:145], v[58:61], v[182:185], v[142:145]
	v_mfma_f32_16x16x32_bf16 v[138:141], v[66:69], v[182:185], v[138:141]
	v_mfma_f32_16x16x32_bf16 v[126:129], v[58:61], v[190:193], v[126:129]
	v_mfma_f32_16x16x32_bf16 v[122:125], v[66:69], v[190:193], v[122:125]
	v_mfma_f32_16x16x32_bf16 v[110:113], v[58:61], v[198:201], v[110:113]
	v_mfma_f32_16x16x32_bf16 v[106:109], v[66:69], v[198:201], v[106:109]
	v_mfma_f32_16x16x32_bf16 v[94:97], v[58:61], v[220:223], v[94:97]
	v_mfma_f32_16x16x32_bf16 v[90:93], v[66:69], v[220:223], v[90:93]
	v_mfma_f32_16x16x32_bf16 v[142:145], v[62:65], v[186:189], v[142:145]
	v_mfma_f32_16x16x32_bf16 v[138:141], v[70:73], v[186:189], v[138:141]
	v_mfma_f32_16x16x32_bf16 v[126:129], v[62:65], v[194:197], v[126:129]
	v_mfma_f32_16x16x32_bf16 v[122:125], v[70:73], v[194:197], v[122:125]
	v_mfma_f32_16x16x32_bf16 v[110:113], v[62:65], v[216:219], v[110:113]
	v_mfma_f32_16x16x32_bf16 v[106:109], v[70:73], v[216:219], v[106:109]
	v_mfma_f32_16x16x32_bf16 v[94:97], v[62:65], v[224:227], v[94:97]
	v_mfma_f32_16x16x32_bf16 v[90:93], v[70:73], v[224:227], v[90:93]
	v_mfma_f32_16x16x32_bf16 v[134:137], v[158:161], v[182:185], v[134:137]
	v_mfma_f32_16x16x32_bf16 v[130:133], v[174:177], v[182:185], v[130:133]
	v_mfma_f32_16x16x32_bf16 v[118:121], v[158:161], v[190:193], v[118:121]
	v_mfma_f32_16x16x32_bf16 v[114:117], v[174:177], v[190:193], v[114:117]
	v_mfma_f32_16x16x32_bf16 v[102:105], v[158:161], v[198:201], v[102:105]
	v_mfma_f32_16x16x32_bf16 v[98:101], v[174:177], v[198:201], v[98:101]
	v_mfma_f32_16x16x32_bf16 v[86:89], v[158:161], v[220:223], v[86:89]
	v_mfma_f32_16x16x32_bf16 v[82:85], v[174:177], v[220:223], v[82:85]
	v_mfma_f32_16x16x32_bf16 v[134:137], v[170:173], v[186:189], v[134:137]
	v_mfma_f32_16x16x32_bf16 v[130:133], v[178:181], v[186:189], v[130:133]
	v_mfma_f32_16x16x32_bf16 v[118:121], v[170:173], v[194:197], v[118:121]
	v_mfma_f32_16x16x32_bf16 v[114:117], v[178:181], v[194:197], v[114:117]
	v_mfma_f32_16x16x32_bf16 v[102:105], v[170:173], v[216:219], v[102:105]
	v_mfma_f32_16x16x32_bf16 v[98:101], v[178:181], v[216:219], v[98:101]
	v_mfma_f32_16x16x32_bf16 v[86:89], v[170:173], v[224:227], v[86:89]
	v_mfma_f32_16x16x32_bf16 v[82:85], v[178:181], v[224:227], v[82:85]
	s_setprio 0
	s_barrier
; #define PG8_STAGE(bufoff, gbase, voff) do { _Pragma("unroll") for (int _i = 0; _i < 2; ++_i) \
;         __builtin_amdgcn_global_load_lds((const unsigned*)((const char*)(gbase) + (voff)[_i]), (LAS unsigned*)(lds + (bufoff) + ldsw + _i * 8192), 16, 0, 0); } while (0)
; #define PG8_LDA(dst, b, h) do { _Pragma("unroll") for (int m = 0; m < 4; ++m) _Pragma("unroll") for (int k = 0; k < 2; ++k) dst[m][k] = *(const LAS bf16x8*)(lds + PG8_SA(b, h) + aoff + m * 2048 + k * 1024); } while (0)
; #define PG8_MMA(ai, bj, At, Bt) do { __builtin_amdgcn_s_setprio(1); _Pragma("unroll") for (int m = 0; m < 4; ++m) _Pragma("unroll") for (int n = 0; n < 2; ++n) _Pragma("unroll") for (int k = 0; k < 2; ++k) \
;         acc[ai][bj][m][n] = __builtin_amdgcn_mfma_f32_16x16x32_bf16(Bt[n][k], At[m][k], acc[ai][bj][m][n], 0, 0, 0); __builtin_amdgcn_s_setprio(0); } while (0)
; #define PG8_WAIT_V(n) asm volatile("s_waitcnt vmcnt(" #n ")" ::: "memory")
; #define PG8_WAIT_L(n) asm volatile("s_waitcnt lgkmcnt(" #n ")" ::: "memory")
; #define PG8_BAR __builtin_amdgcn_s_barrier()
; #define PG8_SCHED __builtin_amdgcn_sched_barrier(0)
; template <class Epi>
; __device__ __forceinline__ void gemm_phase(LAS unsigned char* lds, const int tid, const Gemm g, const StaticOrder& S, const Epi& E) {
;     ...
;             PG8_LDA(At, 1, 1); PG8_STAGE(PG8_SB(1, 0), b3, voffB); PG8_STAGE(PG8_SB(1, 1), b3 + hstepB, voffB); PG8_STAGE(PG8_SA(1, 0), a3, voffA);
;             PG8_WAIT_V(8); PG8_WAIT_L(0); PG8_BAR; PG8_MMA(1, 0, At, B0); PG8_MMA(1, 1, At, B1); PG8_BAR; PG8_SCHED;
;         }
;         if (wr == 0) PG8_BAR;
	s_add_i32 s66, s76, s4
	v_lshl_add_u64 v[162:163], v[162:163], 0, s[36:37]
	s_mov_b32 m0, s66
	ds_read_b128 v[182:185], v214 offset:49152
	ds_read_b128 v[186:189], v214 offset:50176
	ds_read_b128 v[190:193], v214 offset:51200
	ds_read_b128 v[194:197], v214 offset:52224
	ds_read_b128 v[198:201], v214 offset:53248
	ds_read_b128 v[216:219], v214 offset:54272
	ds_read_b128 v[220:223], v214 offset:55296
	ds_read_b128 v[224:227], v214 offset:56320
	global_load_lds_dwordx4 v[162:163], off
	s_add_i32 m0, s66, 0x2000
	s_add_u32 s66, s70, 0xb0080
	v_lshl_add_u64 v[162:163], v[164:165], 0, s[36:37]
	s_addc_u32 s67, s71, 0
	s_add_i32 s70, vcc_lo, s4
	global_load_lds_dwordx4 v[162:163], off
	v_lshl_add_u64 v[162:163], s[66:67], 0, v[0:1]
	s_mov_b32 m0, s70
	s_nop 0
	global_load_lds_dwordx4 v[162:163], off
	v_lshl_add_u64 v[162:163], s[66:67], 0, v[152:153]
	s_add_i32 m0, s70, 0x2000
	s_nop 0
	global_load_lds_dwordx4 v[162:163], off
	v_lshl_add_u64 v[162:163], v[202:203], 0, s[36:37]
	s_mov_b32 m0, s77
	s_nop 0
	global_load_lds_dwordx4 v[162:163], off
	v_lshl_add_u64 v[162:163], v[206:207], 0, s[36:37]
	s_mov_b32 m0, s79
	s_nop 0
	global_load_lds_dwordx4 v[162:163], off
	s_waitcnt vmcnt(8)
	s_waitcnt lgkmcnt(0)
	s_barrier
	s_setprio 1
	s_waitcnt lgkmcnt(0)
	v_mfma_f32_16x16x32_bf16 v[78:81], v[58:61], v[182:185], v[78:81]
	v_mfma_f32_16x16x32_bf16 v[74:77], v[66:69], v[182:185], v[74:77]
	v_mfma_f32_16x16x32_bf16 v[54:57], v[58:61], v[190:193], v[54:57]
	v_mfma_f32_16x16x32_bf16 v[50:53], v[66:69], v[190:193], v[50:53]
	v_mfma_f32_16x16x32_bf16 v[30:33], v[58:61], v[198:201], v[30:33]
	v_mfma_f32_16x16x32_bf16 v[26:29], v[66:69], v[198:201], v[26:29]
	v_mfma_f32_16x16x32_bf16 v[14:17], v[58:61], v[220:223], v[14:17]
	v_mfma_f32_16x16x32_bf16 v[10:13], v[66:69], v[220:223], v[10:13]
	v_mfma_f32_16x16x32_bf16 v[78:81], v[62:65], v[186:189], v[78:81]
	v_mfma_f32_16x16x32_bf16 v[74:77], v[70:73], v[186:189], v[74:77]
	v_mfma_f32_16x16x32_bf16 v[54:57], v[62:65], v[194:197], v[54:57]
	v_mfma_f32_16x16x32_bf16 v[50:53], v[70:73], v[194:197], v[50:53]
	v_mfma_f32_16x16x32_bf16 v[30:33], v[62:65], v[216:219], v[30:33]
	v_mfma_f32_16x16x32_bf16 v[26:29], v[70:73], v[216:219], v[26:29]
	v_mfma_f32_16x16x32_bf16 v[14:17], v[62:65], v[224:227], v[14:17]
	v_mfma_f32_16x16x32_bf16 v[10:13], v[70:73], v[224:227], v[10:13]
	v_mfma_f32_16x16x32_bf16 v[42:45], v[158:161], v[182:185], v[42:45]
	v_mfma_f32_16x16x32_bf16 v[62:65], v[170:173], v[186:189], v[42:45]
	v_mfma_f32_16x16x32_bf16 v[42:45], v[174:177], v[182:185], v[46:49]
	v_mfma_f32_16x16x32_bf16 v[38:41], v[158:161], v[190:193], v[38:41]
	v_mfma_f32_16x16x32_bf16 v[34:37], v[174:177], v[190:193], v[34:37]
	v_mfma_f32_16x16x32_bf16 v[22:25], v[158:161], v[198:201], v[22:25]
	v_mfma_f32_16x16x32_bf16 v[18:21], v[174:177], v[198:201], v[18:21]
	v_mfma_f32_16x16x32_bf16 v[6:9], v[158:161], v[220:223], v[6:9]
	v_mfma_f32_16x16x32_bf16 v[2:5], v[174:177], v[220:223], v[2:5]
	v_mfma_f32_16x16x32_bf16 v[58:61], v[178:181], v[186:189], v[42:45]
	v_mfma_f32_16x16x32_bf16 v[38:41], v[170:173], v[194:197], v[38:41]
	v_mfma_f32_16x16x32_bf16 v[34:37], v[178:181], v[194:197], v[34:37]
	v_mfma_f32_16x16x32_bf16 v[22:25], v[170:173], v[216:219], v[22:25]
	v_mfma_f32_16x16x32_bf16 v[18:21], v[178:181], v[216:219], v[18:21]
	v_mfma_f32_16x16x32_bf16 v[6:9], v[170:173], v[224:227], v[6:9]
	v_mfma_f32_16x16x32_bf16 v[2:5], v[178:181], v[224:227], v[2:5]
	s_setprio 0
	s_barrier
	s_add_i32 s93, s93, 2
	s_add_u32 s11, s11, 0x100
	s_addc_u32 s28, s28, 0
	s_cmp_gt_u32 s93, 41
	s_mov_b64 s[66:67], s[68:69]
	s_cbranch_scc0 .LBB0_2303
	s_and_b64 vcc, exec, s[26:27]
	s_cbranch_vccz .LBB0_2306
	s_barrier

; #define PG8_STAGE(bufoff, gbase, voff) do { _Pragma("unroll") for (int _i = 0; _i < 2; ++_i) \
;         __builtin_amdgcn_global_load_lds((const unsigned*)((const char*)(gbase) + (voff)[_i]), (LAS unsigned*)(lds + (bufoff) + ldsw + _i * 8192), 16, 0, 0); } while (0)
; #define PG8_LDA(dst, b, h) do { _Pragma("unroll") for (int m = 0; m < 4; ++m) _Pragma("unroll") for (int k = 0; k < 2; ++k) dst[m][k] = *(const LAS bf16x8*)(lds + PG8_SA(b, h) + aoff + m * 2048 + k * 1024); } while (0)
; #define PG8_LDB(dst, b, h) do { _Pragma("unroll") for (int n = 0; n < 2; ++n) _Pragma("unroll") for (int k = 0; k < 2; ++k) dst[n][k] = *(const LAS bf16x8*)(lds + PG8_SB(b, h) + boff + n * 2048 + k * 1024); } while (0)
; #define PG8_MMA(ai, bj, At, Bt) do { __builtin_amdgcn_s_setprio(1); _Pragma("unroll") for (int m = 0; m < 4; ++m) _Pragma("unroll") for (int n = 0; n < 2; ++n) _Pragma("unroll") for (int k = 0; k < 2; ++k) \
;         acc[ai][bj][m][n] = __builtin_amdgcn_mfma_f32_16x16x32_bf16(Bt[n][k], At[m][k], acc[ai][bj][m][n], 0, 0, 0); __builtin_amdgcn_s_setprio(0); } while (0)
; #define PG8_WAIT_V(n) asm volatile("s_waitcnt vmcnt(" #n ")" ::: "memory")
; #define PG8_WAIT_L(n) asm volatile("s_waitcnt lgkmcnt(" #n ")" ::: "memory")
; #define PG8_BAR __builtin_amdgcn_s_barrier()
; #define PG8_SCHED __builtin_amdgcn_sched_barrier(0)
; template <class Epi>
; __device__ __forceinline__ void gemm_phase(LAS unsigned char* lds, const int tid, const Gemm g, const StaticOrder& S, const Epi& E) {
;     ...
;             const bool last = (t == nt - 2);
;             const char* a1 = cA + (size_t)(t + 1) * kstep;
;             const char* a2 = last ? nA : cA + (size_t)(t + 2) * kstep; const char* b2 = last ? nB : cB + (size_t)(t + 2) * kstep;
;             const char* a3 = a2 + kstep; const char* b3 = b2 + kstep;
;             PG8_LDB(B0, 0, 0); PG8_LDB(B1, 0, 1); PG8_SCHED; PG8_LDA(At, 0, 0); PG8_STAGE(PG8_SA(1, 1), a1 + hstepA, voffA);
;             PG8_WAIT_V(8); PG8_WAIT_L(0); PG8_BAR; PG8_MMA(0, 0, At, B0); PG8_MMA(0, 1, At, B1); PG8_BAR; PG8_SCHED;
;             PG8_LDA(At, 0, 1); PG8_STAGE(PG8_SB(0, 0), b2, voffB); PG8_STAGE(PG8_SB(0, 1), b2 + hstepB, voffB); PG8_STAGE(PG8_SA(0, 0), a2, voffA);
;             PG8_WAIT_V(8); PG8_WAIT_L(0); PG8_BAR; PG8_MMA(1, 0, At, B0); PG8_MMA(1, 1, At, B1); PG8_BAR; PG8_SCHED;
.LBB0_2353:
	s_add_u32 s70, s68, 0x100
	s_addc_u32 s71, s69, 0
	s_add_i32 s76, 0, 0x10000
	s_cmp_eq_u32 vcc_hi, 40
	s_cselect_b32 s75, s1, s71
	s_cselect_b32 s74, s0, s70
	s_cselect_b32 s73, s31, vcc_lo
	s_cselect_b32 s72, s30, s11
	s_add_i32 s2, 0, 0x14000
	v_add_u32_e32 v154, s76, v199
	v_add_u32_e32 v162, s2, v199
	ds_read_b128 v[130:133], v154
	ds_read_b128 v[134:137], v154 offset:1024
	ds_read_b128 v[138:141], v154 offset:2048
	ds_read_b128 v[154:157], v154 offset:3072
	ds_read_b128 v[158:161], v162
	ds_read_b128 v[170:173], v162 offset:1024
	ds_read_b128 v[174:177], v162 offset:2048
	ds_read_b128 v[212:215], v162 offset:3072
	v_lshl_add_u64 v[162:163], s[68:69], 0, v[150:151]
	s_add_i32 m0, s83, 0xc000
	ds_read_b128 v[216:219], v201
	ds_read_b128 v[220:223], v201 offset:1024
	ds_read_b128 v[224:227], v201 offset:2048
	ds_read_b128 v[228:231], v201 offset:3072
	ds_read_b128 v[232:235], v201 offset:4096
	ds_read_b128 v[236:239], v201 offset:5120
	ds_read_b128 v[240:243], v201 offset:6144
	ds_read_b128 v[244:247], v201 offset:7168
	global_load_lds_dwordx4 v[162:163], off
	v_lshl_add_u64 v[162:163], s[68:69], 0, v[152:153]
	s_add_i32 m0, s83, 0xe000
	s_nop 0
	global_load_lds_dwordx4 v[162:163], off
	s_waitcnt vmcnt(8)
	s_waitcnt lgkmcnt(0)
	s_barrier
	s_setprio 1
	s_waitcnt lgkmcnt(0)
	v_mfma_f32_16x16x32_bf16 v[126:129], v[130:133], v[216:219], v[126:129]
	v_mfma_f32_16x16x32_bf16 v[122:125], v[138:141], v[216:219], v[122:125]
	v_mfma_f32_16x16x32_bf16 v[110:113], v[130:133], v[224:227], v[110:113]
	v_mfma_f32_16x16x32_bf16 v[106:109], v[138:141], v[224:227], v[106:109]
	v_mfma_f32_16x16x32_bf16 v[94:97], v[130:133], v[232:235], v[94:97]
	v_mfma_f32_16x16x32_bf16 v[90:93], v[138:141], v[232:235], v[90:93]
	v_mfma_f32_16x16x32_bf16 v[78:81], v[130:133], v[240:243], v[78:81]
	v_mfma_f32_16x16x32_bf16 v[74:77], v[138:141], v[240:243], v[74:77]
	v_mfma_f32_16x16x32_bf16 v[126:129], v[134:137], v[220:223], v[126:129]
	v_mfma_f32_16x16x32_bf16 v[122:125], v[154:157], v[220:223], v[122:125]
	v_mfma_f32_16x16x32_bf16 v[110:113], v[134:137], v[228:231], v[110:113]
	v_mfma_f32_16x16x32_bf16 v[106:109], v[154:157], v[228:231], v[106:109]
	v_mfma_f32_16x16x32_bf16 v[94:97], v[134:137], v[236:239], v[94:97]
	v_mfma_f32_16x16x32_bf16 v[90:93], v[154:157], v[236:239], v[90:93]
	v_mfma_f32_16x16x32_bf16 v[78:81], v[134:137], v[244:247], v[78:81]
	v_mfma_f32_16x16x32_bf16 v[74:77], v[154:157], v[244:247], v[74:77]
	v_mfma_f32_16x16x32_bf16 v[118:121], v[158:161], v[216:219], v[118:121]
	v_mfma_f32_16x16x32_bf16 v[114:117], v[174:177], v[216:219], v[114:117]
	v_mfma_f32_16x16x32_bf16 v[102:105], v[158:161], v[224:227], v[102:105]
	v_mfma_f32_16x16x32_bf16 v[98:101], v[174:177], v[224:227], v[98:101]
	v_mfma_f32_16x16x32_bf16 v[86:89], v[158:161], v[232:235], v[86:89]
	v_mfma_f32_16x16x32_bf16 v[82:85], v[174:177], v[232:235], v[82:85]
	v_mfma_f32_16x16x32_bf16 v[70:73], v[158:161], v[240:243], v[70:73]
	v_mfma_f32_16x16x32_bf16 v[66:69], v[174:177], v[240:243], v[66:69]
	v_mfma_f32_16x16x32_bf16 v[118:121], v[170:173], v[220:223], v[118:121]
	v_mfma_f32_16x16x32_bf16 v[114:117], v[212:215], v[220:223], v[114:117]
	v_mfma_f32_16x16x32_bf16 v[102:105], v[170:173], v[228:231], v[102:105]
	v_mfma_f32_16x16x32_bf16 v[98:101], v[212:215], v[228:231], v[98:101]
	v_mfma_f32_16x16x32_bf16 v[86:89], v[170:173], v[236:239], v[86:89]
	v_mfma_f32_16x16x32_bf16 v[82:85], v[212:215], v[236:239], v[82:85]
	v_mfma_f32_16x16x32_bf16 v[70:73], v[170:173], v[244:247], v[70:73]
	v_mfma_f32_16x16x32_bf16 v[66:69], v[212:215], v[244:247], v[66:69]
	s_setprio 0
	s_barrier
	s_add_i32 s3, s76, s82
	v_lshl_add_u64 v[162:163], s[72:73], 0, v[0:1]
	s_mov_b32 m0, s3
	ds_read_b128 v[216:219], v201 offset:16384
	ds_read_b128 v[220:223], v201 offset:17408
	ds_read_b128 v[224:227], v201 offset:18432
	ds_read_b128 v[228:231], v201 offset:19456
	ds_read_b128 v[232:235], v201 offset:20480
	ds_read_b128 v[236:239], v201 offset:21504
	ds_read_b128 v[240:243], v201 offset:22528
	ds_read_b128 v[244:247], v201 offset:23552
	global_load_lds_dwordx4 v[162:163], off
	s_add_i32 m0, s3, 0x2000
	s_add_u32 s68, s72, 0xb0000
	v_lshl_add_u64 v[164:165], s[72:73], 0, v[142:143]
	s_addc_u32 s69, s73, 0
	s_add_i32 s2, s2, s82
	global_load_lds_dwordx4 v[164:165], off
	v_lshl_add_u64 v[178:179], s[68:69], 0, v[0:1]
	s_mov_b32 m0, s2
	v_lshl_add_u64 v[206:207], s[74:75], 0, v[148:149]
	global_load_lds_dwordx4 v[178:179], off
	v_lshl_add_u64 v[178:179], s[68:69], 0, v[142:143]
	s_add_i32 m0, s2, 0x2000
	s_nop 0
	global_load_lds_dwordx4 v[178:179], off
	v_lshl_add_u64 v[178:179], s[74:75], 0, v[144:145]
	s_mov_b32 m0, s83
	s_nop 0
	global_load_lds_dwordx4 v[178:179], off
	s_mov_b32 m0, s88
	s_nop 0
	global_load_lds_dwordx4 v[206:207], off
	s_waitcnt vmcnt(8)
	s_waitcnt lgkmcnt(0)
	s_barrier
; #define PG8_STAGE(bufoff, gbase, voff) do { _Pragma("unroll") for (int _i = 0; _i < 2; ++_i) \
;         __builtin_amdgcn_global_load_lds((const unsigned*)((const char*)(gbase) + (voff)[_i]), (LAS unsigned*)(lds + (bufoff) + ldsw + _i * 8192), 16, 0, 0); } while (0)
; #define PG8_LDA(dst, b, h) do { _Pragma("unroll") for (int m = 0; m < 4; ++m) _Pragma("unroll") for (int k = 0; k < 2; ++k) dst[m][k] = *(const LAS bf16x8*)(lds + PG8_SA(b, h) + aoff + m * 2048 + k * 1024); } while (0)
; #define PG8_LDB(dst, b, h) do { _Pragma("unroll") for (int n = 0; n < 2; ++n) _Pragma("unroll") for (int k = 0; k < 2; ++k) dst[n][k] = *(const LAS bf16x8*)(lds + PG8_SB(b, h) + boff + n * 2048 + k * 1024); } while (0)
; #define PG8_MMA(ai, bj, At, Bt) do { __builtin_amdgcn_s_setprio(1); _Pragma("unroll") for (int m = 0; m < 4; ++m) _Pragma("unroll") for (int n = 0; n < 2; ++n) _Pragma("unroll") for (int k = 0; k < 2; ++k) \
;         acc[ai][bj][m][n] = __builtin_amdgcn_mfma_f32_16x16x32_bf16(Bt[n][k], At[m][k], acc[ai][bj][m][n], 0, 0, 0); __builtin_amdgcn_s_setprio(0); } while (0)
; #define PG8_WAIT_V(n) asm volatile("s_waitcnt vmcnt(" #n ")" ::: "memory")
; #define PG8_WAIT_L(n) asm volatile("s_waitcnt lgkmcnt(" #n ")" ::: "memory")
; #define PG8_BAR __builtin_amdgcn_s_barrier()
; #define PG8_SCHED __builtin_amdgcn_sched_barrier(0)
; template <class Epi>
; __device__ __forceinline__ void gemm_phase(LAS unsigned char* lds, const int tid, const Gemm g, const StaticOrder& S, const Epi& E) {
;     ...
;             PG8_WAIT_V(8); PG8_WAIT_L(0); PG8_BAR; PG8_MMA(1, 0, At, B0); PG8_MMA(1, 1, At, B1); PG8_BAR; PG8_SCHED;
;             PG8_LDB(B0, 1, 0); PG8_LDB(B1, 1, 1); PG8_SCHED; PG8_LDA(At, 1, 0); PG8_STAGE(PG8_SA(0, 1), a2 + hstepA, voffA);
;             PG8_WAIT_V(8); PG8_WAIT_L(0); PG8_BAR; PG8_MMA(0, 0, At, B0); PG8_MMA(0, 1, At, B1); PG8_BAR; PG8_SCHED;
	s_setprio 1
	s_waitcnt lgkmcnt(0)
	v_mfma_f32_16x16x32_bf16 v[62:65], v[130:133], v[216:219], v[62:65]
	v_mfma_f32_16x16x32_bf16 v[58:61], v[138:141], v[216:219], v[58:61]
	v_mfma_f32_16x16x32_bf16 v[46:49], v[130:133], v[224:227], v[46:49]
	v_mfma_f32_16x16x32_bf16 v[42:45], v[138:141], v[224:227], v[42:45]
	v_mfma_f32_16x16x32_bf16 v[30:33], v[130:133], v[232:235], v[30:33]
	v_mfma_f32_16x16x32_bf16 v[26:29], v[138:141], v[232:235], v[26:29]
	v_mfma_f32_16x16x32_bf16 v[14:17], v[130:133], v[240:243], v[14:17]
	v_mfma_f32_16x16x32_bf16 v[10:13], v[138:141], v[240:243], v[10:13]
	v_mfma_f32_16x16x32_bf16 v[62:65], v[134:137], v[220:223], v[62:65]
	v_mfma_f32_16x16x32_bf16 v[58:61], v[154:157], v[220:223], v[58:61]
	v_mfma_f32_16x16x32_bf16 v[46:49], v[134:137], v[228:231], v[46:49]
	v_mfma_f32_16x16x32_bf16 v[42:45], v[154:157], v[228:231], v[42:45]
	v_mfma_f32_16x16x32_bf16 v[30:33], v[134:137], v[236:239], v[30:33]
	v_mfma_f32_16x16x32_bf16 v[26:29], v[154:157], v[236:239], v[26:29]
	v_mfma_f32_16x16x32_bf16 v[14:17], v[134:137], v[244:247], v[14:17]
	v_mfma_f32_16x16x32_bf16 v[10:13], v[154:157], v[244:247], v[10:13]
	v_mfma_f32_16x16x32_bf16 v[54:57], v[158:161], v[216:219], v[54:57]
	v_mfma_f32_16x16x32_bf16 v[50:53], v[174:177], v[216:219], v[50:53]
	v_mfma_f32_16x16x32_bf16 v[38:41], v[158:161], v[224:227], v[38:41]
	v_mfma_f32_16x16x32_bf16 v[34:37], v[174:177], v[224:227], v[34:37]
	v_mfma_f32_16x16x32_bf16 v[22:25], v[158:161], v[232:235], v[22:25]
	v_mfma_f32_16x16x32_bf16 v[18:21], v[174:177], v[232:235], v[18:21]
	v_mfma_f32_16x16x32_bf16 v[6:9], v[158:161], v[240:243], v[6:9]
	v_mfma_f32_16x16x32_bf16 v[2:5], v[174:177], v[240:243], v[2:5]
	v_mfma_f32_16x16x32_bf16 v[54:57], v[170:173], v[220:223], v[54:57]
	v_mfma_f32_16x16x32_bf16 v[50:53], v[212:215], v[220:223], v[50:53]
	v_mfma_f32_16x16x32_bf16 v[38:41], v[170:173], v[228:231], v[38:41]
	v_mfma_f32_16x16x32_bf16 v[34:37], v[212:215], v[228:231], v[34:37]
	v_mfma_f32_16x16x32_bf16 v[22:25], v[170:173], v[236:239], v[22:25]
	v_mfma_f32_16x16x32_bf16 v[18:21], v[212:215], v[236:239], v[18:21]
	v_mfma_f32_16x16x32_bf16 v[6:9], v[170:173], v[244:247], v[6:9]
	v_mfma_f32_16x16x32_bf16 v[2:5], v[212:215], v[244:247], v[2:5]
	s_setprio 0
	s_barrier
	s_add_i32 s2, 0, 0x18000
	s_add_i32 s3, 0, 0x1c000
	v_add_u32_e32 v154, s2, v199
	v_add_u32_e32 v192, s3, v199
	ds_read_b128 v[130:133], v154
	ds_read_b128 v[134:137], v154 offset:1024
	ds_read_b128 v[138:141], v154 offset:2048
	ds_read_b128 v[154:157], v154 offset:3072
	ds_read_b128 v[158:161], v192
	ds_read_b128 v[170:173], v192 offset:1024
	ds_read_b128 v[174:177], v192 offset:2048
	ds_read_b128 v[212:215], v192 offset:3072
	s_add_u32 s68, s74, 0x160000
	s_addc_u32 s69, s75, 0
	s_mov_b32 m0, s89
	v_lshl_add_u64 v[192:193], s[68:69], 0, v[144:145]
	ds_read_b128 v[216:219], v201 offset:32768
	ds_read_b128 v[220:223], v201 offset:33792
	ds_read_b128 v[224:227], v201 offset:34816
	ds_read_b128 v[228:231], v201 offset:35840
	ds_read_b128 v[232:235], v201 offset:36864
	ds_read_b128 v[236:239], v201 offset:37888
	ds_read_b128 v[240:243], v201 offset:38912
	ds_read_b128 v[244:247], v201 offset:39936
	global_load_lds_dwordx4 v[192:193], off
	v_lshl_add_u64 v[192:193], s[68:69], 0, v[148:149]
	s_mov_b32 m0, s92
	s_nop 0
	global_load_lds_dwordx4 v[192:193], off
	s_waitcnt vmcnt(8)
	s_waitcnt lgkmcnt(0)
	s_barrier
	s_setprio 1
	s_waitcnt lgkmcnt(0)
	v_mfma_f32_16x16x32_bf16 v[126:129], v[130:133], v[216:219], v[126:129]
	v_mfma_f32_16x16x32_bf16 v[122:125], v[138:141], v[216:219], v[122:125]
	v_mfma_f32_16x16x32_bf16 v[110:113], v[130:133], v[224:227], v[110:113]
	v_mfma_f32_16x16x32_bf16 v[106:109], v[138:141], v[224:227], v[106:109]
	v_mfma_f32_16x16x32_bf16 v[94:97], v[130:133], v[232:235], v[94:97]
	v_mfma_f32_16x16x32_bf16 v[90:93], v[138:141], v[232:235], v[90:93]
	v_mfma_f32_16x16x32_bf16 v[78:81], v[130:133], v[240:243], v[78:81]
	v_mfma_f32_16x16x32_bf16 v[74:77], v[138:141], v[240:243], v[74:77]
	v_mfma_f32_16x16x32_bf16 v[126:129], v[134:137], v[220:223], v[126:129]
	v_mfma_f32_16x16x32_bf16 v[122:125], v[154:157], v[220:223], v[122:125]
	v_mfma_f32_16x16x32_bf16 v[110:113], v[134:137], v[228:231], v[110:113]
	v_mfma_f32_16x16x32_bf16 v[106:109], v[154:157], v[228:231], v[106:109]
	v_mfma_f32_16x16x32_bf16 v[94:97], v[134:137], v[236:239], v[94:97]
	v_mfma_f32_16x16x32_bf16 v[90:93], v[154:157], v[236:239], v[90:93]
	v_mfma_f32_16x16x32_bf16 v[78:81], v[134:137], v[244:247], v[78:81]
	v_mfma_f32_16x16x32_bf16 v[74:77], v[154:157], v[244:247], v[74:77]
	v_mfma_f32_16x16x32_bf16 v[118:121], v[158:161], v[216:219], v[118:121]
	v_mfma_f32_16x16x32_bf16 v[114:117], v[174:177], v[216:219], v[114:117]
	v_mfma_f32_16x16x32_bf16 v[102:105], v[158:161], v[224:227], v[102:105]
	v_mfma_f32_16x16x32_bf16 v[98:101], v[174:177], v[224:227], v[98:101]
	v_mfma_f32_16x16x32_bf16 v[86:89], v[158:161], v[232:235], v[86:89]
	v_mfma_f32_16x16x32_bf16 v[82:85], v[174:177], v[232:235], v[82:85]
	v_mfma_f32_16x16x32_bf16 v[70:73], v[158:161], v[240:243], v[70:73]
	v_mfma_f32_16x16x32_bf16 v[66:69], v[174:177], v[240:243], v[66:69]
	v_mfma_f32_16x16x32_bf16 v[118:121], v[170:173], v[220:223], v[118:121]
	v_mfma_f32_16x16x32_bf16 v[114:117], v[212:215], v[220:223], v[114:117]
	v_mfma_f32_16x16x32_bf16 v[102:105], v[170:173], v[228:231], v[102:105]
	v_mfma_f32_16x16x32_bf16 v[98:101], v[212:215], v[228:231], v[98:101]
	v_mfma_f32_16x16x32_bf16 v[86:89], v[170:173], v[236:239], v[86:89]
	v_mfma_f32_16x16x32_bf16 v[82:85], v[212:215], v[236:239], v[82:85]
	v_mfma_f32_16x16x32_bf16 v[70:73], v[170:173], v[244:247], v[70:73]
	v_mfma_f32_16x16x32_bf16 v[66:69], v[212:215], v[244:247], v[66:69]
	s_setprio 0
	s_barrier
; #define PG8_STAGE(bufoff, gbase, voff) do { _Pragma("unroll") for (int _i = 0; _i < 2; ++_i) \
;         __builtin_amdgcn_global_load_lds((const unsigned*)((const char*)(gbase) + (voff)[_i]), (LAS unsigned*)(lds + (bufoff) + ldsw + _i * 8192), 16, 0, 0); } while (0)
; #define PG8_LDA(dst, b, h) do { _Pragma("unroll") for (int m = 0; m < 4; ++m) _Pragma("unroll") for (int k = 0; k < 2; ++k) dst[m][k] = *(const LAS bf16x8*)(lds + PG8_SA(b, h) + aoff + m * 2048 + k * 1024); } while (0)
; #define PG8_MMA(ai, bj, At, Bt) do { __builtin_amdgcn_s_setprio(1); _Pragma("unroll") for (int m = 0; m < 4; ++m) _Pragma("unroll") for (int n = 0; n < 2; ++n) _Pragma("unroll") for (int k = 0; k < 2; ++k) \
;         acc[ai][bj][m][n] = __builtin_amdgcn_mfma_f32_16x16x32_bf16(Bt[n][k], At[m][k], acc[ai][bj][m][n], 0, 0, 0); __builtin_amdgcn_s_setprio(0); } while (0)
; #define PG8_WAIT_V(n) asm volatile("s_waitcnt vmcnt(" #n ")" ::: "memory")
; #define PG8_WAIT_L(n) asm volatile("s_waitcnt lgkmcnt(" #n ")" ::: "memory")
; #define PG8_BAR __builtin_amdgcn_s_barrier()
; #define PG8_SCHED __builtin_amdgcn_sched_barrier(0)
; template <class Epi>
; __device__ __forceinline__ void gemm_phase(LAS unsigned char* lds, const int tid, const Gemm g, const StaticOrder& S, const Epi& E) {
;     ...
;             PG8_LDA(At, 1, 1); PG8_STAGE(PG8_SB(1, 0), b3, voffB); PG8_STAGE(PG8_SB(1, 1), b3 + hstepB, voffB); PG8_STAGE(PG8_SA(1, 0), a3, voffA);
;             PG8_WAIT_V(8); PG8_WAIT_L(0); PG8_BAR; PG8_MMA(1, 0, At, B0); PG8_MMA(1, 1, At, B1); PG8_BAR; PG8_SCHED;
;         }
;         if (wr == 0) PG8_BAR;
	s_add_i32 s2, s2, s82
	v_lshl_add_u64 v[162:163], v[162:163], 0, s[36:37]
	s_mov_b32 m0, s2
	ds_read_b128 v[216:219], v201 offset:49152
	ds_read_b128 v[220:223], v201 offset:50176
	ds_read_b128 v[224:227], v201 offset:51200
	ds_read_b128 v[228:231], v201 offset:52224
	ds_read_b128 v[232:235], v201 offset:53248
	ds_read_b128 v[236:239], v201 offset:54272
	ds_read_b128 v[240:243], v201 offset:55296
	ds_read_b128 v[244:247], v201 offset:56320
	global_load_lds_dwordx4 v[162:163], off
	s_add_i32 m0, s2, 0x2000
	s_add_u32 s68, s72, 0xb0080
	v_lshl_add_u64 v[162:163], v[164:165], 0, s[36:37]
	s_addc_u32 s69, s73, 0
	s_add_i32 s2, s3, s82
	global_load_lds_dwordx4 v[162:163], off
	v_lshl_add_u64 v[162:163], s[68:69], 0, v[0:1]
	s_mov_b32 m0, s2
	s_nop 0
	global_load_lds_dwordx4 v[162:163], off
	v_lshl_add_u64 v[162:163], s[68:69], 0, v[142:143]
	s_add_i32 m0, s2, 0x2000
	s_nop 0
	global_load_lds_dwordx4 v[162:163], off
	v_lshl_add_u64 v[162:163], v[178:179], 0, s[36:37]
	s_mov_b32 m0, s4
	s_nop 0
	global_load_lds_dwordx4 v[162:163], off
	v_lshl_add_u64 v[162:163], v[206:207], 0, s[36:37]
	s_mov_b32 m0, s5
	s_nop 0
	global_load_lds_dwordx4 v[162:163], off
	s_waitcnt vmcnt(8)
	s_waitcnt lgkmcnt(0)
	s_barrier
	s_setprio 1
	s_waitcnt lgkmcnt(0)
	v_mfma_f32_16x16x32_bf16 v[62:65], v[130:133], v[216:219], v[62:65]
	v_mfma_f32_16x16x32_bf16 v[58:61], v[138:141], v[216:219], v[58:61]
	v_mfma_f32_16x16x32_bf16 v[46:49], v[130:133], v[224:227], v[46:49]
	v_mfma_f32_16x16x32_bf16 v[42:45], v[138:141], v[224:227], v[42:45]
	v_mfma_f32_16x16x32_bf16 v[30:33], v[130:133], v[232:235], v[30:33]
	v_mfma_f32_16x16x32_bf16 v[26:29], v[138:141], v[232:235], v[26:29]
	v_mfma_f32_16x16x32_bf16 v[14:17], v[130:133], v[240:243], v[14:17]
	v_mfma_f32_16x16x32_bf16 v[10:13], v[138:141], v[240:243], v[10:13]
	v_mfma_f32_16x16x32_bf16 v[62:65], v[134:137], v[220:223], v[62:65]
	v_mfma_f32_16x16x32_bf16 v[58:61], v[154:157], v[220:223], v[58:61]
	v_mfma_f32_16x16x32_bf16 v[46:49], v[134:137], v[228:231], v[46:49]
	v_mfma_f32_16x16x32_bf16 v[42:45], v[154:157], v[228:231], v[42:45]
	v_mfma_f32_16x16x32_bf16 v[30:33], v[134:137], v[236:239], v[30:33]
	v_mfma_f32_16x16x32_bf16 v[26:29], v[154:157], v[236:239], v[26:29]
	v_mfma_f32_16x16x32_bf16 v[14:17], v[134:137], v[244:247], v[14:17]
	v_mfma_f32_16x16x32_bf16 v[10:13], v[154:157], v[244:247], v[10:13]
	v_mfma_f32_16x16x32_bf16 v[54:57], v[158:161], v[216:219], v[54:57]
	v_mfma_f32_16x16x32_bf16 v[50:53], v[174:177], v[216:219], v[50:53]
	v_mfma_f32_16x16x32_bf16 v[38:41], v[158:161], v[224:227], v[38:41]
	v_mfma_f32_16x16x32_bf16 v[34:37], v[174:177], v[224:227], v[34:37]
	v_mfma_f32_16x16x32_bf16 v[22:25], v[158:161], v[232:235], v[22:25]
	v_mfma_f32_16x16x32_bf16 v[18:21], v[174:177], v[232:235], v[18:21]
	v_mfma_f32_16x16x32_bf16 v[6:9], v[158:161], v[240:243], v[6:9]
	v_mfma_f32_16x16x32_bf16 v[2:5], v[174:177], v[240:243], v[2:5]
	v_mfma_f32_16x16x32_bf16 v[54:57], v[170:173], v[220:223], v[54:57]
	v_mfma_f32_16x16x32_bf16 v[50:53], v[212:215], v[220:223], v[50:53]
	v_mfma_f32_16x16x32_bf16 v[38:41], v[170:173], v[228:231], v[38:41]
	v_mfma_f32_16x16x32_bf16 v[34:37], v[212:215], v[228:231], v[34:37]
	v_mfma_f32_16x16x32_bf16 v[22:25], v[170:173], v[236:239], v[22:25]
	v_mfma_f32_16x16x32_bf16 v[18:21], v[212:215], v[236:239], v[18:21]
	v_mfma_f32_16x16x32_bf16 v[6:9], v[170:173], v[244:247], v[6:9]
	v_mfma_f32_16x16x32_bf16 v[2:5], v[212:215], v[244:247], v[2:5]
	s_setprio 0
	s_barrier
	s_add_i32 vcc_hi, vcc_hi, 2
	s_add_u32 s11, s11, 0x100
	s_addc_u32 vcc_lo, vcc_lo, 0
	s_cmp_gt_u32 vcc_hi, 41
	s_mov_b64 s[68:69], s[70:71]
	s_cbranch_scc0 .LBB0_2353
	s_and_b64 vcc, exec, s[26:27]
	s_cbranch_vccz .LBB0_2356
	s_barrier
